# stack6 + sample indexer score head-sum shuffles on DPP (396 ds_bpermute round trips removed)
# baseline (speedup 1.0000x reference)
.LBB0_721:
	v_mov_b32_e32 v139, v0
	s_ashr_i32 s3, s4, 3
	v_readfirstlane_b32 s1, v139
	s_lshl_b32 s0, s3, 2
	s_ashr_i32 s6, s1, 6
	s_and_b32 s7, s4, 7
	v_bfe_u32 v36, v139, 3, 2
	s_add_i32 s5, s0, 0x4000
	s_lshl_b32 s1, s7, 11
	s_lshl_b32 s2, s6, 8
	v_or_b32_e32 v2, s5, v36
	s_add_i32 s2, s2, s1
	s_waitcnt lgkmcnt(0)
	v_ashrrev_i32_e32 v3, 31, v2
	v_readlane_b32 s36, v251, 35
	s_lshl_b32 s1, s3, 7
	s_ashr_i32 s3, s2, 7
	v_and_b32_e32 v137, 7, v139
	v_lshlrev_b64 v[4:5], 10, v[2:3]
	v_readlane_b32 s37, v251, 36
	v_readlane_b32 s38, v251, 37
	v_readlane_b32 s39, v251, 38
	v_readlane_b32 s40, v251, 39
	v_readlane_b32 s41, v251, 40
	v_readlane_b32 s42, v251, 41
	v_readlane_b32 s43, v251, 42
	v_readlane_b32 s44, v251, 43
	v_readlane_b32 s45, v251, 44
	v_readlane_b32 s46, v251, 45
	v_readlane_b32 s47, v251, 46
	v_readlane_b32 s48, v251, 47
	v_readlane_b32 s49, v251, 48
	v_readlane_b32 s50, v251, 49
	v_readlane_b32 s51, v251, 50
	v_lshlrev_b64 v[2:3], 5, v[2:3]
	s_add_i32 s8, s3, s1
	v_bfe_u32 v136, v139, 5, 1
	v_lshl_add_u64 v[4:5], s[38:39], 0, v[4:5]
	v_lshlrev_b32_e32 v114, 7, v137
	v_lshl_add_u64 v[2:3], s[42:43], 0, v[2:3]
	s_ashr_i32 s9, s8, 31
	v_readlane_b32 s36, v253, 32
	v_lshl_add_u64 v[4:5], v[4:5], 0, v[114:115]
	v_lshlrev_b32_e32 v114, 4, v136
	s_lshl_b64 s[8:9], s[8:9], 2
	v_readlane_b32 s48, v253, 44
	v_lshl_add_u64 v[4:5], v[4:5], 0, v[114:115]
	v_lshlrev_b32_e32 v114, 2, v137
	v_readlane_b32 s49, v253, 45
	s_add_u32 s8, s48, s8
	v_lshl_add_u64 v[2:3], v[2:3], 0, v[114:115]
	s_addc_u32 s9, s49, s9
	global_load_dwordx4 v[30:33], v[4:5], off
	global_load_dwordx4 v[26:29], v[4:5], off offset:32
	global_load_dwordx4 v[22:25], v[4:5], off offset:64
	global_load_dwordx4 v[18:21], v[4:5], off offset:96
	global_load_dword v138, v[2:3], off
	s_or_b32 s3, s2, 0x80
	global_load_dword v2, v115, s[8:9]
	v_and_b32_e32 v6, 31, v139
	v_readlane_b32 s44, v253, 40
	v_readlane_b32 s45, v253, 41
	s_ashr_i32 s3, s3, 7
	v_lshlrev_b32_e32 v114, 8, v6
	s_add_i32 s8, s3, s1
	v_lshlrev_b32_e32 v144, 6, v6
	s_ashr_i32 s9, s8, 31
	s_lshl_b64 s[8:9], s[8:9], 2
	v_mov_b32_e32 v129, v115
	s_add_u32 s8, s48, s8
	s_addc_u32 s9, s49, s9
	v_or_b32_e32 v85, s0, v36
	v_cmp_lt_i32_e64 s[0:1], v132, v133
	v_lshlrev_b32_e32 v84, 2, v136
	s_ashr_i32 s3, s2, 31
	v_cmp_eq_u32_e32 vcc, 0, v137
	v_lshlrev_b32_e32 v120, 2, v84
	v_readlane_b32 s37, v253, 33
	v_readlane_b32 s38, v253, 34
	v_readlane_b32 s39, v253, 35
	v_readlane_b32 s40, v253, 36
	v_readlane_b32 s41, v253, 37
	v_readlane_b32 s42, v253, 38
	v_readlane_b32 s43, v253, 39
	v_readlane_b32 s46, v253, 42
	v_readlane_b32 s47, v253, 43
	v_readlane_b32 s50, v253, 46
	v_readlane_b32 s51, v253, 47
	s_waitcnt vmcnt(0)
	v_ashrrev_i32_e32 v3, 31, v2
	v_lshlrev_b64 v[2:3], 15, v[2:3]
	v_lshl_add_u64 v[82:83], s[44:45], 0, v[2:3]
	v_lshl_add_u64 v[2:3], v[82:83], 0, v[114:115]
	v_lshlrev_b32_e32 v114, 5, v136
	v_lshl_add_u64 v[34:35], v[2:3], 0, v[114:115]
	v_or_b32_e32 v2, 0x800, v144
	v_lshlrev_b32_e32 v128, 2, v2
	v_lshl_add_u64 v[2:3], v[82:83], 0, v[128:129]
	v_lshl_add_u64 v[58:59], v[2:3], 0, v[114:115]
	global_load_dword v124, v115, s[8:9]
	global_load_dwordx4 v[2:5], v[34:35], off
	global_load_dwordx4 v[6:9], v[34:35], off offset:16
	global_load_dwordx4 v[10:13], v[34:35], off offset:64
	global_load_dwordx4 v[14:17], v[34:35], off offset:80
	global_load_dwordx4 v[66:69], v[34:35], off offset:128
	global_load_dwordx4 v[70:73], v[34:35], off offset:144
	global_load_dwordx4 v[74:77], v[34:35], off offset:192
	global_load_dwordx4 v[78:81], v[34:35], off offset:208
	global_load_dwordx4 v[38:41], v[58:59], off offset:16
	s_nop 0
	global_load_dwordx4 v[34:37], v[58:59], off
	global_load_dwordx4 v[46:49], v[58:59], off offset:80
	global_load_dwordx4 v[42:45], v[58:59], off offset:64
	global_load_dwordx4 v[54:57], v[58:59], off offset:144
	global_load_dwordx4 v[50:53], v[58:59], off offset:128
	global_load_dwordx4 v[62:65], v[58:59], off offset:208
	s_nop 0
	global_load_dwordx4 v[58:61], v[58:59], off offset:192
	s_waitcnt vmcnt(15)
	v_cvt_f16_f32_e32 v2, v2
	s_waitcnt vmcnt(14)
	v_cvt_f16_f32_e32 v9, v9
	v_cvt_pk_f16_f32 v7, v7, v8
	v_cvt_pk_f16_f32 v5, v5, v6
	v_cvt_pk_f16_f32 v3, v3, v4
	v_pack_b32_f16 v2, v2, v3
	v_alignbit_b32 v3, v5, v3, 16
	v_alignbit_b32 v4, v7, v5, 16
	v_alignbit_b32 v5, v9, v7, 16
	s_waitcnt vmcnt(9)
	v_cvt_pk_f16_f32 v75, v75, v76
	v_cvt_pk_f16_f32 v70, v69, v70
	v_cvt_f16_f32_e32 v76, v66
	v_cvt_f16_f32_e32 v69, v17
	v_cvt_f16_f32_e32 v66, v10
	s_waitcnt vmcnt(8)
	v_cvt_pk_f16_f32 v77, v77, v78
	v_cvt_pk_f16_f32 v71, v71, v72
	v_cvt_pk_f16_f32 v72, v67, v68
	v_cvt_pk_f16_f32 v78, v15, v16
	v_cvt_pk_f16_f32 v68, v13, v14
	v_cvt_pk_f16_f32 v67, v11, v12
	v_mfma_f32_32x32x16_f16 v[2:17], v[2:5], v[30:33], 0
	v_pack_b32_f16 v66, v66, v67
	v_alignbit_b32 v67, v68, v67, 16
	v_alignbit_b32 v68, v78, v68, 16
	v_alignbit_b32 v69, v69, v78, 16
	v_cvt_f16_f32_e32 v73, v73
	v_cvt_f16_f32_e32 v81, v81
	v_cvt_f16_f32_e32 v74, v74
	v_mfma_f32_32x32x16_f16 v[2:17], v[66:69], v[26:29], v[2:17]
	v_pack_b32_f16 v66, v76, v72
	v_alignbit_b32 v67, v70, v72, 16
	v_alignbit_b32 v68, v71, v70, 16
	v_alignbit_b32 v69, v73, v71, 16
	v_cvt_pk_f16_f32 v79, v79, v80
	s_nop 0
	v_mfma_f32_32x32x16_f16 v[2:17], v[66:69], v[22:25], v[2:17]
	v_pack_b32_f16 v66, v74, v75
	v_alignbit_b32 v67, v77, v75, 16
	v_alignbit_b32 v68, v79, v77, 16
	v_alignbit_b32 v69, v81, v79, 16
	s_nop 1
	v_mfma_f32_32x32x16_f16 v[2:17], v[66:69], v[18:21], v[2:17]
	v_cndmask_b32_e64 v66, v1, v132, s[0:1]
	v_cmp_lt_i32_e64 s[0:1], v134, v133
	v_lshlrev_b32_e32 v140, 2, v66
	s_nop 0
	v_cndmask_b32_e64 v66, v1, v134, s[0:1]
	v_cmp_lt_i32_e64 s[0:1], v135, v133
	v_lshlrev_b32_e32 v141, 2, v66
	s_nop 4
	v_max_f32_e32 v2, v2, v2
	v_cndmask_b32_e64 v66, v1, v135, s[0:1]
	v_max_f32_e32 v2, 0, v2
	v_lshlrev_b32_e32 v142, 2, v66
	v_mul_f32_e32 v66, v138, v2
	s_nop 1
	v_mov_b32_dpp v66, v66 quad_perm:[1,0,3,2] row_mask:0xf bank_mask:0xf
	s_mov_b32 s0, 0x10020
	v_mad_i64_i32 v[118:119], s[0:1], v85, s0, v[116:117]
	v_lshl_add_u64 v[122:123], s[2:3], 2, v[118:119]
	s_waitcnt lgkmcnt(0)
	v_fmac_f32_e32 v66, v138, v2
	s_nop 1
	v_mov_b32_dpp v2, v66 quad_perm:[2,3,0,1] row_mask:0xf bank_mask:0xf
	s_waitcnt lgkmcnt(0)
	v_add_f32_e32 v2, v66, v2
	s_nop 1
	v_mov_b32_dpp v66, v2 row_shl:4 row_mask:0xf bank_mask:0x5
	v_mov_b32_dpp v66, v2 row_shr:4 row_mask:0xf bank_mask:0xa
	s_and_saveexec_b64 s[0:1], vcc
	s_cbranch_execz .LBB0_723
	v_mov_b32_e32 v121, v115
	s_waitcnt lgkmcnt(0)
	v_add_f32_e32 v2, v2, v66
	v_lshl_add_u64 v[66:67], v[122:123], 0, v[120:121]
	global_store_dword v[66:67], v2, off
.LBB0_723:
	s_or_b64 exec, exec, s[0:1]
	v_max_f32_e32 v2, v3, v3
	v_max_f32_e32 v2, 0, v2
	v_mul_f32_e32 v3, v138, v2
	s_nop 1
	v_mov_b32_dpp v3, v3 quad_perm:[1,0,3,2] row_mask:0xf bank_mask:0xf
	s_waitcnt lgkmcnt(0)
	v_fmac_f32_e32 v3, v138, v2
	s_nop 1
	v_mov_b32_dpp v2, v3 quad_perm:[2,3,0,1] row_mask:0xf bank_mask:0xf
	s_waitcnt lgkmcnt(0)
	v_add_f32_e32 v2, v3, v2
	s_nop 1
	v_mov_b32_dpp v3, v2 row_shl:4 row_mask:0xf bank_mask:0x5
	v_mov_b32_dpp v3, v2 row_shr:4 row_mask:0xf bank_mask:0xa
	s_and_saveexec_b64 s[0:1], vcc
	s_cbranch_execz .LBB0_725
	v_mov_b32_e32 v121, v115
	s_waitcnt lgkmcnt(0)
	v_add_f32_e32 v66, v2, v3
	v_lshl_add_u64 v[2:3], v[122:123], 0, v[120:121]
	global_store_dword v[2:3], v66, off offset:4
.LBB0_725:
	s_or_b64 exec, exec, s[0:1]
	v_max_f32_e32 v2, v4, v4
	v_max_f32_e32 v2, 0, v2
	s_waitcnt lgkmcnt(0)
	v_mul_f32_e32 v3, v138, v2
	s_nop 1
	v_mov_b32_dpp v3, v3 quad_perm:[1,0,3,2] row_mask:0xf bank_mask:0xf
	s_waitcnt lgkmcnt(0)
	v_fmac_f32_e32 v3, v138, v2
	s_nop 1
	v_mov_b32_dpp v2, v3 quad_perm:[2,3,0,1] row_mask:0xf bank_mask:0xf
	s_waitcnt lgkmcnt(0)
	v_add_f32_e32 v2, v3, v2
	s_nop 1
	v_mov_b32_dpp v3, v2 row_shl:4 row_mask:0xf bank_mask:0x5
	v_mov_b32_dpp v3, v2 row_shr:4 row_mask:0xf bank_mask:0xa
	s_and_saveexec_b64 s[0:1], vcc
	s_cbranch_execz .LBB0_727
	v_mov_b32_e32 v121, v115
	s_waitcnt lgkmcnt(0)
	v_add_f32_e32 v4, v2, v3
	v_lshl_add_u64 v[2:3], v[122:123], 0, v[120:121]
	global_store_dword v[2:3], v4, off offset:8
.LBB0_727:
	s_or_b64 exec, exec, s[0:1]
	v_max_f32_e32 v2, v5, v5
	v_max_f32_e32 v2, 0, v2
	s_waitcnt lgkmcnt(0)
	v_mul_f32_e32 v3, v138, v2
	s_nop 1
	v_mov_b32_dpp v3, v3 quad_perm:[1,0,3,2] row_mask:0xf bank_mask:0xf
	s_waitcnt lgkmcnt(0)
	v_fmac_f32_e32 v3, v138, v2
	s_nop 1
	v_mov_b32_dpp v2, v3 quad_perm:[2,3,0,1] row_mask:0xf bank_mask:0xf
	s_waitcnt lgkmcnt(0)
	v_add_f32_e32 v2, v3, v2
	s_nop 1
	v_mov_b32_dpp v3, v2 row_shl:4 row_mask:0xf bank_mask:0x5
	v_mov_b32_dpp v3, v2 row_shr:4 row_mask:0xf bank_mask:0xa
	s_and_saveexec_b64 s[0:1], vcc
	s_cbranch_execz .LBB0_729
	v_mov_b32_e32 v121, v115
	s_waitcnt lgkmcnt(0)
	v_add_f32_e32 v4, v2, v3
	v_lshl_add_u64 v[2:3], v[122:123], 0, v[120:121]
	global_store_dword v[2:3], v4, off offset:12
.LBB0_729:
	s_or_b64 exec, exec, s[0:1]
	v_max_f32_e32 v2, v6, v6
	v_max_f32_e32 v2, 0, v2
	s_waitcnt lgkmcnt(0)
	v_mul_f32_e32 v3, v138, v2
	s_nop 1
	v_mov_b32_dpp v3, v3 quad_perm:[1,0,3,2] row_mask:0xf bank_mask:0xf
	s_waitcnt lgkmcnt(0)
	v_fmac_f32_e32 v3, v138, v2
	s_nop 1
	v_mov_b32_dpp v2, v3 quad_perm:[2,3,0,1] row_mask:0xf bank_mask:0xf
	s_waitcnt lgkmcnt(0)
	v_add_f32_e32 v2, v3, v2
	s_nop 1
	v_mov_b32_dpp v3, v2 row_shl:4 row_mask:0xf bank_mask:0x5
	v_mov_b32_dpp v3, v2 row_shr:4 row_mask:0xf bank_mask:0xa
	s_and_saveexec_b64 s[0:1], vcc
	s_cbranch_execz .LBB0_731
	v_mov_b32_e32 v121, v115
	s_waitcnt lgkmcnt(0)
	v_add_f32_e32 v4, v2, v3
	v_lshl_add_u64 v[2:3], v[122:123], 0, v[120:121]
	global_store_dword v[2:3], v4, off offset:32
.LBB0_731:
	s_or_b64 exec, exec, s[0:1]
	v_max_f32_e32 v2, v7, v7
	v_max_f32_e32 v2, 0, v2
	s_waitcnt lgkmcnt(0)
	v_mul_f32_e32 v3, v138, v2
	s_nop 1
	v_mov_b32_dpp v3, v3 quad_perm:[1,0,3,2] row_mask:0xf bank_mask:0xf
	s_waitcnt lgkmcnt(0)
	v_fmac_f32_e32 v3, v138, v2
	s_nop 1
	v_mov_b32_dpp v2, v3 quad_perm:[2,3,0,1] row_mask:0xf bank_mask:0xf
	s_waitcnt lgkmcnt(0)
	v_add_f32_e32 v2, v3, v2
	s_nop 1
	v_mov_b32_dpp v3, v2 row_shl:4 row_mask:0xf bank_mask:0x5
	v_mov_b32_dpp v3, v2 row_shr:4 row_mask:0xf bank_mask:0xa
	s_and_saveexec_b64 s[0:1], vcc
	s_cbranch_execz .LBB0_733
	v_mov_b32_e32 v121, v115
	s_waitcnt lgkmcnt(0)
	v_add_f32_e32 v4, v2, v3
	v_lshl_add_u64 v[2:3], v[122:123], 0, v[120:121]
	global_store_dword v[2:3], v4, off offset:36
.LBB0_733:
	s_or_b64 exec, exec, s[0:1]
	v_max_f32_e32 v2, v8, v8
	v_max_f32_e32 v2, 0, v2
	s_waitcnt lgkmcnt(0)
	v_mul_f32_e32 v3, v138, v2
	s_nop 1
	v_mov_b32_dpp v3, v3 quad_perm:[1,0,3,2] row_mask:0xf bank_mask:0xf
	s_waitcnt lgkmcnt(0)
	v_fmac_f32_e32 v3, v138, v2
	s_nop 1
	v_mov_b32_dpp v2, v3 quad_perm:[2,3,0,1] row_mask:0xf bank_mask:0xf
	s_waitcnt lgkmcnt(0)
	v_add_f32_e32 v2, v3, v2
	s_nop 1
	v_mov_b32_dpp v3, v2 row_shl:4 row_mask:0xf bank_mask:0x5
	v_mov_b32_dpp v3, v2 row_shr:4 row_mask:0xf bank_mask:0xa
	s_and_saveexec_b64 s[0:1], vcc
	s_cbranch_execz .LBB0_735
	v_mov_b32_e32 v121, v115
	s_waitcnt lgkmcnt(0)
	v_add_f32_e32 v4, v2, v3
	v_lshl_add_u64 v[2:3], v[122:123], 0, v[120:121]
	global_store_dword v[2:3], v4, off offset:40
.LBB0_735:
	s_or_b64 exec, exec, s[0:1]
	v_max_f32_e32 v2, v9, v9
	v_max_f32_e32 v2, 0, v2
	s_waitcnt lgkmcnt(0)
	v_mul_f32_e32 v3, v138, v2
	s_nop 1
	v_mov_b32_dpp v3, v3 quad_perm:[1,0,3,2] row_mask:0xf bank_mask:0xf
	s_waitcnt lgkmcnt(0)
	v_fmac_f32_e32 v3, v138, v2
	s_nop 1
	v_mov_b32_dpp v2, v3 quad_perm:[2,3,0,1] row_mask:0xf bank_mask:0xf
	s_waitcnt lgkmcnt(0)
	v_add_f32_e32 v2, v3, v2
	s_nop 1
	v_mov_b32_dpp v3, v2 row_shl:4 row_mask:0xf bank_mask:0x5
	v_mov_b32_dpp v3, v2 row_shr:4 row_mask:0xf bank_mask:0xa
	s_and_saveexec_b64 s[0:1], vcc
	s_cbranch_execz .LBB0_737
	v_mov_b32_e32 v121, v115
	s_waitcnt lgkmcnt(0)
	v_add_f32_e32 v4, v2, v3
	v_lshl_add_u64 v[2:3], v[122:123], 0, v[120:121]
	global_store_dword v[2:3], v4, off offset:44
.LBB0_737:
	s_or_b64 exec, exec, s[0:1]
	v_max_f32_e32 v2, v10, v10
	v_max_f32_e32 v2, 0, v2
	s_waitcnt lgkmcnt(0)
	v_mul_f32_e32 v3, v138, v2
	s_nop 1
	v_mov_b32_dpp v3, v3 quad_perm:[1,0,3,2] row_mask:0xf bank_mask:0xf
	s_waitcnt lgkmcnt(0)
	v_fmac_f32_e32 v3, v138, v2
	s_nop 1
	v_mov_b32_dpp v2, v3 quad_perm:[2,3,0,1] row_mask:0xf bank_mask:0xf
	s_waitcnt lgkmcnt(0)
	v_add_f32_e32 v2, v3, v2
	s_nop 1
	v_mov_b32_dpp v3, v2 row_shl:4 row_mask:0xf bank_mask:0x5
	v_mov_b32_dpp v3, v2 row_shr:4 row_mask:0xf bank_mask:0xa
	s_and_saveexec_b64 s[0:1], vcc
	s_cbranch_execz .LBB0_739
	v_mov_b32_e32 v121, v115
	s_waitcnt lgkmcnt(0)
	v_add_f32_e32 v4, v2, v3
	v_lshl_add_u64 v[2:3], v[122:123], 0, v[120:121]
	global_store_dword v[2:3], v4, off offset:64
.LBB0_739:
	s_or_b64 exec, exec, s[0:1]
	v_max_f32_e32 v2, v11, v11
	v_max_f32_e32 v2, 0, v2
	s_waitcnt lgkmcnt(0)
	v_mul_f32_e32 v3, v138, v2
	s_nop 1
	v_mov_b32_dpp v3, v3 quad_perm:[1,0,3,2] row_mask:0xf bank_mask:0xf
	s_waitcnt lgkmcnt(0)
	v_fmac_f32_e32 v3, v138, v2
	s_nop 1
	v_mov_b32_dpp v2, v3 quad_perm:[2,3,0,1] row_mask:0xf bank_mask:0xf
	s_waitcnt lgkmcnt(0)
	v_add_f32_e32 v2, v3, v2
	s_nop 1
	v_mov_b32_dpp v3, v2 row_shl:4 row_mask:0xf bank_mask:0x5
	v_mov_b32_dpp v3, v2 row_shr:4 row_mask:0xf bank_mask:0xa
	s_and_saveexec_b64 s[0:1], vcc
	s_cbranch_execz .LBB0_741
	v_mov_b32_e32 v121, v115
	s_waitcnt lgkmcnt(0)
	v_add_f32_e32 v4, v2, v3
	v_lshl_add_u64 v[2:3], v[122:123], 0, v[120:121]
	global_store_dword v[2:3], v4, off offset:68
.LBB0_741:
	s_or_b64 exec, exec, s[0:1]
	v_max_f32_e32 v2, v12, v12
	v_max_f32_e32 v2, 0, v2
	s_waitcnt lgkmcnt(0)
	v_mul_f32_e32 v3, v138, v2
	s_nop 1
	v_mov_b32_dpp v3, v3 quad_perm:[1,0,3,2] row_mask:0xf bank_mask:0xf
	s_waitcnt lgkmcnt(0)
	v_fmac_f32_e32 v3, v138, v2
	s_nop 1
	v_mov_b32_dpp v2, v3 quad_perm:[2,3,0,1] row_mask:0xf bank_mask:0xf
	s_waitcnt lgkmcnt(0)
	v_add_f32_e32 v2, v3, v2
	s_nop 1
	v_mov_b32_dpp v3, v2 row_shl:4 row_mask:0xf bank_mask:0x5
	v_mov_b32_dpp v3, v2 row_shr:4 row_mask:0xf bank_mask:0xa
	s_and_saveexec_b64 s[0:1], vcc
	s_cbranch_execz .LBB0_743
	v_mov_b32_e32 v121, v115
	s_waitcnt lgkmcnt(0)
	v_add_f32_e32 v4, v2, v3
	v_lshl_add_u64 v[2:3], v[122:123], 0, v[120:121]
	global_store_dword v[2:3], v4, off offset:72
.LBB0_743:
	s_or_b64 exec, exec, s[0:1]
	v_max_f32_e32 v2, v13, v13
	v_max_f32_e32 v2, 0, v2
	s_waitcnt lgkmcnt(0)
	v_mul_f32_e32 v3, v138, v2
	s_nop 1
	v_mov_b32_dpp v3, v3 quad_perm:[1,0,3,2] row_mask:0xf bank_mask:0xf
	s_waitcnt lgkmcnt(0)
	v_fmac_f32_e32 v3, v138, v2
	s_nop 1
	v_mov_b32_dpp v2, v3 quad_perm:[2,3,0,1] row_mask:0xf bank_mask:0xf
	s_waitcnt lgkmcnt(0)
	v_add_f32_e32 v2, v3, v2
	s_nop 1
	v_mov_b32_dpp v3, v2 row_shl:4 row_mask:0xf bank_mask:0x5
	v_mov_b32_dpp v3, v2 row_shr:4 row_mask:0xf bank_mask:0xa
	s_and_saveexec_b64 s[0:1], vcc
	s_cbranch_execz .LBB0_745
	v_mov_b32_e32 v121, v115
	s_waitcnt lgkmcnt(0)
	v_add_f32_e32 v4, v2, v3
	v_lshl_add_u64 v[2:3], v[122:123], 0, v[120:121]
	global_store_dword v[2:3], v4, off offset:76
.LBB0_745:
	s_or_b64 exec, exec, s[0:1]
	v_max_f32_e32 v2, v14, v14
	v_max_f32_e32 v2, 0, v2
	s_waitcnt lgkmcnt(0)
	v_mul_f32_e32 v3, v138, v2
	s_nop 1
	v_mov_b32_dpp v3, v3 quad_perm:[1,0,3,2] row_mask:0xf bank_mask:0xf
	s_waitcnt lgkmcnt(0)
	v_fmac_f32_e32 v3, v138, v2
	s_nop 1
	v_mov_b32_dpp v2, v3 quad_perm:[2,3,0,1] row_mask:0xf bank_mask:0xf
	s_waitcnt lgkmcnt(0)
	v_add_f32_e32 v2, v3, v2
	s_nop 1
	v_mov_b32_dpp v3, v2 row_shl:4 row_mask:0xf bank_mask:0x5
	v_mov_b32_dpp v3, v2 row_shr:4 row_mask:0xf bank_mask:0xa
	s_and_saveexec_b64 s[0:1], vcc
	s_cbranch_execz .LBB0_747
	v_mov_b32_e32 v121, v115
	s_waitcnt lgkmcnt(0)
	v_add_f32_e32 v4, v2, v3
	v_lshl_add_u64 v[2:3], v[122:123], 0, v[120:121]
	global_store_dword v[2:3], v4, off offset:96
.LBB0_747:
	s_or_b64 exec, exec, s[0:1]
	v_max_f32_e32 v2, v15, v15
	v_max_f32_e32 v2, 0, v2
	s_waitcnt lgkmcnt(0)
	v_mul_f32_e32 v3, v138, v2
	s_nop 1
	v_mov_b32_dpp v3, v3 quad_perm:[1,0,3,2] row_mask:0xf bank_mask:0xf
	s_waitcnt lgkmcnt(0)
	v_fmac_f32_e32 v3, v138, v2
	s_nop 1
	v_mov_b32_dpp v2, v3 quad_perm:[2,3,0,1] row_mask:0xf bank_mask:0xf
	s_waitcnt lgkmcnt(0)
	v_add_f32_e32 v2, v3, v2
	s_nop 1
	v_mov_b32_dpp v3, v2 row_shl:4 row_mask:0xf bank_mask:0x5
	v_mov_b32_dpp v3, v2 row_shr:4 row_mask:0xf bank_mask:0xa
	s_and_saveexec_b64 s[0:1], vcc
	s_cbranch_execz .LBB0_749
	v_mov_b32_e32 v121, v115
	s_waitcnt lgkmcnt(0)
	v_add_f32_e32 v4, v2, v3
	v_lshl_add_u64 v[2:3], v[122:123], 0, v[120:121]
	global_store_dword v[2:3], v4, off offset:100
.LBB0_749:
	s_or_b64 exec, exec, s[0:1]
	v_max_f32_e32 v2, v16, v16
	v_max_f32_e32 v2, 0, v2
	s_waitcnt lgkmcnt(0)
	v_mul_f32_e32 v3, v138, v2
	s_nop 1
	v_mov_b32_dpp v3, v3 quad_perm:[1,0,3,2] row_mask:0xf bank_mask:0xf
	s_waitcnt lgkmcnt(0)
	v_fmac_f32_e32 v3, v138, v2
	s_nop 1
	v_mov_b32_dpp v2, v3 quad_perm:[2,3,0,1] row_mask:0xf bank_mask:0xf
	s_waitcnt lgkmcnt(0)
	v_add_f32_e32 v2, v3, v2
	s_nop 1
	v_mov_b32_dpp v3, v2 row_shl:4 row_mask:0xf bank_mask:0x5
	v_mov_b32_dpp v3, v2 row_shr:4 row_mask:0xf bank_mask:0xa
	s_and_saveexec_b64 s[0:1], vcc
	s_cbranch_execz .LBB0_751
	v_mov_b32_e32 v121, v115
	s_waitcnt lgkmcnt(0)
	v_add_f32_e32 v4, v2, v3
	v_lshl_add_u64 v[2:3], v[122:123], 0, v[120:121]
	global_store_dword v[2:3], v4, off offset:104
.LBB0_751:
	s_or_b64 exec, exec, s[0:1]
	v_max_f32_e32 v2, v17, v17
	v_max_f32_e32 v2, 0, v2
	s_waitcnt lgkmcnt(0)
	v_mul_f32_e32 v3, v138, v2
	s_nop 1
	v_mov_b32_dpp v3, v3 quad_perm:[1,0,3,2] row_mask:0xf bank_mask:0xf
	s_waitcnt lgkmcnt(0)
	v_fmac_f32_e32 v3, v138, v2
	s_nop 1
	v_mov_b32_dpp v2, v3 quad_perm:[2,3,0,1] row_mask:0xf bank_mask:0xf
	s_waitcnt lgkmcnt(0)
	v_add_f32_e32 v2, v3, v2
	s_nop 1
	v_mov_b32_dpp v3, v2 row_shl:4 row_mask:0xf bank_mask:0x5
	v_mov_b32_dpp v3, v2 row_shr:4 row_mask:0xf bank_mask:0xa
	s_and_saveexec_b64 s[0:1], vcc
	s_cbranch_execz .LBB0_753
	v_mov_b32_e32 v121, v115
	s_waitcnt lgkmcnt(0)
	v_add_f32_e32 v4, v2, v3
	v_lshl_add_u64 v[2:3], v[122:123], 0, v[120:121]
	global_store_dword v[2:3], v4, off offset:108
.LBB0_753:
	s_or_b64 exec, exec, s[0:1]
	v_or_b32_e32 v2, 0x1000, v144
	v_lshlrev_b32_e32 v143, 3, v136
	v_lshlrev_b32_e32 v114, 2, v2
	s_waitcnt lgkmcnt(0)
	v_lshl_add_u64 v[2:3], v[82:83], 0, v[114:115]
	v_lshlrev_b32_e32 v126, 2, v143
	v_mov_b32_e32 v127, v115
	v_lshl_add_u64 v[2:3], v[2:3], 0, v[126:127]
	global_load_dwordx4 v[70:73], v[2:3], off offset:16
	global_load_dwordx4 v[66:69], v[2:3], off
	global_load_dwordx4 v[78:81], v[2:3], off offset:80
	global_load_dwordx4 v[74:77], v[2:3], off offset:64
	global_load_dwordx4 v[94:97], v[2:3], off offset:144
	global_load_dwordx4 v[90:93], v[2:3], off offset:128
	global_load_dwordx4 v[110:113], v[2:3], off offset:208
	global_load_dwordx4 v[106:109], v[2:3], off offset:192
	s_waitcnt vmcnt(15)
	v_cvt_f16_f32_e32 v5, v41
	s_waitcnt vmcnt(14)
	v_cvt_f16_f32_e32 v2, v34
	v_cvt_pk_f16_f32 v6, v39, v40
	v_cvt_pk_f16_f32 v4, v37, v38
	v_cvt_pk_f16_f32 v3, v35, v36
	v_pack_b32_f16 v2, v2, v3
	v_alignbit_b32 v3, v4, v3, 16
	v_alignbit_b32 v4, v6, v4, 16
	v_alignbit_b32 v5, v5, v6, 16
	s_waitcnt vmcnt(13)
	v_cvt_f16_f32_e32 v49, v49
	s_waitcnt vmcnt(12)
	v_cvt_f16_f32_e32 v42, v42
	v_mfma_f32_32x32x16_f16 v[2:17], v[2:5], v[30:33], 0
	v_cvt_pk_f16_f32 v47, v47, v48
	v_cvt_pk_f16_f32 v45, v45, v46
	v_cvt_pk_f16_f32 v43, v43, v44
	v_pack_b32_f16 v34, v42, v43
	v_alignbit_b32 v35, v45, v43, 16
	v_alignbit_b32 v36, v47, v45, 16
	v_alignbit_b32 v37, v49, v47, 16
	s_waitcnt vmcnt(11)
	v_cvt_f16_f32_e32 v57, v57
	s_waitcnt vmcnt(10)
	v_cvt_f16_f32_e32 v50, v50
	v_mfma_f32_32x32x16_f16 v[2:17], v[34:37], v[26:29], v[2:17]
	v_cvt_pk_f16_f32 v55, v55, v56
	v_cvt_pk_f16_f32 v53, v53, v54
	v_cvt_pk_f16_f32 v51, v51, v52
	v_pack_b32_f16 v34, v50, v51
	v_alignbit_b32 v35, v53, v51, 16
	v_alignbit_b32 v36, v55, v53, 16
	v_alignbit_b32 v37, v57, v55, 16
	s_waitcnt vmcnt(9)
	v_cvt_f16_f32_e32 v65, v65
	s_waitcnt vmcnt(8)
	v_cvt_f16_f32_e32 v58, v58
	v_mfma_f32_32x32x16_f16 v[2:17], v[34:37], v[22:25], v[2:17]
	v_cvt_pk_f16_f32 v63, v63, v64
	v_cvt_pk_f16_f32 v61, v61, v62
	v_cvt_pk_f16_f32 v59, v59, v60
	v_pack_b32_f16 v34, v58, v59
	v_alignbit_b32 v35, v61, v59, 16
	v_alignbit_b32 v36, v63, v61, 16
	v_alignbit_b32 v37, v65, v63, 16
	s_nop 1
	v_mfma_f32_32x32x16_f16 v[2:17], v[34:37], v[18:21], v[2:17]
	s_nop 11
	v_max_f32_e32 v2, v2, v2
	v_max_f32_e32 v2, 0, v2
	v_mul_f32_e32 v34, v138, v2
	s_nop 1
	v_mov_b32_dpp v34, v34 quad_perm:[1,0,3,2] row_mask:0xf bank_mask:0xf
	s_waitcnt lgkmcnt(0)
	v_fmac_f32_e32 v34, v138, v2
	s_nop 1
	v_mov_b32_dpp v2, v34 quad_perm:[2,3,0,1] row_mask:0xf bank_mask:0xf
	s_waitcnt lgkmcnt(0)
	v_add_f32_e32 v2, v34, v2
	s_nop 1
	v_mov_b32_dpp v34, v2 row_shl:4 row_mask:0xf bank_mask:0x5
	v_mov_b32_dpp v34, v2 row_shr:4 row_mask:0xf bank_mask:0xa
	s_and_saveexec_b64 s[0:1], vcc
	s_cbranch_execz .LBB0_755
	v_mov_b32_e32 v121, v115
	s_waitcnt lgkmcnt(0)
	v_add_f32_e32 v2, v2, v34
	v_lshl_add_u64 v[34:35], v[122:123], 0, v[120:121]
	global_store_dword v[34:35], v2, off offset:128
.LBB0_755:
	s_or_b64 exec, exec, s[0:1]
	v_max_f32_e32 v2, v3, v3
	v_max_f32_e32 v2, 0, v2
	v_mul_f32_e32 v3, v138, v2
	s_nop 1
	v_mov_b32_dpp v3, v3 quad_perm:[1,0,3,2] row_mask:0xf bank_mask:0xf
	s_waitcnt lgkmcnt(0)
	v_fmac_f32_e32 v3, v138, v2
	s_nop 1
	v_mov_b32_dpp v2, v3 quad_perm:[2,3,0,1] row_mask:0xf bank_mask:0xf
	s_waitcnt lgkmcnt(0)
	v_add_f32_e32 v2, v3, v2
	s_nop 1
	v_mov_b32_dpp v3, v2 row_shl:4 row_mask:0xf bank_mask:0x5
	v_mov_b32_dpp v3, v2 row_shr:4 row_mask:0xf bank_mask:0xa
	s_and_saveexec_b64 s[0:1], vcc
	s_cbranch_execz .LBB0_757
	v_mov_b32_e32 v121, v115
	s_waitcnt lgkmcnt(0)
	v_add_f32_e32 v34, v2, v3
	v_lshl_add_u64 v[2:3], v[122:123], 0, v[120:121]
	global_store_dword v[2:3], v34, off offset:132
.LBB0_757:
	s_or_b64 exec, exec, s[0:1]
	v_max_f32_e32 v2, v4, v4
	v_max_f32_e32 v2, 0, v2
	s_waitcnt lgkmcnt(0)
	v_mul_f32_e32 v3, v138, v2
	s_nop 1
	v_mov_b32_dpp v3, v3 quad_perm:[1,0,3,2] row_mask:0xf bank_mask:0xf
	s_waitcnt lgkmcnt(0)
	v_fmac_f32_e32 v3, v138, v2
	s_nop 1
	v_mov_b32_dpp v2, v3 quad_perm:[2,3,0,1] row_mask:0xf bank_mask:0xf
	s_waitcnt lgkmcnt(0)
	v_add_f32_e32 v2, v3, v2
	s_nop 1
	v_mov_b32_dpp v3, v2 row_shl:4 row_mask:0xf bank_mask:0x5
	v_mov_b32_dpp v3, v2 row_shr:4 row_mask:0xf bank_mask:0xa
	s_and_saveexec_b64 s[0:1], vcc
	s_cbranch_execz .LBB0_759
	v_mov_b32_e32 v121, v115
	s_waitcnt lgkmcnt(0)
	v_add_f32_e32 v4, v2, v3
	v_lshl_add_u64 v[2:3], v[122:123], 0, v[120:121]
	global_store_dword v[2:3], v4, off offset:136
.LBB0_759:
	s_or_b64 exec, exec, s[0:1]
	v_max_f32_e32 v2, v5, v5
	v_max_f32_e32 v2, 0, v2
	s_waitcnt lgkmcnt(0)
	v_mul_f32_e32 v3, v138, v2
	s_nop 1
	v_mov_b32_dpp v3, v3 quad_perm:[1,0,3,2] row_mask:0xf bank_mask:0xf
	s_waitcnt lgkmcnt(0)
	v_fmac_f32_e32 v3, v138, v2
	s_nop 1
	v_mov_b32_dpp v2, v3 quad_perm:[2,3,0,1] row_mask:0xf bank_mask:0xf
	s_waitcnt lgkmcnt(0)
	v_add_f32_e32 v2, v3, v2
	s_nop 1
	v_mov_b32_dpp v3, v2 row_shl:4 row_mask:0xf bank_mask:0x5
	v_mov_b32_dpp v3, v2 row_shr:4 row_mask:0xf bank_mask:0xa
	s_and_saveexec_b64 s[0:1], vcc
	s_cbranch_execz .LBB0_761
	v_mov_b32_e32 v121, v115
	s_waitcnt lgkmcnt(0)
	v_add_f32_e32 v4, v2, v3
	v_lshl_add_u64 v[2:3], v[122:123], 0, v[120:121]
	global_store_dword v[2:3], v4, off offset:140
.LBB0_761:
	s_or_b64 exec, exec, s[0:1]
	v_max_f32_e32 v2, v6, v6
	v_max_f32_e32 v2, 0, v2
	s_waitcnt lgkmcnt(0)
	v_mul_f32_e32 v3, v138, v2
	s_nop 1
	v_mov_b32_dpp v3, v3 quad_perm:[1,0,3,2] row_mask:0xf bank_mask:0xf
	s_waitcnt lgkmcnt(0)
	v_fmac_f32_e32 v3, v138, v2
	s_nop 1
	v_mov_b32_dpp v2, v3 quad_perm:[2,3,0,1] row_mask:0xf bank_mask:0xf
	s_waitcnt lgkmcnt(0)
	v_add_f32_e32 v2, v3, v2
	s_nop 1
	v_mov_b32_dpp v3, v2 row_shl:4 row_mask:0xf bank_mask:0x5
	v_mov_b32_dpp v3, v2 row_shr:4 row_mask:0xf bank_mask:0xa
	s_and_saveexec_b64 s[0:1], vcc
	s_cbranch_execz .LBB0_763
	v_mov_b32_e32 v121, v115
	s_waitcnt lgkmcnt(0)
	v_add_f32_e32 v4, v2, v3
	v_lshl_add_u64 v[2:3], v[122:123], 0, v[120:121]
	global_store_dword v[2:3], v4, off offset:160
.LBB0_763:
	s_or_b64 exec, exec, s[0:1]
	v_max_f32_e32 v2, v7, v7
	v_max_f32_e32 v2, 0, v2
	s_waitcnt lgkmcnt(0)
	v_mul_f32_e32 v3, v138, v2
	s_nop 1
	v_mov_b32_dpp v3, v3 quad_perm:[1,0,3,2] row_mask:0xf bank_mask:0xf
	s_waitcnt lgkmcnt(0)
	v_fmac_f32_e32 v3, v138, v2
	s_nop 1
	v_mov_b32_dpp v2, v3 quad_perm:[2,3,0,1] row_mask:0xf bank_mask:0xf
	s_waitcnt lgkmcnt(0)
	v_add_f32_e32 v2, v3, v2
	s_nop 1
	v_mov_b32_dpp v3, v2 row_shl:4 row_mask:0xf bank_mask:0x5
	v_mov_b32_dpp v3, v2 row_shr:4 row_mask:0xf bank_mask:0xa
	s_and_saveexec_b64 s[0:1], vcc
	s_cbranch_execz .LBB0_765
	v_mov_b32_e32 v121, v115
	s_waitcnt lgkmcnt(0)
	v_add_f32_e32 v4, v2, v3
	v_lshl_add_u64 v[2:3], v[122:123], 0, v[120:121]
	global_store_dword v[2:3], v4, off offset:164
.LBB0_765:
	s_or_b64 exec, exec, s[0:1]
	v_max_f32_e32 v2, v8, v8
	v_max_f32_e32 v2, 0, v2
	s_waitcnt lgkmcnt(0)
	v_mul_f32_e32 v3, v138, v2
	s_nop 1
	v_mov_b32_dpp v3, v3 quad_perm:[1,0,3,2] row_mask:0xf bank_mask:0xf
	s_waitcnt lgkmcnt(0)
	v_fmac_f32_e32 v3, v138, v2
	s_nop 1
	v_mov_b32_dpp v2, v3 quad_perm:[2,3,0,1] row_mask:0xf bank_mask:0xf
	s_waitcnt lgkmcnt(0)
	v_add_f32_e32 v2, v3, v2
	s_nop 1
	v_mov_b32_dpp v3, v2 row_shl:4 row_mask:0xf bank_mask:0x5
	v_mov_b32_dpp v3, v2 row_shr:4 row_mask:0xf bank_mask:0xa
	s_and_saveexec_b64 s[0:1], vcc
	s_cbranch_execz .LBB0_767
	v_mov_b32_e32 v121, v115
	s_waitcnt lgkmcnt(0)
	v_add_f32_e32 v4, v2, v3
	v_lshl_add_u64 v[2:3], v[122:123], 0, v[120:121]
	global_store_dword v[2:3], v4, off offset:168
.LBB0_767:
	s_or_b64 exec, exec, s[0:1]
	v_max_f32_e32 v2, v9, v9
	v_max_f32_e32 v2, 0, v2
	s_waitcnt lgkmcnt(0)
	v_mul_f32_e32 v3, v138, v2
	s_nop 1
	v_mov_b32_dpp v3, v3 quad_perm:[1,0,3,2] row_mask:0xf bank_mask:0xf
	s_waitcnt lgkmcnt(0)
	v_fmac_f32_e32 v3, v138, v2
	s_nop 1
	v_mov_b32_dpp v2, v3 quad_perm:[2,3,0,1] row_mask:0xf bank_mask:0xf
	s_waitcnt lgkmcnt(0)
	v_add_f32_e32 v2, v3, v2
	s_nop 1
	v_mov_b32_dpp v3, v2 row_shl:4 row_mask:0xf bank_mask:0x5
	v_mov_b32_dpp v3, v2 row_shr:4 row_mask:0xf bank_mask:0xa
	s_and_saveexec_b64 s[0:1], vcc
	s_cbranch_execz .LBB0_769
	v_mov_b32_e32 v121, v115
	s_waitcnt lgkmcnt(0)
	v_add_f32_e32 v4, v2, v3
	v_lshl_add_u64 v[2:3], v[122:123], 0, v[120:121]
	global_store_dword v[2:3], v4, off offset:172
.LBB0_769:
	s_or_b64 exec, exec, s[0:1]
	v_max_f32_e32 v2, v10, v10
	v_max_f32_e32 v2, 0, v2
	s_waitcnt lgkmcnt(0)
	v_mul_f32_e32 v3, v138, v2
	s_nop 1
	v_mov_b32_dpp v3, v3 quad_perm:[1,0,3,2] row_mask:0xf bank_mask:0xf
	s_waitcnt lgkmcnt(0)
	v_fmac_f32_e32 v3, v138, v2
	s_nop 1
	v_mov_b32_dpp v2, v3 quad_perm:[2,3,0,1] row_mask:0xf bank_mask:0xf
	s_waitcnt lgkmcnt(0)
	v_add_f32_e32 v2, v3, v2
	s_nop 1
	v_mov_b32_dpp v3, v2 row_shl:4 row_mask:0xf bank_mask:0x5
	v_mov_b32_dpp v3, v2 row_shr:4 row_mask:0xf bank_mask:0xa
	s_and_saveexec_b64 s[0:1], vcc
	s_cbranch_execz .LBB0_771
	v_mov_b32_e32 v121, v115
	s_waitcnt lgkmcnt(0)
	v_add_f32_e32 v4, v2, v3
	v_lshl_add_u64 v[2:3], v[122:123], 0, v[120:121]
	global_store_dword v[2:3], v4, off offset:192
.LBB0_771:
	s_or_b64 exec, exec, s[0:1]
	v_max_f32_e32 v2, v11, v11
	v_max_f32_e32 v2, 0, v2
	s_waitcnt lgkmcnt(0)
	v_mul_f32_e32 v3, v138, v2
	s_nop 1
	v_mov_b32_dpp v3, v3 quad_perm:[1,0,3,2] row_mask:0xf bank_mask:0xf
	s_waitcnt lgkmcnt(0)
	v_fmac_f32_e32 v3, v138, v2
	s_nop 1
	v_mov_b32_dpp v2, v3 quad_perm:[2,3,0,1] row_mask:0xf bank_mask:0xf
	s_waitcnt lgkmcnt(0)
	v_add_f32_e32 v2, v3, v2
	s_nop 1
	v_mov_b32_dpp v3, v2 row_shl:4 row_mask:0xf bank_mask:0x5
	v_mov_b32_dpp v3, v2 row_shr:4 row_mask:0xf bank_mask:0xa
	s_and_saveexec_b64 s[0:1], vcc
	s_cbranch_execz .LBB0_773
	v_mov_b32_e32 v121, v115
	s_waitcnt lgkmcnt(0)
	v_add_f32_e32 v4, v2, v3
	v_lshl_add_u64 v[2:3], v[122:123], 0, v[120:121]
	global_store_dword v[2:3], v4, off offset:196
.LBB0_773:
	s_or_b64 exec, exec, s[0:1]
	v_max_f32_e32 v2, v12, v12
	v_max_f32_e32 v2, 0, v2
	s_waitcnt lgkmcnt(0)
	v_mul_f32_e32 v3, v138, v2
	s_nop 1
	v_mov_b32_dpp v3, v3 quad_perm:[1,0,3,2] row_mask:0xf bank_mask:0xf
	s_waitcnt lgkmcnt(0)
	v_fmac_f32_e32 v3, v138, v2
	s_nop 1
	v_mov_b32_dpp v2, v3 quad_perm:[2,3,0,1] row_mask:0xf bank_mask:0xf
	s_waitcnt lgkmcnt(0)
	v_add_f32_e32 v2, v3, v2
	s_nop 1
	v_mov_b32_dpp v3, v2 row_shl:4 row_mask:0xf bank_mask:0x5
	v_mov_b32_dpp v3, v2 row_shr:4 row_mask:0xf bank_mask:0xa
	s_and_saveexec_b64 s[0:1], vcc
	s_cbranch_execz .LBB0_775
	v_mov_b32_e32 v121, v115
	s_waitcnt lgkmcnt(0)
	v_add_f32_e32 v4, v2, v3
	v_lshl_add_u64 v[2:3], v[122:123], 0, v[120:121]
	global_store_dword v[2:3], v4, off offset:200
.LBB0_775:
	s_or_b64 exec, exec, s[0:1]
	v_max_f32_e32 v2, v13, v13
	v_max_f32_e32 v2, 0, v2
	s_waitcnt lgkmcnt(0)
	v_mul_f32_e32 v3, v138, v2
	s_nop 1
	v_mov_b32_dpp v3, v3 quad_perm:[1,0,3,2] row_mask:0xf bank_mask:0xf
	s_waitcnt lgkmcnt(0)
	v_fmac_f32_e32 v3, v138, v2
	s_nop 1
	v_mov_b32_dpp v2, v3 quad_perm:[2,3,0,1] row_mask:0xf bank_mask:0xf
	s_waitcnt lgkmcnt(0)
	v_add_f32_e32 v2, v3, v2
	s_nop 1
	v_mov_b32_dpp v3, v2 row_shl:4 row_mask:0xf bank_mask:0x5
	v_mov_b32_dpp v3, v2 row_shr:4 row_mask:0xf bank_mask:0xa
	s_and_saveexec_b64 s[0:1], vcc
	s_cbranch_execz .LBB0_777
	v_mov_b32_e32 v121, v115
	s_waitcnt lgkmcnt(0)
	v_add_f32_e32 v4, v2, v3
	v_lshl_add_u64 v[2:3], v[122:123], 0, v[120:121]
	global_store_dword v[2:3], v4, off offset:204
.LBB0_777:
	s_or_b64 exec, exec, s[0:1]
	v_max_f32_e32 v2, v14, v14
	v_max_f32_e32 v2, 0, v2
	s_waitcnt lgkmcnt(0)
	v_mul_f32_e32 v3, v138, v2
	s_nop 1
	v_mov_b32_dpp v3, v3 quad_perm:[1,0,3,2] row_mask:0xf bank_mask:0xf
	s_waitcnt lgkmcnt(0)
	v_fmac_f32_e32 v3, v138, v2
	s_nop 1
	v_mov_b32_dpp v2, v3 quad_perm:[2,3,0,1] row_mask:0xf bank_mask:0xf
	s_waitcnt lgkmcnt(0)
	v_add_f32_e32 v2, v3, v2
	s_nop 1
	v_mov_b32_dpp v3, v2 row_shl:4 row_mask:0xf bank_mask:0x5
	v_mov_b32_dpp v3, v2 row_shr:4 row_mask:0xf bank_mask:0xa
	s_and_saveexec_b64 s[0:1], vcc
	s_cbranch_execz .LBB0_779
	v_mov_b32_e32 v121, v115
	s_waitcnt lgkmcnt(0)
	v_add_f32_e32 v4, v2, v3
	v_lshl_add_u64 v[2:3], v[122:123], 0, v[120:121]
	global_store_dword v[2:3], v4, off offset:224
.LBB0_779:
	s_or_b64 exec, exec, s[0:1]
	v_max_f32_e32 v2, v15, v15
	v_max_f32_e32 v2, 0, v2
	s_waitcnt lgkmcnt(0)
	v_mul_f32_e32 v3, v138, v2
	s_nop 1
	v_mov_b32_dpp v3, v3 quad_perm:[1,0,3,2] row_mask:0xf bank_mask:0xf
	s_waitcnt lgkmcnt(0)
	v_fmac_f32_e32 v3, v138, v2
	s_nop 1
	v_mov_b32_dpp v2, v3 quad_perm:[2,3,0,1] row_mask:0xf bank_mask:0xf
	s_waitcnt lgkmcnt(0)
	v_add_f32_e32 v2, v3, v2
	s_nop 1
	v_mov_b32_dpp v3, v2 row_shl:4 row_mask:0xf bank_mask:0x5
	v_mov_b32_dpp v3, v2 row_shr:4 row_mask:0xf bank_mask:0xa
	s_and_saveexec_b64 s[0:1], vcc
	s_cbranch_execz .LBB0_781
	v_mov_b32_e32 v121, v115
	s_waitcnt lgkmcnt(0)
	v_add_f32_e32 v4, v2, v3
	v_lshl_add_u64 v[2:3], v[122:123], 0, v[120:121]
	global_store_dword v[2:3], v4, off offset:228
.LBB0_781:
	s_or_b64 exec, exec, s[0:1]
	v_max_f32_e32 v2, v16, v16
	v_max_f32_e32 v2, 0, v2
	s_waitcnt lgkmcnt(0)
	v_mul_f32_e32 v3, v138, v2
	s_nop 1
	v_mov_b32_dpp v3, v3 quad_perm:[1,0,3,2] row_mask:0xf bank_mask:0xf
	s_waitcnt lgkmcnt(0)
	v_fmac_f32_e32 v3, v138, v2
	s_nop 1
	v_mov_b32_dpp v2, v3 quad_perm:[2,3,0,1] row_mask:0xf bank_mask:0xf
	s_waitcnt lgkmcnt(0)
	v_add_f32_e32 v2, v3, v2
	s_nop 1
	v_mov_b32_dpp v3, v2 row_shl:4 row_mask:0xf bank_mask:0x5
	v_mov_b32_dpp v3, v2 row_shr:4 row_mask:0xf bank_mask:0xa
	s_and_saveexec_b64 s[0:1], vcc
	s_cbranch_execz .LBB0_783
	v_mov_b32_e32 v121, v115
	s_waitcnt lgkmcnt(0)
	v_add_f32_e32 v4, v2, v3
	v_lshl_add_u64 v[2:3], v[122:123], 0, v[120:121]
	global_store_dword v[2:3], v4, off offset:232
.LBB0_783:
	s_or_b64 exec, exec, s[0:1]
	v_max_f32_e32 v2, v17, v17
	v_max_f32_e32 v2, 0, v2
	s_waitcnt lgkmcnt(0)
	v_mul_f32_e32 v3, v138, v2
	s_nop 1
	v_mov_b32_dpp v3, v3 quad_perm:[1,0,3,2] row_mask:0xf bank_mask:0xf
	s_waitcnt lgkmcnt(0)
	v_fmac_f32_e32 v3, v138, v2
	s_nop 1
	v_mov_b32_dpp v2, v3 quad_perm:[2,3,0,1] row_mask:0xf bank_mask:0xf
	s_waitcnt lgkmcnt(0)
	v_add_f32_e32 v2, v3, v2
	s_nop 1
	v_mov_b32_dpp v3, v2 row_shl:4 row_mask:0xf bank_mask:0x5
	v_mov_b32_dpp v3, v2 row_shr:4 row_mask:0xf bank_mask:0xa
	s_and_saveexec_b64 s[0:1], vcc
	s_cbranch_execz .LBB0_785
	v_mov_b32_e32 v121, v115
	s_waitcnt lgkmcnt(0)
	v_add_f32_e32 v4, v2, v3
	v_lshl_add_u64 v[2:3], v[122:123], 0, v[120:121]
	global_store_dword v[2:3], v4, off offset:236
.LBB0_785:
	s_or_b64 exec, exec, s[0:1]
	v_or_b32_e32 v2, 0x1800, v144
	v_lshlrev_b32_e32 v130, 2, v2
	v_mov_b32_e32 v131, v115
	s_waitcnt lgkmcnt(0)
	v_lshl_add_u64 v[2:3], v[82:83], 0, v[130:131]
	v_mov_b32_e32 v127, v115
	v_lshl_add_u64 v[2:3], v[2:3], 0, v[126:127]
	global_load_dwordx4 v[42:45], v[2:3], off offset:16
	global_load_dwordx4 v[34:37], v[2:3], off
	global_load_dwordx4 v[54:57], v[2:3], off offset:80
	global_load_dwordx4 v[50:53], v[2:3], off offset:64
	global_load_dwordx4 v[86:89], v[2:3], off offset:144
	global_load_dwordx4 v[82:85], v[2:3], off offset:128
	global_load_dwordx4 v[102:105], v[2:3], off offset:208
	global_load_dwordx4 v[98:101], v[2:3], off offset:192
	s_waitcnt vmcnt(15)
	v_cvt_f16_f32_e32 v5, v73
	s_waitcnt vmcnt(14)
	v_cvt_f16_f32_e32 v2, v66
	v_cvt_pk_f16_f32 v6, v71, v72
	v_cvt_pk_f16_f32 v4, v69, v70
	v_cvt_pk_f16_f32 v3, v67, v68
	v_pack_b32_f16 v2, v2, v3
	v_alignbit_b32 v3, v4, v3, 16
	v_alignbit_b32 v4, v6, v4, 16
	v_alignbit_b32 v5, v5, v6, 16
	s_waitcnt vmcnt(13)
	v_cvt_f16_f32_e32 v41, v81
	s_waitcnt vmcnt(12)
	v_cvt_f16_f32_e32 v38, v74
	v_mfma_f32_32x32x16_f16 v[2:17], v[2:5], v[30:33], 0
	v_cvt_pk_f16_f32 v64, v79, v80
	v_cvt_pk_f16_f32 v40, v77, v78
	v_cvt_pk_f16_f32 v39, v75, v76
	v_pack_b32_f16 v38, v38, v39
	v_alignbit_b32 v39, v40, v39, 16
	v_alignbit_b32 v40, v64, v40, 16
	v_alignbit_b32 v41, v41, v64, 16
	s_waitcnt vmcnt(11)
	v_cvt_f16_f32_e32 v59, v97
	s_waitcnt vmcnt(10)
	v_cvt_f16_f32_e32 v63, v90
	v_mfma_f32_32x32x16_f16 v[2:17], v[38:41], v[26:29], v[2:17]
	v_cvt_pk_f16_f32 v60, v95, v96
	v_cvt_pk_f16_f32 v61, v93, v94
	v_cvt_pk_f16_f32 v62, v91, v92
	v_pack_b32_f16 v38, v63, v62
	v_alignbit_b32 v39, v61, v62, 16
	v_alignbit_b32 v40, v60, v61, 16
	v_alignbit_b32 v41, v59, v60, 16
	s_waitcnt vmcnt(9)
	v_cvt_f16_f32_e32 v46, v113
	s_waitcnt vmcnt(8)
	v_cvt_f16_f32_e32 v58, v106
	v_mfma_f32_32x32x16_f16 v[2:17], v[38:41], v[22:25], v[2:17]
	v_cvt_pk_f16_f32 v47, v111, v112
	v_cvt_pk_f16_f32 v48, v109, v110
	v_cvt_pk_f16_f32 v49, v107, v108
	v_pack_b32_f16 v38, v58, v49
	v_alignbit_b32 v39, v48, v49, 16
	v_alignbit_b32 v40, v47, v48, 16
	v_alignbit_b32 v41, v46, v47, 16
	s_nop 1
	v_mfma_f32_32x32x16_f16 v[2:17], v[38:41], v[18:21], v[2:17]
	s_nop 11
	v_max_f32_e32 v2, v2, v2
	v_max_f32_e32 v2, 0, v2
	v_mul_f32_e32 v38, v138, v2
	s_nop 1
	v_mov_b32_dpp v38, v38 quad_perm:[1,0,3,2] row_mask:0xf bank_mask:0xf
	s_waitcnt lgkmcnt(0)
	v_fmac_f32_e32 v38, v138, v2
	s_nop 1
	v_mov_b32_dpp v2, v38 quad_perm:[2,3,0,1] row_mask:0xf bank_mask:0xf
	s_waitcnt lgkmcnt(0)
	v_add_f32_e32 v2, v38, v2
	s_nop 1
	v_mov_b32_dpp v38, v2 row_shl:4 row_mask:0xf bank_mask:0x5
	v_mov_b32_dpp v38, v2 row_shr:4 row_mask:0xf bank_mask:0xa
	s_and_saveexec_b64 s[0:1], vcc
	s_cbranch_execz .LBB0_787
	v_mov_b32_e32 v121, v115
	s_waitcnt lgkmcnt(0)
	v_add_f32_e32 v2, v2, v38
	v_lshl_add_u64 v[38:39], v[122:123], 0, v[120:121]
	global_store_dword v[38:39], v2, off offset:256
.LBB0_787:
	s_or_b64 exec, exec, s[0:1]
	v_max_f32_e32 v2, v3, v3
	v_max_f32_e32 v2, 0, v2
	v_mul_f32_e32 v3, v138, v2
	s_nop 1
	v_mov_b32_dpp v3, v3 quad_perm:[1,0,3,2] row_mask:0xf bank_mask:0xf
	s_waitcnt lgkmcnt(0)
	v_fmac_f32_e32 v3, v138, v2
	s_nop 1
	v_mov_b32_dpp v2, v3 quad_perm:[2,3,0,1] row_mask:0xf bank_mask:0xf
	s_waitcnt lgkmcnt(0)
	v_add_f32_e32 v2, v3, v2
	s_nop 1
	v_mov_b32_dpp v3, v2 row_shl:4 row_mask:0xf bank_mask:0x5
	v_mov_b32_dpp v3, v2 row_shr:4 row_mask:0xf bank_mask:0xa
	s_and_saveexec_b64 s[0:1], vcc
	s_cbranch_execz .LBB0_789
	v_mov_b32_e32 v121, v115
	s_waitcnt lgkmcnt(0)
	v_add_f32_e32 v38, v2, v3
	v_lshl_add_u64 v[2:3], v[122:123], 0, v[120:121]
	global_store_dword v[2:3], v38, off offset:260
.LBB0_789:
	s_or_b64 exec, exec, s[0:1]
	v_max_f32_e32 v2, v4, v4
	v_max_f32_e32 v2, 0, v2
	s_waitcnt lgkmcnt(0)
	v_mul_f32_e32 v3, v138, v2
	s_nop 1
	v_mov_b32_dpp v3, v3 quad_perm:[1,0,3,2] row_mask:0xf bank_mask:0xf
	s_waitcnt lgkmcnt(0)
	v_fmac_f32_e32 v3, v138, v2
	s_nop 1
	v_mov_b32_dpp v2, v3 quad_perm:[2,3,0,1] row_mask:0xf bank_mask:0xf
	s_waitcnt lgkmcnt(0)
	v_add_f32_e32 v2, v3, v2
	s_nop 1
	v_mov_b32_dpp v3, v2 row_shl:4 row_mask:0xf bank_mask:0x5
	v_mov_b32_dpp v3, v2 row_shr:4 row_mask:0xf bank_mask:0xa
	s_and_saveexec_b64 s[0:1], vcc
	s_cbranch_execz .LBB0_791
	v_mov_b32_e32 v121, v115
	s_waitcnt lgkmcnt(0)
	v_add_f32_e32 v4, v2, v3
	v_lshl_add_u64 v[2:3], v[122:123], 0, v[120:121]
	global_store_dword v[2:3], v4, off offset:264
.LBB0_791:
	s_or_b64 exec, exec, s[0:1]
	v_max_f32_e32 v2, v5, v5
	v_max_f32_e32 v2, 0, v2
	s_waitcnt lgkmcnt(0)
	v_mul_f32_e32 v3, v138, v2
	s_nop 1
	v_mov_b32_dpp v3, v3 quad_perm:[1,0,3,2] row_mask:0xf bank_mask:0xf
	s_waitcnt lgkmcnt(0)
	v_fmac_f32_e32 v3, v138, v2
	s_nop 1
	v_mov_b32_dpp v2, v3 quad_perm:[2,3,0,1] row_mask:0xf bank_mask:0xf
	s_waitcnt lgkmcnt(0)
	v_add_f32_e32 v2, v3, v2
	s_nop 1
	v_mov_b32_dpp v3, v2 row_shl:4 row_mask:0xf bank_mask:0x5
	v_mov_b32_dpp v3, v2 row_shr:4 row_mask:0xf bank_mask:0xa
	s_and_saveexec_b64 s[0:1], vcc
	s_cbranch_execz .LBB0_793
	v_mov_b32_e32 v121, v115
	s_waitcnt lgkmcnt(0)
	v_add_f32_e32 v4, v2, v3
	v_lshl_add_u64 v[2:3], v[122:123], 0, v[120:121]
	global_store_dword v[2:3], v4, off offset:268
.LBB0_793:
	s_or_b64 exec, exec, s[0:1]
	v_max_f32_e32 v2, v6, v6
	v_max_f32_e32 v2, 0, v2
	s_waitcnt lgkmcnt(0)
	v_mul_f32_e32 v3, v138, v2
	s_nop 1
	v_mov_b32_dpp v3, v3 quad_perm:[1,0,3,2] row_mask:0xf bank_mask:0xf
	s_waitcnt lgkmcnt(0)
	v_fmac_f32_e32 v3, v138, v2
	s_nop 1
	v_mov_b32_dpp v2, v3 quad_perm:[2,3,0,1] row_mask:0xf bank_mask:0xf
	s_waitcnt lgkmcnt(0)
	v_add_f32_e32 v2, v3, v2
	s_nop 1
	v_mov_b32_dpp v3, v2 row_shl:4 row_mask:0xf bank_mask:0x5
	v_mov_b32_dpp v3, v2 row_shr:4 row_mask:0xf bank_mask:0xa
	s_and_saveexec_b64 s[0:1], vcc
	s_cbranch_execz .LBB0_795
	v_mov_b32_e32 v121, v115
	s_waitcnt lgkmcnt(0)
	v_add_f32_e32 v4, v2, v3
	v_lshl_add_u64 v[2:3], v[122:123], 0, v[120:121]
	global_store_dword v[2:3], v4, off offset:288
.LBB0_795:
	s_or_b64 exec, exec, s[0:1]
	v_max_f32_e32 v2, v7, v7
	v_max_f32_e32 v2, 0, v2
	s_waitcnt lgkmcnt(0)
	v_mul_f32_e32 v3, v138, v2
	s_nop 1
	v_mov_b32_dpp v3, v3 quad_perm:[1,0,3,2] row_mask:0xf bank_mask:0xf
	s_waitcnt lgkmcnt(0)
	v_fmac_f32_e32 v3, v138, v2
	s_nop 1
	v_mov_b32_dpp v2, v3 quad_perm:[2,3,0,1] row_mask:0xf bank_mask:0xf
	s_waitcnt lgkmcnt(0)
	v_add_f32_e32 v2, v3, v2
	s_nop 1
	v_mov_b32_dpp v3, v2 row_shl:4 row_mask:0xf bank_mask:0x5
	v_mov_b32_dpp v3, v2 row_shr:4 row_mask:0xf bank_mask:0xa
	s_and_saveexec_b64 s[0:1], vcc
	s_cbranch_execz .LBB0_797
	v_mov_b32_e32 v121, v115
	s_waitcnt lgkmcnt(0)
	v_add_f32_e32 v4, v2, v3
	v_lshl_add_u64 v[2:3], v[122:123], 0, v[120:121]
	global_store_dword v[2:3], v4, off offset:292
.LBB0_797:
	s_or_b64 exec, exec, s[0:1]
	v_max_f32_e32 v2, v8, v8
	v_max_f32_e32 v2, 0, v2
	s_waitcnt lgkmcnt(0)
	v_mul_f32_e32 v3, v138, v2
	s_nop 1
	v_mov_b32_dpp v3, v3 quad_perm:[1,0,3,2] row_mask:0xf bank_mask:0xf
	s_waitcnt lgkmcnt(0)
	v_fmac_f32_e32 v3, v138, v2
	s_nop 1
	v_mov_b32_dpp v2, v3 quad_perm:[2,3,0,1] row_mask:0xf bank_mask:0xf
	s_waitcnt lgkmcnt(0)
	v_add_f32_e32 v2, v3, v2
	s_nop 1
	v_mov_b32_dpp v3, v2 row_shl:4 row_mask:0xf bank_mask:0x5
	v_mov_b32_dpp v3, v2 row_shr:4 row_mask:0xf bank_mask:0xa
	s_and_saveexec_b64 s[0:1], vcc
	s_cbranch_execz .LBB0_799
	v_mov_b32_e32 v121, v115
	s_waitcnt lgkmcnt(0)
	v_add_f32_e32 v4, v2, v3
	v_lshl_add_u64 v[2:3], v[122:123], 0, v[120:121]
	global_store_dword v[2:3], v4, off offset:296
.LBB0_799:
	s_or_b64 exec, exec, s[0:1]
	v_max_f32_e32 v2, v9, v9
	v_max_f32_e32 v2, 0, v2
	s_waitcnt lgkmcnt(0)
	v_mul_f32_e32 v3, v138, v2
	s_nop 1
	v_mov_b32_dpp v3, v3 quad_perm:[1,0,3,2] row_mask:0xf bank_mask:0xf
	s_waitcnt lgkmcnt(0)
	v_fmac_f32_e32 v3, v138, v2
	s_nop 1
	v_mov_b32_dpp v2, v3 quad_perm:[2,3,0,1] row_mask:0xf bank_mask:0xf
	s_waitcnt lgkmcnt(0)
	v_add_f32_e32 v2, v3, v2
	s_nop 1
	v_mov_b32_dpp v3, v2 row_shl:4 row_mask:0xf bank_mask:0x5
	v_mov_b32_dpp v3, v2 row_shr:4 row_mask:0xf bank_mask:0xa
	s_and_saveexec_b64 s[0:1], vcc
	s_cbranch_execz .LBB0_801
	v_mov_b32_e32 v121, v115
	s_waitcnt lgkmcnt(0)
	v_add_f32_e32 v4, v2, v3
	v_lshl_add_u64 v[2:3], v[122:123], 0, v[120:121]
	global_store_dword v[2:3], v4, off offset:300
.LBB0_801:
	s_or_b64 exec, exec, s[0:1]
	v_max_f32_e32 v2, v10, v10
	v_max_f32_e32 v2, 0, v2
	s_waitcnt lgkmcnt(0)
	v_mul_f32_e32 v3, v138, v2
	s_nop 1
	v_mov_b32_dpp v3, v3 quad_perm:[1,0,3,2] row_mask:0xf bank_mask:0xf
	s_waitcnt lgkmcnt(0)
	v_fmac_f32_e32 v3, v138, v2
	s_nop 1
	v_mov_b32_dpp v2, v3 quad_perm:[2,3,0,1] row_mask:0xf bank_mask:0xf
	s_waitcnt lgkmcnt(0)
	v_add_f32_e32 v2, v3, v2
	s_nop 1
	v_mov_b32_dpp v3, v2 row_shl:4 row_mask:0xf bank_mask:0x5
	v_mov_b32_dpp v3, v2 row_shr:4 row_mask:0xf bank_mask:0xa
	s_and_saveexec_b64 s[0:1], vcc
	s_cbranch_execz .LBB0_803
	v_mov_b32_e32 v121, v115
	s_waitcnt lgkmcnt(0)
	v_add_f32_e32 v4, v2, v3
	v_lshl_add_u64 v[2:3], v[122:123], 0, v[120:121]
	global_store_dword v[2:3], v4, off offset:320
.LBB0_803:
	s_or_b64 exec, exec, s[0:1]
	v_max_f32_e32 v2, v11, v11
	v_max_f32_e32 v2, 0, v2
	s_waitcnt lgkmcnt(0)
	v_mul_f32_e32 v3, v138, v2
	s_nop 1
	v_mov_b32_dpp v3, v3 quad_perm:[1,0,3,2] row_mask:0xf bank_mask:0xf
	s_waitcnt lgkmcnt(0)
	v_fmac_f32_e32 v3, v138, v2
	s_nop 1
	v_mov_b32_dpp v2, v3 quad_perm:[2,3,0,1] row_mask:0xf bank_mask:0xf
	s_waitcnt lgkmcnt(0)
	v_add_f32_e32 v2, v3, v2
	s_nop 1
	v_mov_b32_dpp v3, v2 row_shl:4 row_mask:0xf bank_mask:0x5
	v_mov_b32_dpp v3, v2 row_shr:4 row_mask:0xf bank_mask:0xa
	s_and_saveexec_b64 s[0:1], vcc
	s_cbranch_execz .LBB0_805
	v_mov_b32_e32 v121, v115
	s_waitcnt lgkmcnt(0)
	v_add_f32_e32 v4, v2, v3
	v_lshl_add_u64 v[2:3], v[122:123], 0, v[120:121]
	global_store_dword v[2:3], v4, off offset:324
.LBB0_805:
	s_or_b64 exec, exec, s[0:1]
	v_max_f32_e32 v2, v12, v12
	v_max_f32_e32 v2, 0, v2
	s_waitcnt lgkmcnt(0)
	v_mul_f32_e32 v3, v138, v2
	s_nop 1
	v_mov_b32_dpp v3, v3 quad_perm:[1,0,3,2] row_mask:0xf bank_mask:0xf
	s_waitcnt lgkmcnt(0)
	v_fmac_f32_e32 v3, v138, v2
	s_nop 1
	v_mov_b32_dpp v2, v3 quad_perm:[2,3,0,1] row_mask:0xf bank_mask:0xf
	s_waitcnt lgkmcnt(0)
	v_add_f32_e32 v2, v3, v2
	s_nop 1
	v_mov_b32_dpp v3, v2 row_shl:4 row_mask:0xf bank_mask:0x5
	v_mov_b32_dpp v3, v2 row_shr:4 row_mask:0xf bank_mask:0xa
	s_and_saveexec_b64 s[0:1], vcc
	s_cbranch_execz .LBB0_807
	v_mov_b32_e32 v121, v115
	s_waitcnt lgkmcnt(0)
	v_add_f32_e32 v4, v2, v3
	v_lshl_add_u64 v[2:3], v[122:123], 0, v[120:121]
	global_store_dword v[2:3], v4, off offset:328
.LBB0_807:
	s_or_b64 exec, exec, s[0:1]
	v_max_f32_e32 v2, v13, v13
	v_max_f32_e32 v2, 0, v2
	s_waitcnt lgkmcnt(0)
	v_mul_f32_e32 v3, v138, v2
	s_nop 1
	v_mov_b32_dpp v3, v3 quad_perm:[1,0,3,2] row_mask:0xf bank_mask:0xf
	s_waitcnt lgkmcnt(0)
	v_fmac_f32_e32 v3, v138, v2
	s_nop 1
	v_mov_b32_dpp v2, v3 quad_perm:[2,3,0,1] row_mask:0xf bank_mask:0xf
	s_waitcnt lgkmcnt(0)
	v_add_f32_e32 v2, v3, v2
	s_nop 1
	v_mov_b32_dpp v3, v2 row_shl:4 row_mask:0xf bank_mask:0x5
	v_mov_b32_dpp v3, v2 row_shr:4 row_mask:0xf bank_mask:0xa
	s_and_saveexec_b64 s[0:1], vcc
	s_cbranch_execz .LBB0_809
	v_mov_b32_e32 v121, v115
	s_waitcnt lgkmcnt(0)
	v_add_f32_e32 v4, v2, v3
	v_lshl_add_u64 v[2:3], v[122:123], 0, v[120:121]
	global_store_dword v[2:3], v4, off offset:332
.LBB0_809:
	s_or_b64 exec, exec, s[0:1]
	v_max_f32_e32 v2, v14, v14
	v_max_f32_e32 v2, 0, v2
	s_waitcnt lgkmcnt(0)
	v_mul_f32_e32 v3, v138, v2
	s_nop 1
	v_mov_b32_dpp v3, v3 quad_perm:[1,0,3,2] row_mask:0xf bank_mask:0xf
	s_waitcnt lgkmcnt(0)
	v_fmac_f32_e32 v3, v138, v2
	s_nop 1
	v_mov_b32_dpp v2, v3 quad_perm:[2,3,0,1] row_mask:0xf bank_mask:0xf
	s_waitcnt lgkmcnt(0)
	v_add_f32_e32 v2, v3, v2
	s_nop 1
	v_mov_b32_dpp v3, v2 row_shl:4 row_mask:0xf bank_mask:0x5
	v_mov_b32_dpp v3, v2 row_shr:4 row_mask:0xf bank_mask:0xa
	s_and_saveexec_b64 s[0:1], vcc
	s_cbranch_execz .LBB0_811
	v_mov_b32_e32 v121, v115
	s_waitcnt lgkmcnt(0)
	v_add_f32_e32 v4, v2, v3
	v_lshl_add_u64 v[2:3], v[122:123], 0, v[120:121]
	global_store_dword v[2:3], v4, off offset:352
.LBB0_811:
	s_or_b64 exec, exec, s[0:1]
	v_max_f32_e32 v2, v15, v15
	v_max_f32_e32 v2, 0, v2
	s_waitcnt lgkmcnt(0)
	v_mul_f32_e32 v3, v138, v2
	s_nop 1
	v_mov_b32_dpp v3, v3 quad_perm:[1,0,3,2] row_mask:0xf bank_mask:0xf
	s_waitcnt lgkmcnt(0)
	v_fmac_f32_e32 v3, v138, v2
	s_nop 1
	v_mov_b32_dpp v2, v3 quad_perm:[2,3,0,1] row_mask:0xf bank_mask:0xf
	s_waitcnt lgkmcnt(0)
	v_add_f32_e32 v2, v3, v2
	s_nop 1
	v_mov_b32_dpp v3, v2 row_shl:4 row_mask:0xf bank_mask:0x5
	v_mov_b32_dpp v3, v2 row_shr:4 row_mask:0xf bank_mask:0xa
	s_and_saveexec_b64 s[0:1], vcc
	s_cbranch_execz .LBB0_813
	v_mov_b32_e32 v121, v115
	s_waitcnt lgkmcnt(0)
	v_add_f32_e32 v4, v2, v3
	v_lshl_add_u64 v[2:3], v[122:123], 0, v[120:121]
	global_store_dword v[2:3], v4, off offset:356
.LBB0_813:
	s_or_b64 exec, exec, s[0:1]
	v_max_f32_e32 v2, v16, v16
	v_max_f32_e32 v2, 0, v2
	s_waitcnt lgkmcnt(0)
	v_mul_f32_e32 v3, v138, v2
	s_nop 1
	v_mov_b32_dpp v3, v3 quad_perm:[1,0,3,2] row_mask:0xf bank_mask:0xf
	s_waitcnt lgkmcnt(0)
	v_fmac_f32_e32 v3, v138, v2
	s_nop 1
	v_mov_b32_dpp v2, v3 quad_perm:[2,3,0,1] row_mask:0xf bank_mask:0xf
	s_waitcnt lgkmcnt(0)
	v_add_f32_e32 v2, v3, v2
	s_nop 1
	v_mov_b32_dpp v3, v2 row_shl:4 row_mask:0xf bank_mask:0x5
	v_mov_b32_dpp v3, v2 row_shr:4 row_mask:0xf bank_mask:0xa
	s_and_saveexec_b64 s[0:1], vcc
	s_cbranch_execz .LBB0_815
	v_mov_b32_e32 v121, v115
	s_waitcnt lgkmcnt(0)
	v_add_f32_e32 v4, v2, v3
	v_lshl_add_u64 v[2:3], v[122:123], 0, v[120:121]
	global_store_dword v[2:3], v4, off offset:360
.LBB0_815:
	s_or_b64 exec, exec, s[0:1]
	v_max_f32_e32 v2, v17, v17
	v_max_f32_e32 v2, 0, v2
	s_waitcnt lgkmcnt(0)
	v_mul_f32_e32 v3, v138, v2
	s_nop 1
	v_mov_b32_dpp v3, v3 quad_perm:[1,0,3,2] row_mask:0xf bank_mask:0xf
	s_waitcnt lgkmcnt(0)
	v_fmac_f32_e32 v3, v138, v2
	s_nop 1
	v_mov_b32_dpp v2, v3 quad_perm:[2,3,0,1] row_mask:0xf bank_mask:0xf
	s_waitcnt lgkmcnt(0)
	v_add_f32_e32 v2, v3, v2
	s_nop 1
	v_mov_b32_dpp v3, v2 row_shl:4 row_mask:0xf bank_mask:0x5
	v_mov_b32_dpp v3, v2 row_shr:4 row_mask:0xf bank_mask:0xa
	s_and_saveexec_b64 s[0:1], vcc
	s_cbranch_execz .LBB0_817
	v_mov_b32_e32 v121, v115
	s_waitcnt lgkmcnt(0)
	v_add_f32_e32 v4, v2, v3
	v_lshl_add_u64 v[2:3], v[122:123], 0, v[120:121]
	global_store_dword v[2:3], v4, off offset:364
.LBB0_817:
	s_or_b64 exec, exec, s[0:1]
	v_ashrrev_i32_e32 v125, 31, v124
	v_readlane_b32 s36, v253, 32
	s_waitcnt lgkmcnt(0)
	v_lshlrev_b64 v[2:3], 15, v[124:125]
	v_readlane_b32 s44, v253, 40
	v_readlane_b32 s45, v253, 41
	v_lshlrev_b32_e32 v4, 2, v144
	v_mov_b32_e32 v5, v115
	v_lshl_add_u64 v[2:3], s[44:45], 0, v[2:3]
	v_lshl_add_u64 v[2:3], v[2:3], 0, v[4:5]
	v_mov_b32_e32 v127, v115
	v_lshl_add_u64 v[2:3], v[2:3], 0, v[126:127]
	global_load_dwordx4 v[46:49], v[2:3], off offset:16
	global_load_dwordx4 v[38:41], v[2:3], off
	global_load_dwordx4 v[62:65], v[2:3], off offset:80
	global_load_dwordx4 v[58:61], v[2:3], off offset:64
	global_load_dwordx4 v[78:81], v[2:3], off offset:144
	global_load_dwordx4 v[70:73], v[2:3], off offset:128
	global_load_dwordx4 v[94:97], v[2:3], off offset:208
	global_load_dwordx4 v[90:93], v[2:3], off offset:192
	s_waitcnt vmcnt(15)
	v_cvt_f16_f32_e32 v5, v45
	s_waitcnt vmcnt(14)
	v_cvt_f16_f32_e32 v2, v34
	v_cvt_pk_f16_f32 v6, v43, v44
	v_cvt_pk_f16_f32 v4, v37, v42
	v_cvt_pk_f16_f32 v3, v35, v36
	v_pack_b32_f16 v2, v2, v3
	v_alignbit_b32 v3, v4, v3, 16
	v_alignbit_b32 v4, v6, v4, 16
	v_alignbit_b32 v5, v5, v6, 16
	s_waitcnt vmcnt(13)
	v_cvt_f16_f32_e32 v57, v57
	s_waitcnt vmcnt(12)
	v_cvt_f16_f32_e32 v50, v50
	v_mfma_f32_32x32x16_f16 v[2:17], v[2:5], v[30:33], 0
	v_cvt_pk_f16_f32 v55, v55, v56
	v_cvt_pk_f16_f32 v53, v53, v54
	v_cvt_pk_f16_f32 v51, v51, v52
	v_pack_b32_f16 v34, v50, v51
	v_alignbit_b32 v35, v53, v51, 16
	v_alignbit_b32 v36, v55, v53, 16
	v_alignbit_b32 v37, v57, v55, 16
	s_waitcnt vmcnt(11)
	v_cvt_f16_f32_e32 v75, v89
	s_waitcnt vmcnt(10)
	v_cvt_f16_f32_e32 v82, v82
	v_mfma_f32_32x32x16_f16 v[2:17], v[34:37], v[26:29], v[2:17]
	v_cvt_pk_f16_f32 v76, v87, v88
	v_cvt_pk_f16_f32 v77, v85, v86
	v_cvt_pk_f16_f32 v83, v83, v84
	v_pack_b32_f16 v34, v82, v83
	v_alignbit_b32 v35, v77, v83, 16
	v_alignbit_b32 v36, v76, v77, 16
	v_alignbit_b32 v37, v75, v76, 16
	s_waitcnt vmcnt(9)
	v_cvt_f16_f32_e32 v66, v105
	s_waitcnt vmcnt(8)
	v_cvt_f16_f32_e32 v74, v98
	v_mfma_f32_32x32x16_f16 v[2:17], v[34:37], v[22:25], v[2:17]
	v_cvt_pk_f16_f32 v67, v103, v104
	v_cvt_pk_f16_f32 v68, v101, v102
	v_cvt_pk_f16_f32 v69, v99, v100
	v_pack_b32_f16 v34, v74, v69
	v_alignbit_b32 v35, v68, v69, 16
	v_alignbit_b32 v36, v67, v68, 16
	v_alignbit_b32 v37, v66, v67, 16
	v_readlane_b32 s37, v253, 33
	v_readlane_b32 s38, v253, 34
	v_mfma_f32_32x32x16_f16 v[2:17], v[34:37], v[18:21], v[2:17]
	v_readlane_b32 s39, v253, 35
	v_readlane_b32 s40, v253, 36
	v_readlane_b32 s41, v253, 37
	v_readlane_b32 s42, v253, 38
	v_readlane_b32 s43, v253, 39
	v_readlane_b32 s46, v253, 42
	v_readlane_b32 s47, v253, 43
	s_nop 4
	v_max_f32_e32 v2, v2, v2
	v_max_f32_e32 v2, 0, v2
	v_mul_f32_e32 v34, v138, v2
	s_nop 1
	v_mov_b32_dpp v34, v34 quad_perm:[1,0,3,2] row_mask:0xf bank_mask:0xf
	v_readlane_b32 s48, v253, 44
	v_readlane_b32 s49, v253, 45
	v_readlane_b32 s50, v253, 46
	v_readlane_b32 s51, v253, 47
	s_waitcnt lgkmcnt(0)
	v_fmac_f32_e32 v34, v138, v2
	s_nop 1
	v_mov_b32_dpp v2, v34 quad_perm:[2,3,0,1] row_mask:0xf bank_mask:0xf
	s_waitcnt lgkmcnt(0)
	v_add_f32_e32 v2, v34, v2
	s_nop 1
	v_mov_b32_dpp v34, v2 row_shl:4 row_mask:0xf bank_mask:0x5
	v_mov_b32_dpp v34, v2 row_shr:4 row_mask:0xf bank_mask:0xa
	s_and_saveexec_b64 s[0:1], vcc
	s_cbranch_execz .LBB0_819
	v_mov_b32_e32 v121, v115
	s_waitcnt lgkmcnt(0)
	v_add_f32_e32 v2, v2, v34
	v_lshl_add_u64 v[34:35], v[122:123], 0, v[120:121]
	global_store_dword v[34:35], v2, off offset:384
.LBB0_819:
	s_or_b64 exec, exec, s[0:1]
	v_max_f32_e32 v2, v3, v3
	v_max_f32_e32 v2, 0, v2
	v_mul_f32_e32 v3, v138, v2
	s_nop 1
	v_mov_b32_dpp v3, v3 quad_perm:[1,0,3,2] row_mask:0xf bank_mask:0xf
	s_waitcnt lgkmcnt(0)
	v_fmac_f32_e32 v3, v138, v2
	s_nop 1
	v_mov_b32_dpp v2, v3 quad_perm:[2,3,0,1] row_mask:0xf bank_mask:0xf
	s_waitcnt lgkmcnt(0)
	v_add_f32_e32 v2, v3, v2
	s_nop 1
	v_mov_b32_dpp v3, v2 row_shl:4 row_mask:0xf bank_mask:0x5
	v_mov_b32_dpp v3, v2 row_shr:4 row_mask:0xf bank_mask:0xa
	s_and_saveexec_b64 s[0:1], vcc
	s_cbranch_execz .LBB0_821
	v_mov_b32_e32 v121, v115
	s_waitcnt lgkmcnt(0)
	v_add_f32_e32 v34, v2, v3
	v_lshl_add_u64 v[2:3], v[122:123], 0, v[120:121]
	global_store_dword v[2:3], v34, off offset:388
.LBB0_821:
	s_or_b64 exec, exec, s[0:1]
	v_max_f32_e32 v2, v4, v4
	v_max_f32_e32 v2, 0, v2
	s_waitcnt lgkmcnt(0)
	v_mul_f32_e32 v3, v138, v2
	s_nop 1
	v_mov_b32_dpp v3, v3 quad_perm:[1,0,3,2] row_mask:0xf bank_mask:0xf
	s_waitcnt lgkmcnt(0)
	v_fmac_f32_e32 v3, v138, v2
	s_nop 1
	v_mov_b32_dpp v2, v3 quad_perm:[2,3,0,1] row_mask:0xf bank_mask:0xf
	s_waitcnt lgkmcnt(0)
	v_add_f32_e32 v2, v3, v2
	s_nop 1
	v_mov_b32_dpp v3, v2 row_shl:4 row_mask:0xf bank_mask:0x5
	v_mov_b32_dpp v3, v2 row_shr:4 row_mask:0xf bank_mask:0xa
	s_and_saveexec_b64 s[0:1], vcc
	s_cbranch_execz .LBB0_823
	v_mov_b32_e32 v121, v115
	s_waitcnt lgkmcnt(0)
	v_add_f32_e32 v4, v2, v3
	v_lshl_add_u64 v[2:3], v[122:123], 0, v[120:121]
	global_store_dword v[2:3], v4, off offset:392
.LBB0_823:
	s_or_b64 exec, exec, s[0:1]
	v_max_f32_e32 v2, v5, v5
	v_max_f32_e32 v2, 0, v2
	s_waitcnt lgkmcnt(0)
	v_mul_f32_e32 v3, v138, v2
	s_nop 1
	v_mov_b32_dpp v3, v3 quad_perm:[1,0,3,2] row_mask:0xf bank_mask:0xf
	s_waitcnt lgkmcnt(0)
	v_fmac_f32_e32 v3, v138, v2
	s_nop 1
	v_mov_b32_dpp v2, v3 quad_perm:[2,3,0,1] row_mask:0xf bank_mask:0xf
	s_waitcnt lgkmcnt(0)
	v_add_f32_e32 v2, v3, v2
	s_nop 1
	v_mov_b32_dpp v3, v2 row_shl:4 row_mask:0xf bank_mask:0x5
	v_mov_b32_dpp v3, v2 row_shr:4 row_mask:0xf bank_mask:0xa
	s_and_saveexec_b64 s[0:1], vcc
	s_cbranch_execz .LBB0_825
	v_mov_b32_e32 v121, v115
	s_waitcnt lgkmcnt(0)
	v_add_f32_e32 v4, v2, v3
	v_lshl_add_u64 v[2:3], v[122:123], 0, v[120:121]
	global_store_dword v[2:3], v4, off offset:396
.LBB0_825:
	s_or_b64 exec, exec, s[0:1]
	v_max_f32_e32 v2, v6, v6
	v_max_f32_e32 v2, 0, v2
	s_waitcnt lgkmcnt(0)
	v_mul_f32_e32 v3, v138, v2
	s_nop 1
	v_mov_b32_dpp v3, v3 quad_perm:[1,0,3,2] row_mask:0xf bank_mask:0xf
	s_waitcnt lgkmcnt(0)
	v_fmac_f32_e32 v3, v138, v2
	s_nop 1
	v_mov_b32_dpp v2, v3 quad_perm:[2,3,0,1] row_mask:0xf bank_mask:0xf
	s_waitcnt lgkmcnt(0)
	v_add_f32_e32 v2, v3, v2
	s_nop 1
	v_mov_b32_dpp v3, v2 row_shl:4 row_mask:0xf bank_mask:0x5
	v_mov_b32_dpp v3, v2 row_shr:4 row_mask:0xf bank_mask:0xa
	s_and_saveexec_b64 s[0:1], vcc
	s_cbranch_execz .LBB0_827
	v_mov_b32_e32 v121, v115
	s_waitcnt lgkmcnt(0)
	v_add_f32_e32 v4, v2, v3
	v_lshl_add_u64 v[2:3], v[122:123], 0, v[120:121]
	global_store_dword v[2:3], v4, off offset:416
.LBB0_827:
	s_or_b64 exec, exec, s[0:1]
	v_max_f32_e32 v2, v7, v7
	v_max_f32_e32 v2, 0, v2
	s_waitcnt lgkmcnt(0)
	v_mul_f32_e32 v3, v138, v2
	s_nop 1
	v_mov_b32_dpp v3, v3 quad_perm:[1,0,3,2] row_mask:0xf bank_mask:0xf
	s_waitcnt lgkmcnt(0)
	v_fmac_f32_e32 v3, v138, v2
	s_nop 1
	v_mov_b32_dpp v2, v3 quad_perm:[2,3,0,1] row_mask:0xf bank_mask:0xf
	s_waitcnt lgkmcnt(0)
	v_add_f32_e32 v2, v3, v2
	s_nop 1
	v_mov_b32_dpp v3, v2 row_shl:4 row_mask:0xf bank_mask:0x5
	v_mov_b32_dpp v3, v2 row_shr:4 row_mask:0xf bank_mask:0xa
	s_and_saveexec_b64 s[0:1], vcc
	s_cbranch_execz .LBB0_829
	v_mov_b32_e32 v121, v115
	s_waitcnt lgkmcnt(0)
	v_add_f32_e32 v4, v2, v3
	v_lshl_add_u64 v[2:3], v[122:123], 0, v[120:121]
	global_store_dword v[2:3], v4, off offset:420
.LBB0_829:
	s_or_b64 exec, exec, s[0:1]
	v_max_f32_e32 v2, v8, v8
	v_max_f32_e32 v2, 0, v2
	s_waitcnt lgkmcnt(0)
	v_mul_f32_e32 v3, v138, v2
	s_nop 1
	v_mov_b32_dpp v3, v3 quad_perm:[1,0,3,2] row_mask:0xf bank_mask:0xf
	s_waitcnt lgkmcnt(0)
	v_fmac_f32_e32 v3, v138, v2
	s_nop 1
	v_mov_b32_dpp v2, v3 quad_perm:[2,3,0,1] row_mask:0xf bank_mask:0xf
	s_waitcnt lgkmcnt(0)
	v_add_f32_e32 v2, v3, v2
	s_nop 1
	v_mov_b32_dpp v3, v2 row_shl:4 row_mask:0xf bank_mask:0x5
	v_mov_b32_dpp v3, v2 row_shr:4 row_mask:0xf bank_mask:0xa
	s_and_saveexec_b64 s[0:1], vcc
	s_cbranch_execz .LBB0_831
	v_mov_b32_e32 v121, v115
	s_waitcnt lgkmcnt(0)
	v_add_f32_e32 v4, v2, v3
	v_lshl_add_u64 v[2:3], v[122:123], 0, v[120:121]
	global_store_dword v[2:3], v4, off offset:424
.LBB0_831:
	s_or_b64 exec, exec, s[0:1]
	v_max_f32_e32 v2, v9, v9
	v_max_f32_e32 v2, 0, v2
	s_waitcnt lgkmcnt(0)
	v_mul_f32_e32 v3, v138, v2
	s_nop 1
	v_mov_b32_dpp v3, v3 quad_perm:[1,0,3,2] row_mask:0xf bank_mask:0xf
	s_waitcnt lgkmcnt(0)
	v_fmac_f32_e32 v3, v138, v2
	s_nop 1
	v_mov_b32_dpp v2, v3 quad_perm:[2,3,0,1] row_mask:0xf bank_mask:0xf
	s_waitcnt lgkmcnt(0)
	v_add_f32_e32 v2, v3, v2
	s_nop 1
	v_mov_b32_dpp v3, v2 row_shl:4 row_mask:0xf bank_mask:0x5
	v_mov_b32_dpp v3, v2 row_shr:4 row_mask:0xf bank_mask:0xa
	s_and_saveexec_b64 s[0:1], vcc
	s_cbranch_execz .LBB0_833
	v_mov_b32_e32 v121, v115
	s_waitcnt lgkmcnt(0)
	v_add_f32_e32 v4, v2, v3
	v_lshl_add_u64 v[2:3], v[122:123], 0, v[120:121]
	global_store_dword v[2:3], v4, off offset:428
.LBB0_833:
	s_or_b64 exec, exec, s[0:1]
	v_max_f32_e32 v2, v10, v10
	v_max_f32_e32 v2, 0, v2
	s_waitcnt lgkmcnt(0)
	v_mul_f32_e32 v3, v138, v2
	s_nop 1
	v_mov_b32_dpp v3, v3 quad_perm:[1,0,3,2] row_mask:0xf bank_mask:0xf
	s_waitcnt lgkmcnt(0)
	v_fmac_f32_e32 v3, v138, v2
	s_nop 1
	v_mov_b32_dpp v2, v3 quad_perm:[2,3,0,1] row_mask:0xf bank_mask:0xf
	s_waitcnt lgkmcnt(0)
	v_add_f32_e32 v2, v3, v2
	s_nop 1
	v_mov_b32_dpp v3, v2 row_shl:4 row_mask:0xf bank_mask:0x5
	v_mov_b32_dpp v3, v2 row_shr:4 row_mask:0xf bank_mask:0xa
	s_and_saveexec_b64 s[0:1], vcc
	s_cbranch_execz .LBB0_835
	v_mov_b32_e32 v121, v115
	s_waitcnt lgkmcnt(0)
	v_add_f32_e32 v4, v2, v3
	v_lshl_add_u64 v[2:3], v[122:123], 0, v[120:121]
	global_store_dword v[2:3], v4, off offset:448
.LBB0_835:
	s_or_b64 exec, exec, s[0:1]
	v_max_f32_e32 v2, v11, v11
	v_max_f32_e32 v2, 0, v2
	s_waitcnt lgkmcnt(0)
	v_mul_f32_e32 v3, v138, v2
	s_nop 1
	v_mov_b32_dpp v3, v3 quad_perm:[1,0,3,2] row_mask:0xf bank_mask:0xf
	s_waitcnt lgkmcnt(0)
	v_fmac_f32_e32 v3, v138, v2
	s_nop 1
	v_mov_b32_dpp v2, v3 quad_perm:[2,3,0,1] row_mask:0xf bank_mask:0xf
	s_waitcnt lgkmcnt(0)
	v_add_f32_e32 v2, v3, v2
	s_nop 1
	v_mov_b32_dpp v3, v2 row_shl:4 row_mask:0xf bank_mask:0x5
	v_mov_b32_dpp v3, v2 row_shr:4 row_mask:0xf bank_mask:0xa
	s_and_saveexec_b64 s[0:1], vcc
	s_cbranch_execz .LBB0_837
	v_mov_b32_e32 v121, v115
	s_waitcnt lgkmcnt(0)
	v_add_f32_e32 v4, v2, v3
	v_lshl_add_u64 v[2:3], v[122:123], 0, v[120:121]
	global_store_dword v[2:3], v4, off offset:452
.LBB0_837:
	s_or_b64 exec, exec, s[0:1]
	v_max_f32_e32 v2, v12, v12
	v_max_f32_e32 v2, 0, v2
	s_waitcnt lgkmcnt(0)
	v_mul_f32_e32 v3, v138, v2
	s_nop 1
	v_mov_b32_dpp v3, v3 quad_perm:[1,0,3,2] row_mask:0xf bank_mask:0xf
	s_waitcnt lgkmcnt(0)
	v_fmac_f32_e32 v3, v138, v2
	s_nop 1
	v_mov_b32_dpp v2, v3 quad_perm:[2,3,0,1] row_mask:0xf bank_mask:0xf
	s_waitcnt lgkmcnt(0)
	v_add_f32_e32 v2, v3, v2
	s_nop 1
	v_mov_b32_dpp v3, v2 row_shl:4 row_mask:0xf bank_mask:0x5
	v_mov_b32_dpp v3, v2 row_shr:4 row_mask:0xf bank_mask:0xa
	s_and_saveexec_b64 s[0:1], vcc
	s_cbranch_execz .LBB0_839
	v_mov_b32_e32 v121, v115
	s_waitcnt lgkmcnt(0)
	v_add_f32_e32 v4, v2, v3
	v_lshl_add_u64 v[2:3], v[122:123], 0, v[120:121]
	global_store_dword v[2:3], v4, off offset:456
.LBB0_839:
	s_or_b64 exec, exec, s[0:1]
	v_max_f32_e32 v2, v13, v13
	v_max_f32_e32 v2, 0, v2
	s_waitcnt lgkmcnt(0)
	v_mul_f32_e32 v3, v138, v2
	s_nop 1
	v_mov_b32_dpp v3, v3 quad_perm:[1,0,3,2] row_mask:0xf bank_mask:0xf
	s_waitcnt lgkmcnt(0)
	v_fmac_f32_e32 v3, v138, v2
	s_nop 1
	v_mov_b32_dpp v2, v3 quad_perm:[2,3,0,1] row_mask:0xf bank_mask:0xf
	s_waitcnt lgkmcnt(0)
	v_add_f32_e32 v2, v3, v2
	s_nop 1
	v_mov_b32_dpp v3, v2 row_shl:4 row_mask:0xf bank_mask:0x5
	v_mov_b32_dpp v3, v2 row_shr:4 row_mask:0xf bank_mask:0xa
	s_and_saveexec_b64 s[0:1], vcc
	s_cbranch_execz .LBB0_841
	v_mov_b32_e32 v121, v115
	s_waitcnt lgkmcnt(0)
	v_add_f32_e32 v4, v2, v3
	v_lshl_add_u64 v[2:3], v[122:123], 0, v[120:121]
	global_store_dword v[2:3], v4, off offset:460
.LBB0_841:
	s_or_b64 exec, exec, s[0:1]
	v_max_f32_e32 v2, v14, v14
	v_max_f32_e32 v2, 0, v2
	s_waitcnt lgkmcnt(0)
	v_mul_f32_e32 v3, v138, v2
	s_nop 1
	v_mov_b32_dpp v3, v3 quad_perm:[1,0,3,2] row_mask:0xf bank_mask:0xf
	s_waitcnt lgkmcnt(0)
	v_fmac_f32_e32 v3, v138, v2
	s_nop 1
	v_mov_b32_dpp v2, v3 quad_perm:[2,3,0,1] row_mask:0xf bank_mask:0xf
	s_waitcnt lgkmcnt(0)
	v_add_f32_e32 v2, v3, v2
	s_nop 1
	v_mov_b32_dpp v3, v2 row_shl:4 row_mask:0xf bank_mask:0x5
	v_mov_b32_dpp v3, v2 row_shr:4 row_mask:0xf bank_mask:0xa
	s_and_saveexec_b64 s[0:1], vcc
	s_cbranch_execz .LBB0_843
	v_mov_b32_e32 v121, v115
	s_waitcnt lgkmcnt(0)
	v_add_f32_e32 v4, v2, v3
	v_lshl_add_u64 v[2:3], v[122:123], 0, v[120:121]
	global_store_dword v[2:3], v4, off offset:480
.LBB0_843:
	s_or_b64 exec, exec, s[0:1]
	v_max_f32_e32 v2, v15, v15
	v_max_f32_e32 v2, 0, v2
	s_waitcnt lgkmcnt(0)
	v_mul_f32_e32 v3, v138, v2
	s_nop 1
	v_mov_b32_dpp v3, v3 quad_perm:[1,0,3,2] row_mask:0xf bank_mask:0xf
	s_waitcnt lgkmcnt(0)
	v_fmac_f32_e32 v3, v138, v2
	s_nop 1
	v_mov_b32_dpp v2, v3 quad_perm:[2,3,0,1] row_mask:0xf bank_mask:0xf
	s_waitcnt lgkmcnt(0)
	v_add_f32_e32 v2, v3, v2
	s_nop 1
	v_mov_b32_dpp v3, v2 row_shl:4 row_mask:0xf bank_mask:0x5
	v_mov_b32_dpp v3, v2 row_shr:4 row_mask:0xf bank_mask:0xa
	s_and_saveexec_b64 s[0:1], vcc
	s_cbranch_execz .LBB0_845
	v_mov_b32_e32 v121, v115
	s_waitcnt lgkmcnt(0)
	v_add_f32_e32 v4, v2, v3
	v_lshl_add_u64 v[2:3], v[122:123], 0, v[120:121]
	global_store_dword v[2:3], v4, off offset:484
.LBB0_845:
	s_or_b64 exec, exec, s[0:1]
	v_max_f32_e32 v2, v16, v16
	v_max_f32_e32 v2, 0, v2
	s_waitcnt lgkmcnt(0)
	v_mul_f32_e32 v3, v138, v2
	s_nop 1
	v_mov_b32_dpp v3, v3 quad_perm:[1,0,3,2] row_mask:0xf bank_mask:0xf
	s_waitcnt lgkmcnt(0)
	v_fmac_f32_e32 v3, v138, v2
	s_nop 1
	v_mov_b32_dpp v2, v3 quad_perm:[2,3,0,1] row_mask:0xf bank_mask:0xf
	s_waitcnt lgkmcnt(0)
	v_add_f32_e32 v2, v3, v2
	s_nop 1
	v_mov_b32_dpp v3, v2 row_shl:4 row_mask:0xf bank_mask:0x5
	v_mov_b32_dpp v3, v2 row_shr:4 row_mask:0xf bank_mask:0xa
	s_and_saveexec_b64 s[0:1], vcc
	s_cbranch_execz .LBB0_847
	v_mov_b32_e32 v121, v115
	s_waitcnt lgkmcnt(0)
	v_add_f32_e32 v4, v2, v3
	v_lshl_add_u64 v[2:3], v[122:123], 0, v[120:121]
	global_store_dword v[2:3], v4, off offset:488
.LBB0_847:
	s_or_b64 exec, exec, s[0:1]
	v_max_f32_e32 v2, v17, v17
	v_max_f32_e32 v2, 0, v2
	s_waitcnt lgkmcnt(0)
	v_mul_f32_e32 v3, v138, v2
	s_nop 1
	v_mov_b32_dpp v3, v3 quad_perm:[1,0,3,2] row_mask:0xf bank_mask:0xf
	s_waitcnt lgkmcnt(0)
	v_fmac_f32_e32 v3, v138, v2
	s_nop 1
	v_mov_b32_dpp v2, v3 quad_perm:[2,3,0,1] row_mask:0xf bank_mask:0xf
	s_waitcnt lgkmcnt(0)
	v_add_f32_e32 v2, v3, v2
	s_nop 1
	v_mov_b32_dpp v3, v2 row_shl:4 row_mask:0xf bank_mask:0x5
	v_mov_b32_dpp v3, v2 row_shr:4 row_mask:0xf bank_mask:0xa
	s_and_saveexec_b64 s[0:1], vcc
	s_cbranch_execz .LBB0_849
	v_mov_b32_e32 v121, v115
	s_waitcnt lgkmcnt(0)
	v_add_f32_e32 v4, v2, v3
	v_lshl_add_u64 v[2:3], v[122:123], 0, v[120:121]
	global_store_dword v[2:3], v4, off offset:492
.LBB0_849:
	s_or_b64 exec, exec, s[0:1]
	v_readlane_b32 s36, v253, 32
	s_waitcnt lgkmcnt(0)
	v_lshlrev_b64 v[2:3], 15, v[124:125]
	v_readlane_b32 s44, v253, 40
	v_readlane_b32 s45, v253, 41
	v_mov_b32_e32 v129, v115
	v_mov_b32_e32 v127, v115
	v_lshl_add_u64 v[2:3], s[44:45], 0, v[2:3]
	v_lshl_add_u64 v[2:3], v[2:3], 0, v[128:129]
	v_lshl_add_u64 v[2:3], v[2:3], 0, v[126:127]
	global_load_dwordx4 v[42:45], v[2:3], off offset:16
	global_load_dwordx4 v[34:37], v[2:3], off
	global_load_dwordx4 v[66:69], v[2:3], off offset:80
	global_load_dwordx4 v[50:53], v[2:3], off offset:64
	global_load_dwordx4 v[82:85], v[2:3], off offset:144
	global_load_dwordx4 v[74:77], v[2:3], off offset:128
	global_load_dwordx4 v[98:101], v[2:3], off offset:208
	global_load_dwordx4 v[86:89], v[2:3], off offset:192
	s_waitcnt vmcnt(15)
	v_cvt_f16_f32_e32 v5, v49
	s_waitcnt vmcnt(14)
	v_cvt_f16_f32_e32 v2, v38
	v_cvt_pk_f16_f32 v6, v47, v48
	v_cvt_pk_f16_f32 v4, v41, v46
	v_cvt_pk_f16_f32 v3, v39, v40
	v_pack_b32_f16 v2, v2, v3
	v_alignbit_b32 v3, v4, v3, 16
	v_alignbit_b32 v4, v6, v4, 16
	v_alignbit_b32 v5, v5, v6, 16
	s_waitcnt vmcnt(13)
	v_cvt_f16_f32_e32 v65, v65
	s_waitcnt vmcnt(12)
	v_cvt_f16_f32_e32 v58, v58
	v_mfma_f32_32x32x16_f16 v[2:17], v[2:5], v[30:33], 0
	v_cvt_pk_f16_f32 v63, v63, v64
	v_cvt_pk_f16_f32 v61, v61, v62
	v_cvt_pk_f16_f32 v59, v59, v60
	v_pack_b32_f16 v38, v58, v59
	v_alignbit_b32 v39, v61, v59, 16
	v_alignbit_b32 v40, v63, v61, 16
	v_alignbit_b32 v41, v65, v63, 16
	s_waitcnt vmcnt(11)
	v_cvt_f16_f32_e32 v81, v81
	s_waitcnt vmcnt(10)
	v_cvt_f16_f32_e32 v70, v70
	v_mfma_f32_32x32x16_f16 v[2:17], v[38:41], v[26:29], v[2:17]
	v_cvt_pk_f16_f32 v79, v79, v80
	v_cvt_pk_f16_f32 v73, v73, v78
	v_cvt_pk_f16_f32 v71, v71, v72
	v_pack_b32_f16 v38, v70, v71
	v_alignbit_b32 v39, v73, v71, 16
	v_alignbit_b32 v40, v79, v73, 16
	v_alignbit_b32 v41, v81, v79, 16
	s_waitcnt vmcnt(9)
	v_cvt_f16_f32_e32 v54, v97
	s_waitcnt vmcnt(8)
	v_cvt_f16_f32_e32 v90, v90
	v_mfma_f32_32x32x16_f16 v[2:17], v[38:41], v[22:25], v[2:17]
	v_cvt_pk_f16_f32 v55, v95, v96
	v_cvt_pk_f16_f32 v56, v93, v94
	v_cvt_pk_f16_f32 v57, v91, v92
	v_pack_b32_f16 v38, v90, v57
	v_alignbit_b32 v39, v56, v57, 16
	v_alignbit_b32 v40, v55, v56, 16
	v_alignbit_b32 v41, v54, v55, 16
	v_readlane_b32 s37, v253, 33
	v_readlane_b32 s38, v253, 34
	v_mfma_f32_32x32x16_f16 v[2:17], v[38:41], v[18:21], v[2:17]
	v_readlane_b32 s39, v253, 35
	v_readlane_b32 s40, v253, 36
	v_readlane_b32 s41, v253, 37
	v_readlane_b32 s42, v253, 38
	v_readlane_b32 s43, v253, 39
	v_readlane_b32 s46, v253, 42
	v_readlane_b32 s47, v253, 43
	s_nop 4
	v_max_f32_e32 v2, v2, v2
	v_max_f32_e32 v2, 0, v2
	v_mul_f32_e32 v38, v138, v2
	s_nop 1
	v_mov_b32_dpp v38, v38 quad_perm:[1,0,3,2] row_mask:0xf bank_mask:0xf
	v_readlane_b32 s48, v253, 44
	v_readlane_b32 s49, v253, 45
	v_readlane_b32 s50, v253, 46
	v_readlane_b32 s51, v253, 47
	s_waitcnt lgkmcnt(0)
	v_fmac_f32_e32 v38, v138, v2
	s_nop 1
	v_mov_b32_dpp v2, v38 quad_perm:[2,3,0,1] row_mask:0xf bank_mask:0xf
	s_waitcnt lgkmcnt(0)
	v_add_f32_e32 v2, v38, v2
	s_nop 1
	v_mov_b32_dpp v38, v2 row_shl:4 row_mask:0xf bank_mask:0x5
	v_mov_b32_dpp v38, v2 row_shr:4 row_mask:0xf bank_mask:0xa
	s_and_saveexec_b64 s[0:1], vcc
	s_cbranch_execz .LBB0_851
	v_mov_b32_e32 v121, v115
	s_waitcnt lgkmcnt(0)
	v_add_f32_e32 v2, v2, v38
	v_lshl_add_u64 v[38:39], v[122:123], 0, v[120:121]
	global_store_dword v[38:39], v2, off offset:512
.LBB0_851:
	s_or_b64 exec, exec, s[0:1]
	v_max_f32_e32 v2, v3, v3
	v_max_f32_e32 v2, 0, v2
	v_mul_f32_e32 v3, v138, v2
	s_nop 1
	v_mov_b32_dpp v3, v3 quad_perm:[1,0,3,2] row_mask:0xf bank_mask:0xf
	s_waitcnt lgkmcnt(0)
	v_fmac_f32_e32 v3, v138, v2
	s_nop 1
	v_mov_b32_dpp v2, v3 quad_perm:[2,3,0,1] row_mask:0xf bank_mask:0xf
	s_waitcnt lgkmcnt(0)
	v_add_f32_e32 v2, v3, v2
	s_nop 1
	v_mov_b32_dpp v3, v2 row_shl:4 row_mask:0xf bank_mask:0x5
	v_mov_b32_dpp v3, v2 row_shr:4 row_mask:0xf bank_mask:0xa
	s_and_saveexec_b64 s[0:1], vcc
	s_cbranch_execz .LBB0_853
	v_mov_b32_e32 v121, v115
	s_waitcnt lgkmcnt(0)
	v_add_f32_e32 v38, v2, v3
	v_lshl_add_u64 v[2:3], v[122:123], 0, v[120:121]
	global_store_dword v[2:3], v38, off offset:516
.LBB0_853:
	s_or_b64 exec, exec, s[0:1]
	v_max_f32_e32 v2, v4, v4
	v_max_f32_e32 v2, 0, v2
	s_waitcnt lgkmcnt(0)
	v_mul_f32_e32 v3, v138, v2
	s_nop 1
	v_mov_b32_dpp v3, v3 quad_perm:[1,0,3,2] row_mask:0xf bank_mask:0xf
	s_waitcnt lgkmcnt(0)
	v_fmac_f32_e32 v3, v138, v2
	s_nop 1
	v_mov_b32_dpp v2, v3 quad_perm:[2,3,0,1] row_mask:0xf bank_mask:0xf
	s_waitcnt lgkmcnt(0)
	v_add_f32_e32 v2, v3, v2
	s_nop 1
	v_mov_b32_dpp v3, v2 row_shl:4 row_mask:0xf bank_mask:0x5
	v_mov_b32_dpp v3, v2 row_shr:4 row_mask:0xf bank_mask:0xa
	s_and_saveexec_b64 s[0:1], vcc
	s_cbranch_execz .LBB0_855
	v_mov_b32_e32 v121, v115
	s_waitcnt lgkmcnt(0)
	v_add_f32_e32 v4, v2, v3
	v_lshl_add_u64 v[2:3], v[122:123], 0, v[120:121]
	global_store_dword v[2:3], v4, off offset:520
.LBB0_855:
	s_or_b64 exec, exec, s[0:1]
	v_max_f32_e32 v2, v5, v5
	v_max_f32_e32 v2, 0, v2
	s_waitcnt lgkmcnt(0)
	v_mul_f32_e32 v3, v138, v2
	s_nop 1
	v_mov_b32_dpp v3, v3 quad_perm:[1,0,3,2] row_mask:0xf bank_mask:0xf
	s_waitcnt lgkmcnt(0)
	v_fmac_f32_e32 v3, v138, v2
	s_nop 1
	v_mov_b32_dpp v2, v3 quad_perm:[2,3,0,1] row_mask:0xf bank_mask:0xf
	s_waitcnt lgkmcnt(0)
	v_add_f32_e32 v2, v3, v2
	s_nop 1
	v_mov_b32_dpp v3, v2 row_shl:4 row_mask:0xf bank_mask:0x5
	v_mov_b32_dpp v3, v2 row_shr:4 row_mask:0xf bank_mask:0xa
	s_and_saveexec_b64 s[0:1], vcc
	s_cbranch_execz .LBB0_857
	v_mov_b32_e32 v121, v115
	s_waitcnt lgkmcnt(0)
	v_add_f32_e32 v4, v2, v3
	v_lshl_add_u64 v[2:3], v[122:123], 0, v[120:121]
	global_store_dword v[2:3], v4, off offset:524
.LBB0_857:
	s_or_b64 exec, exec, s[0:1]
	v_max_f32_e32 v2, v6, v6
	v_max_f32_e32 v2, 0, v2
	s_waitcnt lgkmcnt(0)
	v_mul_f32_e32 v3, v138, v2
	s_nop 1
	v_mov_b32_dpp v3, v3 quad_perm:[1,0,3,2] row_mask:0xf bank_mask:0xf
	s_waitcnt lgkmcnt(0)
	v_fmac_f32_e32 v3, v138, v2
	s_nop 1
	v_mov_b32_dpp v2, v3 quad_perm:[2,3,0,1] row_mask:0xf bank_mask:0xf
	s_waitcnt lgkmcnt(0)
	v_add_f32_e32 v2, v3, v2
	s_nop 1
	v_mov_b32_dpp v3, v2 row_shl:4 row_mask:0xf bank_mask:0x5
	v_mov_b32_dpp v3, v2 row_shr:4 row_mask:0xf bank_mask:0xa
	s_and_saveexec_b64 s[0:1], vcc
	s_cbranch_execz .LBB0_859
	v_mov_b32_e32 v121, v115
	s_waitcnt lgkmcnt(0)
	v_add_f32_e32 v4, v2, v3
	v_lshl_add_u64 v[2:3], v[122:123], 0, v[120:121]
	global_store_dword v[2:3], v4, off offset:544
.LBB0_859:
	s_or_b64 exec, exec, s[0:1]
	v_max_f32_e32 v2, v7, v7
	v_max_f32_e32 v2, 0, v2
	s_waitcnt lgkmcnt(0)
	v_mul_f32_e32 v3, v138, v2
	s_nop 1
	v_mov_b32_dpp v3, v3 quad_perm:[1,0,3,2] row_mask:0xf bank_mask:0xf
	s_waitcnt lgkmcnt(0)
	v_fmac_f32_e32 v3, v138, v2
	s_nop 1
	v_mov_b32_dpp v2, v3 quad_perm:[2,3,0,1] row_mask:0xf bank_mask:0xf
	s_waitcnt lgkmcnt(0)
	v_add_f32_e32 v2, v3, v2
	s_nop 1
	v_mov_b32_dpp v3, v2 row_shl:4 row_mask:0xf bank_mask:0x5
	v_mov_b32_dpp v3, v2 row_shr:4 row_mask:0xf bank_mask:0xa
	s_and_saveexec_b64 s[0:1], vcc
	s_cbranch_execz .LBB0_861
	v_mov_b32_e32 v121, v115
	s_waitcnt lgkmcnt(0)
	v_add_f32_e32 v4, v2, v3
	v_lshl_add_u64 v[2:3], v[122:123], 0, v[120:121]
	global_store_dword v[2:3], v4, off offset:548
.LBB0_861:
	s_or_b64 exec, exec, s[0:1]
	v_max_f32_e32 v2, v8, v8
	v_max_f32_e32 v2, 0, v2
	s_waitcnt lgkmcnt(0)
	v_mul_f32_e32 v3, v138, v2
	s_nop 1
	v_mov_b32_dpp v3, v3 quad_perm:[1,0,3,2] row_mask:0xf bank_mask:0xf
	s_waitcnt lgkmcnt(0)
	v_fmac_f32_e32 v3, v138, v2
	s_nop 1
	v_mov_b32_dpp v2, v3 quad_perm:[2,3,0,1] row_mask:0xf bank_mask:0xf
	s_waitcnt lgkmcnt(0)
	v_add_f32_e32 v2, v3, v2
	s_nop 1
	v_mov_b32_dpp v3, v2 row_shl:4 row_mask:0xf bank_mask:0x5
	v_mov_b32_dpp v3, v2 row_shr:4 row_mask:0xf bank_mask:0xa
	s_and_saveexec_b64 s[0:1], vcc
	s_cbranch_execz .LBB0_863
	v_mov_b32_e32 v121, v115
	s_waitcnt lgkmcnt(0)
	v_add_f32_e32 v4, v2, v3
	v_lshl_add_u64 v[2:3], v[122:123], 0, v[120:121]
	global_store_dword v[2:3], v4, off offset:552
.LBB0_863:
	s_or_b64 exec, exec, s[0:1]
	v_max_f32_e32 v2, v9, v9
	v_max_f32_e32 v2, 0, v2
	s_waitcnt lgkmcnt(0)
	v_mul_f32_e32 v3, v138, v2
	s_nop 1
	v_mov_b32_dpp v3, v3 quad_perm:[1,0,3,2] row_mask:0xf bank_mask:0xf
	s_waitcnt lgkmcnt(0)
	v_fmac_f32_e32 v3, v138, v2
	s_nop 1
	v_mov_b32_dpp v2, v3 quad_perm:[2,3,0,1] row_mask:0xf bank_mask:0xf
	s_waitcnt lgkmcnt(0)
	v_add_f32_e32 v2, v3, v2
	s_nop 1
	v_mov_b32_dpp v3, v2 row_shl:4 row_mask:0xf bank_mask:0x5
	v_mov_b32_dpp v3, v2 row_shr:4 row_mask:0xf bank_mask:0xa
	s_and_saveexec_b64 s[0:1], vcc
	s_cbranch_execz .LBB0_865
	v_mov_b32_e32 v121, v115
	s_waitcnt lgkmcnt(0)
	v_add_f32_e32 v4, v2, v3
	v_lshl_add_u64 v[2:3], v[122:123], 0, v[120:121]
	global_store_dword v[2:3], v4, off offset:556
.LBB0_865:
	s_or_b64 exec, exec, s[0:1]
	v_max_f32_e32 v2, v10, v10
	v_max_f32_e32 v2, 0, v2
	s_waitcnt lgkmcnt(0)
	v_mul_f32_e32 v3, v138, v2
	s_nop 1
	v_mov_b32_dpp v3, v3 quad_perm:[1,0,3,2] row_mask:0xf bank_mask:0xf
	s_waitcnt lgkmcnt(0)
	v_fmac_f32_e32 v3, v138, v2
	s_nop 1
	v_mov_b32_dpp v2, v3 quad_perm:[2,3,0,1] row_mask:0xf bank_mask:0xf
	s_waitcnt lgkmcnt(0)
	v_add_f32_e32 v2, v3, v2
	s_nop 1
	v_mov_b32_dpp v3, v2 row_shl:4 row_mask:0xf bank_mask:0x5
	v_mov_b32_dpp v3, v2 row_shr:4 row_mask:0xf bank_mask:0xa
	s_and_saveexec_b64 s[0:1], vcc
	s_cbranch_execz .LBB0_867
	v_mov_b32_e32 v121, v115
	s_waitcnt lgkmcnt(0)
	v_add_f32_e32 v4, v2, v3
	v_lshl_add_u64 v[2:3], v[122:123], 0, v[120:121]
	global_store_dword v[2:3], v4, off offset:576
.LBB0_867:
	s_or_b64 exec, exec, s[0:1]
	v_max_f32_e32 v2, v11, v11
	v_max_f32_e32 v2, 0, v2
	s_waitcnt lgkmcnt(0)
	v_mul_f32_e32 v3, v138, v2
	s_nop 1
	v_mov_b32_dpp v3, v3 quad_perm:[1,0,3,2] row_mask:0xf bank_mask:0xf
	s_waitcnt lgkmcnt(0)
	v_fmac_f32_e32 v3, v138, v2
	s_nop 1
	v_mov_b32_dpp v2, v3 quad_perm:[2,3,0,1] row_mask:0xf bank_mask:0xf
	s_waitcnt lgkmcnt(0)
	v_add_f32_e32 v2, v3, v2
	s_nop 1
	v_mov_b32_dpp v3, v2 row_shl:4 row_mask:0xf bank_mask:0x5
	v_mov_b32_dpp v3, v2 row_shr:4 row_mask:0xf bank_mask:0xa
	s_and_saveexec_b64 s[0:1], vcc
	s_cbranch_execz .LBB0_869
	v_mov_b32_e32 v121, v115
	s_waitcnt lgkmcnt(0)
	v_add_f32_e32 v4, v2, v3
	v_lshl_add_u64 v[2:3], v[122:123], 0, v[120:121]
	global_store_dword v[2:3], v4, off offset:580
.LBB0_869:
	s_or_b64 exec, exec, s[0:1]
	v_max_f32_e32 v2, v12, v12
	v_max_f32_e32 v2, 0, v2
	s_waitcnt lgkmcnt(0)
	v_mul_f32_e32 v3, v138, v2
	s_nop 1
	v_mov_b32_dpp v3, v3 quad_perm:[1,0,3,2] row_mask:0xf bank_mask:0xf
	s_waitcnt lgkmcnt(0)
	v_fmac_f32_e32 v3, v138, v2
	s_nop 1
	v_mov_b32_dpp v2, v3 quad_perm:[2,3,0,1] row_mask:0xf bank_mask:0xf
	s_waitcnt lgkmcnt(0)
	v_add_f32_e32 v2, v3, v2
	s_nop 1
	v_mov_b32_dpp v3, v2 row_shl:4 row_mask:0xf bank_mask:0x5
	v_mov_b32_dpp v3, v2 row_shr:4 row_mask:0xf bank_mask:0xa
	s_and_saveexec_b64 s[0:1], vcc
	s_cbranch_execz .LBB0_871
	v_mov_b32_e32 v121, v115
	s_waitcnt lgkmcnt(0)
	v_add_f32_e32 v4, v2, v3
	v_lshl_add_u64 v[2:3], v[122:123], 0, v[120:121]
	global_store_dword v[2:3], v4, off offset:584
.LBB0_871:
	s_or_b64 exec, exec, s[0:1]
	v_max_f32_e32 v2, v13, v13
	v_max_f32_e32 v2, 0, v2
	s_waitcnt lgkmcnt(0)
	v_mul_f32_e32 v3, v138, v2
	s_nop 1
	v_mov_b32_dpp v3, v3 quad_perm:[1,0,3,2] row_mask:0xf bank_mask:0xf
	s_waitcnt lgkmcnt(0)
	v_fmac_f32_e32 v3, v138, v2
	s_nop 1
	v_mov_b32_dpp v2, v3 quad_perm:[2,3,0,1] row_mask:0xf bank_mask:0xf
	s_waitcnt lgkmcnt(0)
	v_add_f32_e32 v2, v3, v2
	s_nop 1
	v_mov_b32_dpp v3, v2 row_shl:4 row_mask:0xf bank_mask:0x5
	v_mov_b32_dpp v3, v2 row_shr:4 row_mask:0xf bank_mask:0xa
	s_and_saveexec_b64 s[0:1], vcc
	s_cbranch_execz .LBB0_873
	v_mov_b32_e32 v121, v115
	s_waitcnt lgkmcnt(0)
	v_add_f32_e32 v4, v2, v3
	v_lshl_add_u64 v[2:3], v[122:123], 0, v[120:121]
	global_store_dword v[2:3], v4, off offset:588
.LBB0_873:
	s_or_b64 exec, exec, s[0:1]
	v_max_f32_e32 v2, v14, v14
	v_max_f32_e32 v2, 0, v2
	s_waitcnt lgkmcnt(0)
	v_mul_f32_e32 v3, v138, v2
	s_nop 1
	v_mov_b32_dpp v3, v3 quad_perm:[1,0,3,2] row_mask:0xf bank_mask:0xf
	s_waitcnt lgkmcnt(0)
	v_fmac_f32_e32 v3, v138, v2
	s_nop 1
	v_mov_b32_dpp v2, v3 quad_perm:[2,3,0,1] row_mask:0xf bank_mask:0xf
	s_waitcnt lgkmcnt(0)
	v_add_f32_e32 v2, v3, v2
	s_nop 1
	v_mov_b32_dpp v3, v2 row_shl:4 row_mask:0xf bank_mask:0x5
	v_mov_b32_dpp v3, v2 row_shr:4 row_mask:0xf bank_mask:0xa
	s_and_saveexec_b64 s[0:1], vcc
	s_cbranch_execz .LBB0_875
	v_mov_b32_e32 v121, v115
	s_waitcnt lgkmcnt(0)
	v_add_f32_e32 v4, v2, v3
	v_lshl_add_u64 v[2:3], v[122:123], 0, v[120:121]
	global_store_dword v[2:3], v4, off offset:608
.LBB0_875:
	s_or_b64 exec, exec, s[0:1]
	v_max_f32_e32 v2, v15, v15
	v_max_f32_e32 v2, 0, v2
	s_waitcnt lgkmcnt(0)
	v_mul_f32_e32 v3, v138, v2
	s_nop 1
	v_mov_b32_dpp v3, v3 quad_perm:[1,0,3,2] row_mask:0xf bank_mask:0xf
	s_waitcnt lgkmcnt(0)
	v_fmac_f32_e32 v3, v138, v2
	s_nop 1
	v_mov_b32_dpp v2, v3 quad_perm:[2,3,0,1] row_mask:0xf bank_mask:0xf
	s_waitcnt lgkmcnt(0)
	v_add_f32_e32 v2, v3, v2
	s_nop 1
	v_mov_b32_dpp v3, v2 row_shl:4 row_mask:0xf bank_mask:0x5
	v_mov_b32_dpp v3, v2 row_shr:4 row_mask:0xf bank_mask:0xa
	s_and_saveexec_b64 s[0:1], vcc
	s_cbranch_execz .LBB0_877
	v_mov_b32_e32 v121, v115
	s_waitcnt lgkmcnt(0)
	v_add_f32_e32 v4, v2, v3
	v_lshl_add_u64 v[2:3], v[122:123], 0, v[120:121]
	global_store_dword v[2:3], v4, off offset:612
.LBB0_877:
	s_or_b64 exec, exec, s[0:1]
	v_max_f32_e32 v2, v16, v16
	v_max_f32_e32 v2, 0, v2
	s_waitcnt lgkmcnt(0)
	v_mul_f32_e32 v3, v138, v2
	s_nop 1
	v_mov_b32_dpp v3, v3 quad_perm:[1,0,3,2] row_mask:0xf bank_mask:0xf
	s_waitcnt lgkmcnt(0)
	v_fmac_f32_e32 v3, v138, v2
	s_nop 1
	v_mov_b32_dpp v2, v3 quad_perm:[2,3,0,1] row_mask:0xf bank_mask:0xf
	s_waitcnt lgkmcnt(0)
	v_add_f32_e32 v2, v3, v2
	s_nop 1
	v_mov_b32_dpp v3, v2 row_shl:4 row_mask:0xf bank_mask:0x5
	v_mov_b32_dpp v3, v2 row_shr:4 row_mask:0xf bank_mask:0xa
	s_and_saveexec_b64 s[0:1], vcc
	s_cbranch_execz .LBB0_879
	v_mov_b32_e32 v121, v115
	s_waitcnt lgkmcnt(0)
	v_add_f32_e32 v4, v2, v3
	v_lshl_add_u64 v[2:3], v[122:123], 0, v[120:121]
	global_store_dword v[2:3], v4, off offset:616
.LBB0_879:
	s_or_b64 exec, exec, s[0:1]
	v_max_f32_e32 v2, v17, v17
	v_max_f32_e32 v2, 0, v2
	s_waitcnt lgkmcnt(0)
	v_mul_f32_e32 v3, v138, v2
	s_nop 1
	v_mov_b32_dpp v3, v3 quad_perm:[1,0,3,2] row_mask:0xf bank_mask:0xf
	s_waitcnt lgkmcnt(0)
	v_fmac_f32_e32 v3, v138, v2
	s_nop 1
	v_mov_b32_dpp v2, v3 quad_perm:[2,3,0,1] row_mask:0xf bank_mask:0xf
	s_waitcnt lgkmcnt(0)
	v_add_f32_e32 v2, v3, v2
	s_nop 1
	v_mov_b32_dpp v3, v2 row_shl:4 row_mask:0xf bank_mask:0x5
	v_mov_b32_dpp v3, v2 row_shr:4 row_mask:0xf bank_mask:0xa
	s_and_saveexec_b64 s[0:1], vcc
	s_cbranch_execz .LBB0_881
	v_mov_b32_e32 v121, v115
	s_waitcnt lgkmcnt(0)
	v_add_f32_e32 v4, v2, v3
	v_lshl_add_u64 v[2:3], v[122:123], 0, v[120:121]
	global_store_dword v[2:3], v4, off offset:620
.LBB0_881:
	s_or_b64 exec, exec, s[0:1]
	v_readlane_b32 s36, v253, 32
	s_waitcnt lgkmcnt(0)
	v_lshlrev_b64 v[2:3], 15, v[124:125]
	v_readlane_b32 s44, v253, 40
	v_readlane_b32 s45, v253, 41
	v_mov_b32_e32 v127, v115
	s_waitcnt vmcnt(7)
	v_cvt_f16_f32_e32 v5, v45
	v_lshl_add_u64 v[2:3], s[44:45], 0, v[2:3]
	v_lshl_add_u64 v[2:3], v[2:3], 0, v[114:115]
	v_lshl_add_u64 v[2:3], v[2:3], 0, v[126:127]
	global_load_dwordx4 v[46:49], v[2:3], off offset:16
	global_load_dwordx4 v[38:41], v[2:3], off
	global_load_dwordx4 v[58:61], v[2:3], off offset:80
	global_load_dwordx4 v[54:57], v[2:3], off offset:64
	global_load_dwordx4 v[70:73], v[2:3], off offset:144
	global_load_dwordx4 v[62:65], v[2:3], off offset:128
	global_load_dwordx4 v[90:93], v[2:3], off offset:208
	global_load_dwordx4 v[78:81], v[2:3], off offset:192
	s_waitcnt vmcnt(14)
	v_cvt_f16_f32_e32 v2, v34
	v_cvt_pk_f16_f32 v6, v43, v44
	v_cvt_pk_f16_f32 v4, v37, v42
	v_cvt_pk_f16_f32 v3, v35, v36
	v_pack_b32_f16 v2, v2, v3
	v_alignbit_b32 v3, v4, v3, 16
	v_alignbit_b32 v4, v6, v4, 16
	v_alignbit_b32 v5, v5, v6, 16
	s_waitcnt vmcnt(13)
	v_cvt_f16_f32_e32 v69, v69
	s_waitcnt vmcnt(12)
	v_cvt_f16_f32_e32 v50, v50
	v_mfma_f32_32x32x16_f16 v[2:17], v[2:5], v[30:33], 0
	v_cvt_pk_f16_f32 v67, v67, v68
	v_cvt_pk_f16_f32 v53, v53, v66
	v_cvt_pk_f16_f32 v51, v51, v52
	v_pack_b32_f16 v34, v50, v51
	v_alignbit_b32 v35, v53, v51, 16
	v_alignbit_b32 v36, v67, v53, 16
	v_alignbit_b32 v37, v69, v67, 16
	s_waitcnt vmcnt(11)
	v_cvt_f16_f32_e32 v85, v85
	s_waitcnt vmcnt(10)
	v_cvt_f16_f32_e32 v74, v74
	v_mfma_f32_32x32x16_f16 v[2:17], v[34:37], v[26:29], v[2:17]
	v_cvt_pk_f16_f32 v83, v83, v84
	v_cvt_pk_f16_f32 v77, v77, v82
	v_cvt_pk_f16_f32 v75, v75, v76
	v_pack_b32_f16 v34, v74, v75
	v_alignbit_b32 v35, v77, v75, 16
	v_alignbit_b32 v36, v83, v77, 16
	v_alignbit_b32 v37, v85, v83, 16
	s_waitcnt vmcnt(9)
	v_cvt_f16_f32_e32 v94, v101
	s_waitcnt vmcnt(8)
	v_cvt_f16_f32_e32 v86, v86
	v_mfma_f32_32x32x16_f16 v[2:17], v[34:37], v[22:25], v[2:17]
	v_cvt_pk_f16_f32 v95, v99, v100
	v_cvt_pk_f16_f32 v89, v89, v98
	v_cvt_pk_f16_f32 v87, v87, v88
	v_pack_b32_f16 v34, v86, v87
	v_alignbit_b32 v35, v89, v87, 16
	v_alignbit_b32 v36, v95, v89, 16
	v_alignbit_b32 v37, v94, v95, 16
	v_readlane_b32 s37, v253, 33
	v_readlane_b32 s38, v253, 34
	v_mfma_f32_32x32x16_f16 v[2:17], v[34:37], v[18:21], v[2:17]
	v_readlane_b32 s39, v253, 35
	v_readlane_b32 s40, v253, 36
	v_readlane_b32 s41, v253, 37
	v_readlane_b32 s42, v253, 38
	v_readlane_b32 s43, v253, 39
	v_readlane_b32 s46, v253, 42
	v_readlane_b32 s47, v253, 43
	s_nop 4
	v_max_f32_e32 v2, v2, v2
	v_max_f32_e32 v2, 0, v2
	v_mul_f32_e32 v34, v138, v2
	s_nop 1
	v_mov_b32_dpp v34, v34 quad_perm:[1,0,3,2] row_mask:0xf bank_mask:0xf
	v_readlane_b32 s48, v253, 44
	v_readlane_b32 s49, v253, 45
	v_readlane_b32 s50, v253, 46
	v_readlane_b32 s51, v253, 47
	s_waitcnt lgkmcnt(0)
	v_fmac_f32_e32 v34, v138, v2
	s_nop 1
	v_mov_b32_dpp v2, v34 quad_perm:[2,3,0,1] row_mask:0xf bank_mask:0xf
	s_waitcnt lgkmcnt(0)
	v_add_f32_e32 v2, v34, v2
	s_nop 1
	v_mov_b32_dpp v34, v2 row_shl:4 row_mask:0xf bank_mask:0x5
	v_mov_b32_dpp v34, v2 row_shr:4 row_mask:0xf bank_mask:0xa
	s_and_saveexec_b64 s[0:1], vcc
	s_cbranch_execz .LBB0_883
	v_mov_b32_e32 v121, v115
	s_waitcnt lgkmcnt(0)
	v_add_f32_e32 v2, v2, v34
	v_lshl_add_u64 v[34:35], v[122:123], 0, v[120:121]
	global_store_dword v[34:35], v2, off offset:640
.LBB0_883:
	s_or_b64 exec, exec, s[0:1]
	v_max_f32_e32 v2, v3, v3
	v_max_f32_e32 v2, 0, v2
	v_mul_f32_e32 v3, v138, v2
	s_nop 1
	v_mov_b32_dpp v3, v3 quad_perm:[1,0,3,2] row_mask:0xf bank_mask:0xf
	s_waitcnt lgkmcnt(0)
	v_fmac_f32_e32 v3, v138, v2
	s_nop 1
	v_mov_b32_dpp v2, v3 quad_perm:[2,3,0,1] row_mask:0xf bank_mask:0xf
	s_waitcnt lgkmcnt(0)
	v_add_f32_e32 v2, v3, v2
	s_nop 1
	v_mov_b32_dpp v3, v2 row_shl:4 row_mask:0xf bank_mask:0x5
	v_mov_b32_dpp v3, v2 row_shr:4 row_mask:0xf bank_mask:0xa
	s_and_saveexec_b64 s[0:1], vcc
	s_cbranch_execz .LBB0_885
	v_mov_b32_e32 v121, v115
	s_waitcnt lgkmcnt(0)
	v_add_f32_e32 v34, v2, v3
	v_lshl_add_u64 v[2:3], v[122:123], 0, v[120:121]
	global_store_dword v[2:3], v34, off offset:644
.LBB0_885:
	s_or_b64 exec, exec, s[0:1]
	v_max_f32_e32 v2, v4, v4
	v_max_f32_e32 v2, 0, v2
	s_waitcnt lgkmcnt(0)
	v_mul_f32_e32 v3, v138, v2
	s_nop 1
	v_mov_b32_dpp v3, v3 quad_perm:[1,0,3,2] row_mask:0xf bank_mask:0xf
	s_waitcnt lgkmcnt(0)
	v_fmac_f32_e32 v3, v138, v2
	s_nop 1
	v_mov_b32_dpp v2, v3 quad_perm:[2,3,0,1] row_mask:0xf bank_mask:0xf
	s_waitcnt lgkmcnt(0)
	v_add_f32_e32 v2, v3, v2
	s_nop 1
	v_mov_b32_dpp v3, v2 row_shl:4 row_mask:0xf bank_mask:0x5
	v_mov_b32_dpp v3, v2 row_shr:4 row_mask:0xf bank_mask:0xa
	s_and_saveexec_b64 s[0:1], vcc
	s_cbranch_execz .LBB0_887
	v_mov_b32_e32 v121, v115
	s_waitcnt lgkmcnt(0)
	v_add_f32_e32 v4, v2, v3
	v_lshl_add_u64 v[2:3], v[122:123], 0, v[120:121]
	global_store_dword v[2:3], v4, off offset:648
.LBB0_887:
	s_or_b64 exec, exec, s[0:1]
	v_max_f32_e32 v2, v5, v5
	v_max_f32_e32 v2, 0, v2
	s_waitcnt lgkmcnt(0)
	v_mul_f32_e32 v3, v138, v2
	s_nop 1
	v_mov_b32_dpp v3, v3 quad_perm:[1,0,3,2] row_mask:0xf bank_mask:0xf
	s_waitcnt lgkmcnt(0)
	v_fmac_f32_e32 v3, v138, v2
	s_nop 1
	v_mov_b32_dpp v2, v3 quad_perm:[2,3,0,1] row_mask:0xf bank_mask:0xf
	s_waitcnt lgkmcnt(0)
	v_add_f32_e32 v2, v3, v2
	s_nop 1
	v_mov_b32_dpp v3, v2 row_shl:4 row_mask:0xf bank_mask:0x5
	v_mov_b32_dpp v3, v2 row_shr:4 row_mask:0xf bank_mask:0xa
	s_and_saveexec_b64 s[0:1], vcc
	s_cbranch_execz .LBB0_889
	v_mov_b32_e32 v121, v115
	s_waitcnt lgkmcnt(0)
	v_add_f32_e32 v4, v2, v3
	v_lshl_add_u64 v[2:3], v[122:123], 0, v[120:121]
	global_store_dword v[2:3], v4, off offset:652
.LBB0_889:
	s_or_b64 exec, exec, s[0:1]
	v_max_f32_e32 v2, v6, v6
	v_max_f32_e32 v2, 0, v2
	s_waitcnt lgkmcnt(0)
	v_mul_f32_e32 v3, v138, v2
	s_nop 1
	v_mov_b32_dpp v3, v3 quad_perm:[1,0,3,2] row_mask:0xf bank_mask:0xf
	s_waitcnt lgkmcnt(0)
	v_fmac_f32_e32 v3, v138, v2
	s_nop 1
	v_mov_b32_dpp v2, v3 quad_perm:[2,3,0,1] row_mask:0xf bank_mask:0xf
	s_waitcnt lgkmcnt(0)
	v_add_f32_e32 v2, v3, v2
	s_nop 1
	v_mov_b32_dpp v3, v2 row_shl:4 row_mask:0xf bank_mask:0x5
	v_mov_b32_dpp v3, v2 row_shr:4 row_mask:0xf bank_mask:0xa
	s_and_saveexec_b64 s[0:1], vcc
	s_cbranch_execz .LBB0_891
	v_mov_b32_e32 v121, v115
	s_waitcnt lgkmcnt(0)
	v_add_f32_e32 v4, v2, v3
	v_lshl_add_u64 v[2:3], v[122:123], 0, v[120:121]
	global_store_dword v[2:3], v4, off offset:672
.LBB0_891:
	s_or_b64 exec, exec, s[0:1]
	v_max_f32_e32 v2, v7, v7
	v_max_f32_e32 v2, 0, v2
	s_waitcnt lgkmcnt(0)
	v_mul_f32_e32 v3, v138, v2
	s_nop 1
	v_mov_b32_dpp v3, v3 quad_perm:[1,0,3,2] row_mask:0xf bank_mask:0xf
	s_waitcnt lgkmcnt(0)
	v_fmac_f32_e32 v3, v138, v2
	s_nop 1
	v_mov_b32_dpp v2, v3 quad_perm:[2,3,0,1] row_mask:0xf bank_mask:0xf
	s_waitcnt lgkmcnt(0)
	v_add_f32_e32 v2, v3, v2
	s_nop 1
	v_mov_b32_dpp v3, v2 row_shl:4 row_mask:0xf bank_mask:0x5
	v_mov_b32_dpp v3, v2 row_shr:4 row_mask:0xf bank_mask:0xa
	s_and_saveexec_b64 s[0:1], vcc
	s_cbranch_execz .LBB0_893
	v_mov_b32_e32 v121, v115
	s_waitcnt lgkmcnt(0)
	v_add_f32_e32 v4, v2, v3
	v_lshl_add_u64 v[2:3], v[122:123], 0, v[120:121]
	global_store_dword v[2:3], v4, off offset:676
.LBB0_893:
	s_or_b64 exec, exec, s[0:1]
	v_max_f32_e32 v2, v8, v8
	v_max_f32_e32 v2, 0, v2
	s_waitcnt lgkmcnt(0)
	v_mul_f32_e32 v3, v138, v2
	s_nop 1
	v_mov_b32_dpp v3, v3 quad_perm:[1,0,3,2] row_mask:0xf bank_mask:0xf
	s_waitcnt lgkmcnt(0)
	v_fmac_f32_e32 v3, v138, v2
	s_nop 1
	v_mov_b32_dpp v2, v3 quad_perm:[2,3,0,1] row_mask:0xf bank_mask:0xf
	s_waitcnt lgkmcnt(0)
	v_add_f32_e32 v2, v3, v2
	s_nop 1
	v_mov_b32_dpp v3, v2 row_shl:4 row_mask:0xf bank_mask:0x5
	v_mov_b32_dpp v3, v2 row_shr:4 row_mask:0xf bank_mask:0xa
	s_and_saveexec_b64 s[0:1], vcc
	s_cbranch_execz .LBB0_895
	v_mov_b32_e32 v121, v115
	s_waitcnt lgkmcnt(0)
	v_add_f32_e32 v4, v2, v3
	v_lshl_add_u64 v[2:3], v[122:123], 0, v[120:121]
	global_store_dword v[2:3], v4, off offset:680
.LBB0_895:
	s_or_b64 exec, exec, s[0:1]
	v_max_f32_e32 v2, v9, v9
	v_max_f32_e32 v2, 0, v2
	s_waitcnt lgkmcnt(0)
	v_mul_f32_e32 v3, v138, v2
	s_nop 1
	v_mov_b32_dpp v3, v3 quad_perm:[1,0,3,2] row_mask:0xf bank_mask:0xf
	s_waitcnt lgkmcnt(0)
	v_fmac_f32_e32 v3, v138, v2
	s_nop 1
	v_mov_b32_dpp v2, v3 quad_perm:[2,3,0,1] row_mask:0xf bank_mask:0xf
	s_waitcnt lgkmcnt(0)
	v_add_f32_e32 v2, v3, v2
	s_nop 1
	v_mov_b32_dpp v3, v2 row_shl:4 row_mask:0xf bank_mask:0x5
	v_mov_b32_dpp v3, v2 row_shr:4 row_mask:0xf bank_mask:0xa
	s_and_saveexec_b64 s[0:1], vcc
	s_cbranch_execz .LBB0_897
	v_mov_b32_e32 v121, v115
	s_waitcnt lgkmcnt(0)
	v_add_f32_e32 v4, v2, v3
	v_lshl_add_u64 v[2:3], v[122:123], 0, v[120:121]
	global_store_dword v[2:3], v4, off offset:684
.LBB0_897:
	s_or_b64 exec, exec, s[0:1]
	v_max_f32_e32 v2, v10, v10
	v_max_f32_e32 v2, 0, v2
	s_waitcnt lgkmcnt(0)
	v_mul_f32_e32 v3, v138, v2
	s_nop 1
	v_mov_b32_dpp v3, v3 quad_perm:[1,0,3,2] row_mask:0xf bank_mask:0xf
	s_waitcnt lgkmcnt(0)
	v_fmac_f32_e32 v3, v138, v2
	s_nop 1
	v_mov_b32_dpp v2, v3 quad_perm:[2,3,0,1] row_mask:0xf bank_mask:0xf
	s_waitcnt lgkmcnt(0)
	v_add_f32_e32 v2, v3, v2
	s_nop 1
	v_mov_b32_dpp v3, v2 row_shl:4 row_mask:0xf bank_mask:0x5
	v_mov_b32_dpp v3, v2 row_shr:4 row_mask:0xf bank_mask:0xa
	s_and_saveexec_b64 s[0:1], vcc
	s_cbranch_execz .LBB0_899
	v_mov_b32_e32 v121, v115
	s_waitcnt lgkmcnt(0)
	v_add_f32_e32 v4, v2, v3
	v_lshl_add_u64 v[2:3], v[122:123], 0, v[120:121]
	global_store_dword v[2:3], v4, off offset:704
.LBB0_899:
	s_or_b64 exec, exec, s[0:1]
	v_max_f32_e32 v2, v11, v11
	v_max_f32_e32 v2, 0, v2
	s_waitcnt lgkmcnt(0)
	v_mul_f32_e32 v3, v138, v2
	s_nop 1
	v_mov_b32_dpp v3, v3 quad_perm:[1,0,3,2] row_mask:0xf bank_mask:0xf
	s_waitcnt lgkmcnt(0)
	v_fmac_f32_e32 v3, v138, v2
	s_nop 1
	v_mov_b32_dpp v2, v3 quad_perm:[2,3,0,1] row_mask:0xf bank_mask:0xf
	s_waitcnt lgkmcnt(0)
	v_add_f32_e32 v2, v3, v2
	s_nop 1
	v_mov_b32_dpp v3, v2 row_shl:4 row_mask:0xf bank_mask:0x5
	v_mov_b32_dpp v3, v2 row_shr:4 row_mask:0xf bank_mask:0xa
	s_and_saveexec_b64 s[0:1], vcc
	s_cbranch_execz .LBB0_901
	v_mov_b32_e32 v121, v115
	s_waitcnt lgkmcnt(0)
	v_add_f32_e32 v4, v2, v3
	v_lshl_add_u64 v[2:3], v[122:123], 0, v[120:121]
	global_store_dword v[2:3], v4, off offset:708
.LBB0_901:
	s_or_b64 exec, exec, s[0:1]
	v_max_f32_e32 v2, v12, v12
	v_max_f32_e32 v2, 0, v2
	s_waitcnt lgkmcnt(0)
	v_mul_f32_e32 v3, v138, v2
	s_nop 1
	v_mov_b32_dpp v3, v3 quad_perm:[1,0,3,2] row_mask:0xf bank_mask:0xf
	s_waitcnt lgkmcnt(0)
	v_fmac_f32_e32 v3, v138, v2
	s_nop 1
	v_mov_b32_dpp v2, v3 quad_perm:[2,3,0,1] row_mask:0xf bank_mask:0xf
	s_waitcnt lgkmcnt(0)
	v_add_f32_e32 v2, v3, v2
	s_nop 1
	v_mov_b32_dpp v3, v2 row_shl:4 row_mask:0xf bank_mask:0x5
	v_mov_b32_dpp v3, v2 row_shr:4 row_mask:0xf bank_mask:0xa
	s_and_saveexec_b64 s[0:1], vcc
	s_cbranch_execz .LBB0_903
	v_mov_b32_e32 v121, v115
	s_waitcnt lgkmcnt(0)
	v_add_f32_e32 v4, v2, v3
	v_lshl_add_u64 v[2:3], v[122:123], 0, v[120:121]
	global_store_dword v[2:3], v4, off offset:712
.LBB0_903:
	s_or_b64 exec, exec, s[0:1]
	v_max_f32_e32 v2, v13, v13
	v_max_f32_e32 v2, 0, v2
	s_waitcnt lgkmcnt(0)
	v_mul_f32_e32 v3, v138, v2
	s_nop 1
	v_mov_b32_dpp v3, v3 quad_perm:[1,0,3,2] row_mask:0xf bank_mask:0xf
	s_waitcnt lgkmcnt(0)
	v_fmac_f32_e32 v3, v138, v2
	s_nop 1
	v_mov_b32_dpp v2, v3 quad_perm:[2,3,0,1] row_mask:0xf bank_mask:0xf
	s_waitcnt lgkmcnt(0)
	v_add_f32_e32 v2, v3, v2
	s_nop 1
	v_mov_b32_dpp v3, v2 row_shl:4 row_mask:0xf bank_mask:0x5
	v_mov_b32_dpp v3, v2 row_shr:4 row_mask:0xf bank_mask:0xa
	s_and_saveexec_b64 s[0:1], vcc
	s_cbranch_execz .LBB0_905
	v_mov_b32_e32 v121, v115
	s_waitcnt lgkmcnt(0)
	v_add_f32_e32 v4, v2, v3
	v_lshl_add_u64 v[2:3], v[122:123], 0, v[120:121]
	global_store_dword v[2:3], v4, off offset:716
.LBB0_905:
	s_or_b64 exec, exec, s[0:1]
	v_max_f32_e32 v2, v14, v14
	v_max_f32_e32 v2, 0, v2
	s_waitcnt lgkmcnt(0)
	v_mul_f32_e32 v3, v138, v2
	s_nop 1
	v_mov_b32_dpp v3, v3 quad_perm:[1,0,3,2] row_mask:0xf bank_mask:0xf
	s_waitcnt lgkmcnt(0)
	v_fmac_f32_e32 v3, v138, v2
	s_nop 1
	v_mov_b32_dpp v2, v3 quad_perm:[2,3,0,1] row_mask:0xf bank_mask:0xf
	s_waitcnt lgkmcnt(0)
	v_add_f32_e32 v2, v3, v2
	s_nop 1
	v_mov_b32_dpp v3, v2 row_shl:4 row_mask:0xf bank_mask:0x5
	v_mov_b32_dpp v3, v2 row_shr:4 row_mask:0xf bank_mask:0xa
	s_and_saveexec_b64 s[0:1], vcc
	s_cbranch_execz .LBB0_907
	v_mov_b32_e32 v121, v115
	s_waitcnt lgkmcnt(0)
	v_add_f32_e32 v4, v2, v3
	v_lshl_add_u64 v[2:3], v[122:123], 0, v[120:121]
	global_store_dword v[2:3], v4, off offset:736
.LBB0_907:
	s_or_b64 exec, exec, s[0:1]
	v_max_f32_e32 v2, v15, v15
	v_max_f32_e32 v2, 0, v2
	s_waitcnt lgkmcnt(0)
	v_mul_f32_e32 v3, v138, v2
	s_nop 1
	v_mov_b32_dpp v3, v3 quad_perm:[1,0,3,2] row_mask:0xf bank_mask:0xf
	s_waitcnt lgkmcnt(0)
	v_fmac_f32_e32 v3, v138, v2
	s_nop 1
	v_mov_b32_dpp v2, v3 quad_perm:[2,3,0,1] row_mask:0xf bank_mask:0xf
	s_waitcnt lgkmcnt(0)
	v_add_f32_e32 v2, v3, v2
	s_nop 1
	v_mov_b32_dpp v3, v2 row_shl:4 row_mask:0xf bank_mask:0x5
	v_mov_b32_dpp v3, v2 row_shr:4 row_mask:0xf bank_mask:0xa
	s_and_saveexec_b64 s[0:1], vcc
	s_cbranch_execz .LBB0_909
	v_mov_b32_e32 v121, v115
	s_waitcnt lgkmcnt(0)
	v_add_f32_e32 v4, v2, v3
	v_lshl_add_u64 v[2:3], v[122:123], 0, v[120:121]
	global_store_dword v[2:3], v4, off offset:740
.LBB0_909:
	s_or_b64 exec, exec, s[0:1]
	v_max_f32_e32 v2, v16, v16
	v_max_f32_e32 v2, 0, v2
	s_waitcnt lgkmcnt(0)
	v_mul_f32_e32 v3, v138, v2
	s_nop 1
	v_mov_b32_dpp v3, v3 quad_perm:[1,0,3,2] row_mask:0xf bank_mask:0xf
	s_waitcnt lgkmcnt(0)
	v_fmac_f32_e32 v3, v138, v2
	s_nop 1
	v_mov_b32_dpp v2, v3 quad_perm:[2,3,0,1] row_mask:0xf bank_mask:0xf
	s_waitcnt lgkmcnt(0)
	v_add_f32_e32 v2, v3, v2
	s_nop 1
	v_mov_b32_dpp v3, v2 row_shl:4 row_mask:0xf bank_mask:0x5
	v_mov_b32_dpp v3, v2 row_shr:4 row_mask:0xf bank_mask:0xa
	s_and_saveexec_b64 s[0:1], vcc
	s_cbranch_execz .LBB0_911
	v_mov_b32_e32 v121, v115
	s_waitcnt lgkmcnt(0)
	v_add_f32_e32 v4, v2, v3
	v_lshl_add_u64 v[2:3], v[122:123], 0, v[120:121]
	global_store_dword v[2:3], v4, off offset:744
.LBB0_911:
	s_or_b64 exec, exec, s[0:1]
	v_max_f32_e32 v2, v17, v17
	v_max_f32_e32 v2, 0, v2
	s_waitcnt lgkmcnt(0)
	v_mul_f32_e32 v3, v138, v2
	s_nop 1
	v_mov_b32_dpp v3, v3 quad_perm:[1,0,3,2] row_mask:0xf bank_mask:0xf
	s_waitcnt lgkmcnt(0)
	v_fmac_f32_e32 v3, v138, v2
	s_nop 1
	v_mov_b32_dpp v2, v3 quad_perm:[2,3,0,1] row_mask:0xf bank_mask:0xf
	s_waitcnt lgkmcnt(0)
	v_add_f32_e32 v2, v3, v2
	s_nop 1
	v_mov_b32_dpp v3, v2 row_shl:4 row_mask:0xf bank_mask:0x5
	v_mov_b32_dpp v3, v2 row_shr:4 row_mask:0xf bank_mask:0xa
	s_and_saveexec_b64 s[0:1], vcc
	s_cbranch_execz .LBB0_913
	v_mov_b32_e32 v121, v115
	s_waitcnt lgkmcnt(0)
	v_add_f32_e32 v4, v2, v3
	v_lshl_add_u64 v[2:3], v[122:123], 0, v[120:121]
	global_store_dword v[2:3], v4, off offset:748
.LBB0_913:
	s_or_b64 exec, exec, s[0:1]
	v_readlane_b32 s36, v253, 32
	s_waitcnt lgkmcnt(0)
	v_lshlrev_b64 v[2:3], 15, v[124:125]
	v_readlane_b32 s44, v253, 40
	v_readlane_b32 s45, v253, 41
	v_mov_b32_e32 v131, v115
	v_mov_b32_e32 v127, v115
	v_lshl_add_u64 v[2:3], s[44:45], 0, v[2:3]
	v_lshl_add_u64 v[2:3], v[2:3], 0, v[130:131]
	v_lshl_add_u64 v[2:3], v[2:3], 0, v[126:127]
	global_load_dwordx4 v[42:45], v[2:3], off offset:16
	global_load_dwordx4 v[34:37], v[2:3], off
	global_load_dwordx4 v[66:69], v[2:3], off offset:80
	global_load_dwordx4 v[50:53], v[2:3], off offset:64
	global_load_dwordx4 v[82:85], v[2:3], off offset:144
	global_load_dwordx4 v[74:77], v[2:3], off offset:128
	global_load_dwordx4 v[94:97], v[2:3], off offset:208
	global_load_dwordx4 v[86:89], v[2:3], off offset:192
	s_waitcnt vmcnt(15)
	v_cvt_f16_f32_e32 v5, v49
	s_waitcnt vmcnt(14)
	v_cvt_f16_f32_e32 v2, v38
	v_cvt_pk_f16_f32 v6, v47, v48
	v_cvt_pk_f16_f32 v4, v41, v46
	v_cvt_pk_f16_f32 v3, v39, v40
	v_pack_b32_f16 v2, v2, v3
	v_alignbit_b32 v3, v4, v3, 16
	v_alignbit_b32 v4, v6, v4, 16
	v_alignbit_b32 v5, v5, v6, 16
	s_waitcnt vmcnt(13)
	v_cvt_f16_f32_e32 v61, v61
	s_waitcnt vmcnt(12)
	v_cvt_f16_f32_e32 v54, v54
	v_mfma_f32_32x32x16_f16 v[2:17], v[2:5], v[30:33], 0
	v_cvt_pk_f16_f32 v59, v59, v60
	v_cvt_pk_f16_f32 v57, v57, v58
	v_cvt_pk_f16_f32 v55, v55, v56
	v_pack_b32_f16 v38, v54, v55
	v_alignbit_b32 v39, v57, v55, 16
	v_alignbit_b32 v40, v59, v57, 16
	v_alignbit_b32 v41, v61, v59, 16
	s_waitcnt vmcnt(11)
	v_cvt_f16_f32_e32 v73, v73
	s_waitcnt vmcnt(10)
	v_cvt_f16_f32_e32 v62, v62
	v_mfma_f32_32x32x16_f16 v[2:17], v[38:41], v[26:29], v[2:17]
	v_cvt_pk_f16_f32 v71, v71, v72
	v_cvt_pk_f16_f32 v65, v65, v70
	v_cvt_pk_f16_f32 v63, v63, v64
	v_pack_b32_f16 v38, v62, v63
	v_alignbit_b32 v39, v65, v63, 16
	v_alignbit_b32 v40, v71, v65, 16
	v_alignbit_b32 v41, v73, v71, 16
	s_waitcnt vmcnt(9)
	v_cvt_f16_f32_e32 v93, v93
	s_waitcnt vmcnt(8)
	v_cvt_f16_f32_e32 v78, v78
	v_mfma_f32_32x32x16_f16 v[2:17], v[38:41], v[22:25], v[2:17]
	v_cvt_pk_f16_f32 v91, v91, v92
	v_cvt_pk_f16_f32 v81, v81, v90
	v_cvt_pk_f16_f32 v79, v79, v80
	v_pack_b32_f16 v38, v78, v79
	v_alignbit_b32 v39, v81, v79, 16
	v_alignbit_b32 v40, v91, v81, 16
	v_alignbit_b32 v41, v93, v91, 16
	v_readlane_b32 s37, v253, 33
	v_readlane_b32 s38, v253, 34
	v_mfma_f32_32x32x16_f16 v[2:17], v[38:41], v[18:21], v[2:17]
	v_readlane_b32 s39, v253, 35
	v_readlane_b32 s40, v253, 36
	v_readlane_b32 s41, v253, 37
	v_readlane_b32 s42, v253, 38
	v_readlane_b32 s43, v253, 39
	v_readlane_b32 s46, v253, 42
	v_readlane_b32 s47, v253, 43
	s_nop 4
	v_max_f32_e32 v2, v2, v2
	v_max_f32_e32 v2, 0, v2
	v_mul_f32_e32 v38, v138, v2
	s_nop 1
	v_mov_b32_dpp v38, v38 quad_perm:[1,0,3,2] row_mask:0xf bank_mask:0xf
	v_readlane_b32 s48, v253, 44
	v_readlane_b32 s49, v253, 45
	v_readlane_b32 s50, v253, 46
	v_readlane_b32 s51, v253, 47
	s_waitcnt lgkmcnt(0)
	v_fmac_f32_e32 v38, v138, v2
	s_nop 1
	v_mov_b32_dpp v2, v38 quad_perm:[2,3,0,1] row_mask:0xf bank_mask:0xf
	s_waitcnt lgkmcnt(0)
	v_add_f32_e32 v2, v38, v2
	s_nop 1
	v_mov_b32_dpp v38, v2 row_shl:4 row_mask:0xf bank_mask:0x5
	v_mov_b32_dpp v38, v2 row_shr:4 row_mask:0xf bank_mask:0xa
	s_and_saveexec_b64 s[0:1], vcc
	s_cbranch_execz .LBB0_915
	v_mov_b32_e32 v121, v115
	s_waitcnt lgkmcnt(0)
	v_add_f32_e32 v2, v2, v38
	v_lshl_add_u64 v[38:39], v[122:123], 0, v[120:121]
	global_store_dword v[38:39], v2, off offset:768
.LBB0_915:
	s_or_b64 exec, exec, s[0:1]
	v_max_f32_e32 v2, v3, v3
	v_max_f32_e32 v2, 0, v2
	v_mul_f32_e32 v3, v138, v2
	s_nop 1
	v_mov_b32_dpp v3, v3 quad_perm:[1,0,3,2] row_mask:0xf bank_mask:0xf
	s_waitcnt lgkmcnt(0)
	v_fmac_f32_e32 v3, v138, v2
	s_nop 1
	v_mov_b32_dpp v2, v3 quad_perm:[2,3,0,1] row_mask:0xf bank_mask:0xf
	s_waitcnt lgkmcnt(0)
	v_add_f32_e32 v2, v3, v2
	s_nop 1
	v_mov_b32_dpp v3, v2 row_shl:4 row_mask:0xf bank_mask:0x5
	v_mov_b32_dpp v3, v2 row_shr:4 row_mask:0xf bank_mask:0xa
	s_and_saveexec_b64 s[0:1], vcc
	s_cbranch_execz .LBB0_917
	v_mov_b32_e32 v121, v115
	s_waitcnt lgkmcnt(0)
	v_add_f32_e32 v38, v2, v3
	v_lshl_add_u64 v[2:3], v[122:123], 0, v[120:121]
	global_store_dword v[2:3], v38, off offset:772
.LBB0_917:
	s_or_b64 exec, exec, s[0:1]
	v_max_f32_e32 v2, v4, v4
	v_max_f32_e32 v2, 0, v2
	s_waitcnt lgkmcnt(0)
	v_mul_f32_e32 v3, v138, v2
	s_nop 1
	v_mov_b32_dpp v3, v3 quad_perm:[1,0,3,2] row_mask:0xf bank_mask:0xf
	s_waitcnt lgkmcnt(0)
	v_fmac_f32_e32 v3, v138, v2
	s_nop 1
	v_mov_b32_dpp v2, v3 quad_perm:[2,3,0,1] row_mask:0xf bank_mask:0xf
	s_waitcnt lgkmcnt(0)
	v_add_f32_e32 v2, v3, v2
	s_nop 1
	v_mov_b32_dpp v3, v2 row_shl:4 row_mask:0xf bank_mask:0x5
	v_mov_b32_dpp v3, v2 row_shr:4 row_mask:0xf bank_mask:0xa
	s_and_saveexec_b64 s[0:1], vcc
	s_cbranch_execz .LBB0_919
	v_mov_b32_e32 v121, v115
	s_waitcnt lgkmcnt(0)
	v_add_f32_e32 v4, v2, v3
	v_lshl_add_u64 v[2:3], v[122:123], 0, v[120:121]
	global_store_dword v[2:3], v4, off offset:776
.LBB0_919:
	s_or_b64 exec, exec, s[0:1]
	v_max_f32_e32 v2, v5, v5
	v_max_f32_e32 v2, 0, v2
	s_waitcnt lgkmcnt(0)
	v_mul_f32_e32 v3, v138, v2
	s_nop 1
	v_mov_b32_dpp v3, v3 quad_perm:[1,0,3,2] row_mask:0xf bank_mask:0xf
	s_waitcnt lgkmcnt(0)
	v_fmac_f32_e32 v3, v138, v2
	s_nop 1
	v_mov_b32_dpp v2, v3 quad_perm:[2,3,0,1] row_mask:0xf bank_mask:0xf
	s_waitcnt lgkmcnt(0)
	v_add_f32_e32 v2, v3, v2
	s_nop 1
	v_mov_b32_dpp v3, v2 row_shl:4 row_mask:0xf bank_mask:0x5
	v_mov_b32_dpp v3, v2 row_shr:4 row_mask:0xf bank_mask:0xa
	s_and_saveexec_b64 s[0:1], vcc
	s_cbranch_execz .LBB0_921
	v_mov_b32_e32 v121, v115
	s_waitcnt lgkmcnt(0)
	v_add_f32_e32 v4, v2, v3
	v_lshl_add_u64 v[2:3], v[122:123], 0, v[120:121]
	global_store_dword v[2:3], v4, off offset:780
.LBB0_921:
	s_or_b64 exec, exec, s[0:1]
	v_max_f32_e32 v2, v6, v6
	v_max_f32_e32 v2, 0, v2
	s_waitcnt lgkmcnt(0)
	v_mul_f32_e32 v3, v138, v2
	s_nop 1
	v_mov_b32_dpp v3, v3 quad_perm:[1,0,3,2] row_mask:0xf bank_mask:0xf
	s_waitcnt lgkmcnt(0)
	v_fmac_f32_e32 v3, v138, v2
	s_nop 1
	v_mov_b32_dpp v2, v3 quad_perm:[2,3,0,1] row_mask:0xf bank_mask:0xf
	s_waitcnt lgkmcnt(0)
	v_add_f32_e32 v2, v3, v2
	s_nop 1
	v_mov_b32_dpp v3, v2 row_shl:4 row_mask:0xf bank_mask:0x5
	v_mov_b32_dpp v3, v2 row_shr:4 row_mask:0xf bank_mask:0xa
	s_and_saveexec_b64 s[0:1], vcc
	s_cbranch_execz .LBB0_923
	v_mov_b32_e32 v121, v115
	s_waitcnt lgkmcnt(0)
	v_add_f32_e32 v4, v2, v3
	v_lshl_add_u64 v[2:3], v[122:123], 0, v[120:121]
	global_store_dword v[2:3], v4, off offset:800
.LBB0_923:
	s_or_b64 exec, exec, s[0:1]
	v_max_f32_e32 v2, v7, v7
	v_max_f32_e32 v2, 0, v2
	s_waitcnt lgkmcnt(0)
	v_mul_f32_e32 v3, v138, v2
	s_nop 1
	v_mov_b32_dpp v3, v3 quad_perm:[1,0,3,2] row_mask:0xf bank_mask:0xf
	s_waitcnt lgkmcnt(0)
	v_fmac_f32_e32 v3, v138, v2
	s_nop 1
	v_mov_b32_dpp v2, v3 quad_perm:[2,3,0,1] row_mask:0xf bank_mask:0xf
	s_waitcnt lgkmcnt(0)
	v_add_f32_e32 v2, v3, v2
	s_nop 1
	v_mov_b32_dpp v3, v2 row_shl:4 row_mask:0xf bank_mask:0x5
	v_mov_b32_dpp v3, v2 row_shr:4 row_mask:0xf bank_mask:0xa
	s_and_saveexec_b64 s[0:1], vcc
	s_cbranch_execz .LBB0_925
	v_mov_b32_e32 v121, v115
	s_waitcnt lgkmcnt(0)
	v_add_f32_e32 v4, v2, v3
	v_lshl_add_u64 v[2:3], v[122:123], 0, v[120:121]
	global_store_dword v[2:3], v4, off offset:804
.LBB0_925:
	s_or_b64 exec, exec, s[0:1]
	v_max_f32_e32 v2, v8, v8
	v_max_f32_e32 v2, 0, v2
	s_waitcnt lgkmcnt(0)
	v_mul_f32_e32 v3, v138, v2
	s_nop 1
	v_mov_b32_dpp v3, v3 quad_perm:[1,0,3,2] row_mask:0xf bank_mask:0xf
	s_waitcnt lgkmcnt(0)
	v_fmac_f32_e32 v3, v138, v2
	s_nop 1
	v_mov_b32_dpp v2, v3 quad_perm:[2,3,0,1] row_mask:0xf bank_mask:0xf
	s_waitcnt lgkmcnt(0)
	v_add_f32_e32 v2, v3, v2
	s_nop 1
	v_mov_b32_dpp v3, v2 row_shl:4 row_mask:0xf bank_mask:0x5
	v_mov_b32_dpp v3, v2 row_shr:4 row_mask:0xf bank_mask:0xa
	s_and_saveexec_b64 s[0:1], vcc
	s_cbranch_execz .LBB0_927
	v_mov_b32_e32 v121, v115
	s_waitcnt lgkmcnt(0)
	v_add_f32_e32 v4, v2, v3
	v_lshl_add_u64 v[2:3], v[122:123], 0, v[120:121]
	global_store_dword v[2:3], v4, off offset:808
.LBB0_927:
	s_or_b64 exec, exec, s[0:1]
	v_max_f32_e32 v2, v9, v9
	v_max_f32_e32 v2, 0, v2
	s_waitcnt lgkmcnt(0)
	v_mul_f32_e32 v3, v138, v2
	s_nop 1
	v_mov_b32_dpp v3, v3 quad_perm:[1,0,3,2] row_mask:0xf bank_mask:0xf
	s_waitcnt lgkmcnt(0)
	v_fmac_f32_e32 v3, v138, v2
	s_nop 1
	v_mov_b32_dpp v2, v3 quad_perm:[2,3,0,1] row_mask:0xf bank_mask:0xf
	s_waitcnt lgkmcnt(0)
	v_add_f32_e32 v2, v3, v2
	s_nop 1
	v_mov_b32_dpp v3, v2 row_shl:4 row_mask:0xf bank_mask:0x5
	v_mov_b32_dpp v3, v2 row_shr:4 row_mask:0xf bank_mask:0xa
	s_and_saveexec_b64 s[0:1], vcc
	s_cbranch_execz .LBB0_929
	v_mov_b32_e32 v121, v115
	s_waitcnt lgkmcnt(0)
	v_add_f32_e32 v4, v2, v3
	v_lshl_add_u64 v[2:3], v[122:123], 0, v[120:121]
	global_store_dword v[2:3], v4, off offset:812
.LBB0_929:
	s_or_b64 exec, exec, s[0:1]
	v_max_f32_e32 v2, v10, v10
	v_max_f32_e32 v2, 0, v2
	s_waitcnt lgkmcnt(0)
	v_mul_f32_e32 v3, v138, v2
	s_nop 1
	v_mov_b32_dpp v3, v3 quad_perm:[1,0,3,2] row_mask:0xf bank_mask:0xf
	s_waitcnt lgkmcnt(0)
	v_fmac_f32_e32 v3, v138, v2
	s_nop 1
	v_mov_b32_dpp v2, v3 quad_perm:[2,3,0,1] row_mask:0xf bank_mask:0xf
	s_waitcnt lgkmcnt(0)
	v_add_f32_e32 v2, v3, v2
	s_nop 1
	v_mov_b32_dpp v3, v2 row_shl:4 row_mask:0xf bank_mask:0x5
	v_mov_b32_dpp v3, v2 row_shr:4 row_mask:0xf bank_mask:0xa
	s_and_saveexec_b64 s[0:1], vcc
	s_cbranch_execz .LBB0_931
	v_mov_b32_e32 v121, v115
	s_waitcnt lgkmcnt(0)
	v_add_f32_e32 v4, v2, v3
	v_lshl_add_u64 v[2:3], v[122:123], 0, v[120:121]
	global_store_dword v[2:3], v4, off offset:832
.LBB0_931:
	s_or_b64 exec, exec, s[0:1]
	v_max_f32_e32 v2, v11, v11
	v_max_f32_e32 v2, 0, v2
	s_waitcnt lgkmcnt(0)
	v_mul_f32_e32 v3, v138, v2
	s_nop 1
	v_mov_b32_dpp v3, v3 quad_perm:[1,0,3,2] row_mask:0xf bank_mask:0xf
	s_waitcnt lgkmcnt(0)
	v_fmac_f32_e32 v3, v138, v2
	s_nop 1
	v_mov_b32_dpp v2, v3 quad_perm:[2,3,0,1] row_mask:0xf bank_mask:0xf
	s_waitcnt lgkmcnt(0)
	v_add_f32_e32 v2, v3, v2
	s_nop 1
	v_mov_b32_dpp v3, v2 row_shl:4 row_mask:0xf bank_mask:0x5
	v_mov_b32_dpp v3, v2 row_shr:4 row_mask:0xf bank_mask:0xa
	s_and_saveexec_b64 s[0:1], vcc
	s_cbranch_execz .LBB0_933
	v_mov_b32_e32 v121, v115
	s_waitcnt lgkmcnt(0)
	v_add_f32_e32 v4, v2, v3
	v_lshl_add_u64 v[2:3], v[122:123], 0, v[120:121]
	global_store_dword v[2:3], v4, off offset:836
.LBB0_933:
	s_or_b64 exec, exec, s[0:1]
	v_max_f32_e32 v2, v12, v12
	v_max_f32_e32 v2, 0, v2
	s_waitcnt lgkmcnt(0)
	v_mul_f32_e32 v3, v138, v2
	s_nop 1
	v_mov_b32_dpp v3, v3 quad_perm:[1,0,3,2] row_mask:0xf bank_mask:0xf
	s_waitcnt lgkmcnt(0)
	v_fmac_f32_e32 v3, v138, v2
	s_nop 1
	v_mov_b32_dpp v2, v3 quad_perm:[2,3,0,1] row_mask:0xf bank_mask:0xf
	s_waitcnt lgkmcnt(0)
	v_add_f32_e32 v2, v3, v2
	s_nop 1
	v_mov_b32_dpp v3, v2 row_shl:4 row_mask:0xf bank_mask:0x5
	v_mov_b32_dpp v3, v2 row_shr:4 row_mask:0xf bank_mask:0xa
	s_and_saveexec_b64 s[0:1], vcc
	s_cbranch_execz .LBB0_935
	v_mov_b32_e32 v121, v115
	s_waitcnt lgkmcnt(0)
	v_add_f32_e32 v4, v2, v3
	v_lshl_add_u64 v[2:3], v[122:123], 0, v[120:121]
	global_store_dword v[2:3], v4, off offset:840
.LBB0_935:
	s_or_b64 exec, exec, s[0:1]
	v_max_f32_e32 v2, v13, v13
	v_max_f32_e32 v2, 0, v2
	s_waitcnt lgkmcnt(0)
	v_mul_f32_e32 v3, v138, v2
	s_nop 1
	v_mov_b32_dpp v3, v3 quad_perm:[1,0,3,2] row_mask:0xf bank_mask:0xf
	s_waitcnt lgkmcnt(0)
	v_fmac_f32_e32 v3, v138, v2
	s_nop 1
	v_mov_b32_dpp v2, v3 quad_perm:[2,3,0,1] row_mask:0xf bank_mask:0xf
	s_waitcnt lgkmcnt(0)
	v_add_f32_e32 v2, v3, v2
	s_nop 1
	v_mov_b32_dpp v3, v2 row_shl:4 row_mask:0xf bank_mask:0x5
	v_mov_b32_dpp v3, v2 row_shr:4 row_mask:0xf bank_mask:0xa
	s_and_saveexec_b64 s[0:1], vcc
	s_cbranch_execz .LBB0_937
	v_mov_b32_e32 v121, v115
	s_waitcnt lgkmcnt(0)
	v_add_f32_e32 v4, v2, v3
	v_lshl_add_u64 v[2:3], v[122:123], 0, v[120:121]
	global_store_dword v[2:3], v4, off offset:844
.LBB0_937:
	s_or_b64 exec, exec, s[0:1]
	v_max_f32_e32 v2, v14, v14
	v_max_f32_e32 v2, 0, v2
	s_waitcnt lgkmcnt(0)
	v_mul_f32_e32 v3, v138, v2
	s_nop 1
	v_mov_b32_dpp v3, v3 quad_perm:[1,0,3,2] row_mask:0xf bank_mask:0xf
	s_waitcnt lgkmcnt(0)
	v_fmac_f32_e32 v3, v138, v2
	s_nop 1
	v_mov_b32_dpp v2, v3 quad_perm:[2,3,0,1] row_mask:0xf bank_mask:0xf
	s_waitcnt lgkmcnt(0)
	v_add_f32_e32 v2, v3, v2
	s_nop 1
	v_mov_b32_dpp v3, v2 row_shl:4 row_mask:0xf bank_mask:0x5
	v_mov_b32_dpp v3, v2 row_shr:4 row_mask:0xf bank_mask:0xa
	s_and_saveexec_b64 s[0:1], vcc
	s_cbranch_execz .LBB0_939
	v_mov_b32_e32 v121, v115
	s_waitcnt lgkmcnt(0)
	v_add_f32_e32 v4, v2, v3
	v_lshl_add_u64 v[2:3], v[122:123], 0, v[120:121]
	global_store_dword v[2:3], v4, off offset:864
.LBB0_939:
	s_or_b64 exec, exec, s[0:1]
	v_max_f32_e32 v2, v15, v15
	v_max_f32_e32 v2, 0, v2
	s_waitcnt lgkmcnt(0)
	v_mul_f32_e32 v3, v138, v2
	s_nop 1
	v_mov_b32_dpp v3, v3 quad_perm:[1,0,3,2] row_mask:0xf bank_mask:0xf
	s_waitcnt lgkmcnt(0)
	v_fmac_f32_e32 v3, v138, v2
	s_nop 1
	v_mov_b32_dpp v2, v3 quad_perm:[2,3,0,1] row_mask:0xf bank_mask:0xf
	s_waitcnt lgkmcnt(0)
	v_add_f32_e32 v2, v3, v2
	s_nop 1
	v_mov_b32_dpp v3, v2 row_shl:4 row_mask:0xf bank_mask:0x5
	v_mov_b32_dpp v3, v2 row_shr:4 row_mask:0xf bank_mask:0xa
	s_and_saveexec_b64 s[0:1], vcc
	s_cbranch_execz .LBB0_941
	v_mov_b32_e32 v121, v115
	s_waitcnt lgkmcnt(0)
	v_add_f32_e32 v4, v2, v3
	v_lshl_add_u64 v[2:3], v[122:123], 0, v[120:121]
	global_store_dword v[2:3], v4, off offset:868
.LBB0_941:
	s_or_b64 exec, exec, s[0:1]
	v_max_f32_e32 v2, v16, v16
	v_max_f32_e32 v2, 0, v2
	s_waitcnt lgkmcnt(0)
	v_mul_f32_e32 v3, v138, v2
	s_nop 1
	v_mov_b32_dpp v3, v3 quad_perm:[1,0,3,2] row_mask:0xf bank_mask:0xf
	s_waitcnt lgkmcnt(0)
	v_fmac_f32_e32 v3, v138, v2
	s_nop 1
	v_mov_b32_dpp v2, v3 quad_perm:[2,3,0,1] row_mask:0xf bank_mask:0xf
	s_waitcnt lgkmcnt(0)
	v_add_f32_e32 v2, v3, v2
	s_nop 1
	v_mov_b32_dpp v3, v2 row_shl:4 row_mask:0xf bank_mask:0x5
	v_mov_b32_dpp v3, v2 row_shr:4 row_mask:0xf bank_mask:0xa
	s_and_saveexec_b64 s[0:1], vcc
	s_cbranch_execz .LBB0_943
	v_mov_b32_e32 v121, v115
	s_waitcnt lgkmcnt(0)
	v_add_f32_e32 v4, v2, v3
	v_lshl_add_u64 v[2:3], v[122:123], 0, v[120:121]
	global_store_dword v[2:3], v4, off offset:872
.LBB0_943:
	s_or_b64 exec, exec, s[0:1]
	v_max_f32_e32 v2, v17, v17
	v_max_f32_e32 v2, 0, v2
	s_waitcnt lgkmcnt(0)
	v_mul_f32_e32 v3, v138, v2
	s_nop 1
	v_mov_b32_dpp v3, v3 quad_perm:[1,0,3,2] row_mask:0xf bank_mask:0xf
	s_waitcnt lgkmcnt(0)
	v_fmac_f32_e32 v3, v138, v2
	s_nop 1
	v_mov_b32_dpp v2, v3 quad_perm:[2,3,0,1] row_mask:0xf bank_mask:0xf
	s_waitcnt lgkmcnt(0)
	v_add_f32_e32 v2, v3, v2
	s_nop 1
	v_mov_b32_dpp v3, v2 row_shl:4 row_mask:0xf bank_mask:0x5
	v_mov_b32_dpp v3, v2 row_shr:4 row_mask:0xf bank_mask:0xa
	s_and_saveexec_b64 s[0:1], vcc
	s_cbranch_execz .LBB0_945
	v_mov_b32_e32 v121, v115
	s_waitcnt lgkmcnt(0)
	v_add_f32_e32 v4, v2, v3
	v_lshl_add_u64 v[2:3], v[122:123], 0, v[120:121]
	global_store_dword v[2:3], v4, off offset:876
.LBB0_945:
	s_or_b64 exec, exec, s[0:1]
	s_waitcnt vmcnt(7)
	v_cvt_f16_f32_e32 v5, v45
	s_waitcnt vmcnt(6)
	v_cvt_f16_f32_e32 v2, v34
	v_cvt_pk_f16_f32 v6, v43, v44
	v_cvt_pk_f16_f32 v4, v37, v42
	s_waitcnt lgkmcnt(0)
	v_cvt_pk_f16_f32 v3, v35, v36
	v_pack_b32_f16 v2, v2, v3
	v_alignbit_b32 v3, v4, v3, 16
	v_alignbit_b32 v4, v6, v4, 16
	v_alignbit_b32 v5, v5, v6, 16
	s_waitcnt vmcnt(5)
	v_cvt_f16_f32_e32 v56, v69
	s_waitcnt vmcnt(4)
	v_cvt_f16_f32_e32 v50, v50
	v_mfma_f32_32x32x16_f16 v[2:17], v[2:5], v[30:33], 0
	v_cvt_pk_f16_f32 v57, v67, v68
	v_cvt_pk_f16_f32 v53, v53, v66
	v_cvt_pk_f16_f32 v51, v51, v52
	v_pack_b32_f16 v34, v50, v51
	v_alignbit_b32 v35, v53, v51, 16
	v_alignbit_b32 v36, v57, v53, 16
	v_alignbit_b32 v37, v56, v57, 16
	s_waitcnt vmcnt(3)
	v_cvt_f16_f32_e32 v47, v85
	s_waitcnt vmcnt(2)
	v_cvt_f16_f32_e32 v55, v74
	v_mfma_f32_32x32x16_f16 v[2:17], v[34:37], v[26:29], v[2:17]
	v_cvt_pk_f16_f32 v48, v83, v84
	v_cvt_pk_f16_f32 v49, v77, v82
	v_cvt_pk_f16_f32 v54, v75, v76
	v_pack_b32_f16 v34, v55, v54
	v_alignbit_b32 v35, v49, v54, 16
	v_alignbit_b32 v36, v48, v49, 16
	v_alignbit_b32 v37, v47, v48, 16
	s_waitcnt vmcnt(1)
	v_cvt_f16_f32_e32 v38, v97
	s_waitcnt vmcnt(0)
	v_cvt_f16_f32_e32 v46, v86
	v_mfma_f32_32x32x16_f16 v[2:17], v[34:37], v[22:25], v[2:17]
	v_cvt_pk_f16_f32 v39, v95, v96
	v_cvt_pk_f16_f32 v40, v89, v94
	v_cvt_pk_f16_f32 v41, v87, v88
	v_pack_b32_f16 v34, v46, v41
	v_alignbit_b32 v35, v40, v41, 16
	v_alignbit_b32 v36, v39, v40, 16
	v_alignbit_b32 v37, v38, v39, 16
	s_nop 1
	v_mfma_f32_32x32x16_f16 v[2:17], v[34:37], v[18:21], v[2:17]
	s_nop 11
	v_max_f32_e32 v2, v2, v2
	v_max_f32_e32 v2, 0, v2
	v_mul_f32_e32 v34, v138, v2
	s_nop 1
	v_mov_b32_dpp v34, v34 quad_perm:[1,0,3,2] row_mask:0xf bank_mask:0xf
	s_waitcnt lgkmcnt(0)
	v_fmac_f32_e32 v34, v138, v2
	s_nop 1
	v_mov_b32_dpp v2, v34 quad_perm:[2,3,0,1] row_mask:0xf bank_mask:0xf
	s_waitcnt lgkmcnt(0)
	v_add_f32_e32 v2, v34, v2
	s_nop 1
	v_mov_b32_dpp v34, v2 row_shl:4 row_mask:0xf bank_mask:0x5
	v_mov_b32_dpp v34, v2 row_shr:4 row_mask:0xf bank_mask:0xa
	s_and_saveexec_b64 s[0:1], vcc
	s_cbranch_execz .LBB0_947
	v_mov_b32_e32 v121, v115
	s_waitcnt lgkmcnt(0)
	v_add_f32_e32 v2, v2, v34
	v_lshl_add_u64 v[34:35], v[122:123], 0, v[120:121]
	global_store_dword v[34:35], v2, off offset:896
.LBB0_947:
	s_or_b64 exec, exec, s[0:1]
	v_max_f32_e32 v2, v3, v3
	v_max_f32_e32 v2, 0, v2
	v_mul_f32_e32 v3, v138, v2
	s_nop 1
	v_mov_b32_dpp v3, v3 quad_perm:[1,0,3,2] row_mask:0xf bank_mask:0xf
	s_waitcnt lgkmcnt(0)
	v_fmac_f32_e32 v3, v138, v2
	s_nop 1
	v_mov_b32_dpp v2, v3 quad_perm:[2,3,0,1] row_mask:0xf bank_mask:0xf
	s_waitcnt lgkmcnt(0)
	v_add_f32_e32 v2, v3, v2
	s_nop 1
	v_mov_b32_dpp v3, v2 row_shl:4 row_mask:0xf bank_mask:0x5
	v_mov_b32_dpp v3, v2 row_shr:4 row_mask:0xf bank_mask:0xa
	s_and_saveexec_b64 s[0:1], vcc
	s_cbranch_execz .LBB0_949
	v_mov_b32_e32 v121, v115
	s_waitcnt lgkmcnt(0)
	v_add_f32_e32 v34, v2, v3
	v_lshl_add_u64 v[2:3], v[122:123], 0, v[120:121]
	global_store_dword v[2:3], v34, off offset:900
.LBB0_949:
	s_or_b64 exec, exec, s[0:1]
	v_max_f32_e32 v2, v4, v4
	v_max_f32_e32 v2, 0, v2
	s_waitcnt lgkmcnt(0)
	v_mul_f32_e32 v3, v138, v2
	s_nop 1
	v_mov_b32_dpp v3, v3 quad_perm:[1,0,3,2] row_mask:0xf bank_mask:0xf
	s_waitcnt lgkmcnt(0)
	v_fmac_f32_e32 v3, v138, v2
	s_nop 1
	v_mov_b32_dpp v2, v3 quad_perm:[2,3,0,1] row_mask:0xf bank_mask:0xf
	s_waitcnt lgkmcnt(0)
	v_add_f32_e32 v2, v3, v2
	s_nop 1
	v_mov_b32_dpp v3, v2 row_shl:4 row_mask:0xf bank_mask:0x5
	v_mov_b32_dpp v3, v2 row_shr:4 row_mask:0xf bank_mask:0xa
	s_and_saveexec_b64 s[0:1], vcc
	s_cbranch_execz .LBB0_951
	v_mov_b32_e32 v121, v115
	s_waitcnt lgkmcnt(0)
	v_add_f32_e32 v4, v2, v3
	v_lshl_add_u64 v[2:3], v[122:123], 0, v[120:121]
	global_store_dword v[2:3], v4, off offset:904
.LBB0_951:
	s_or_b64 exec, exec, s[0:1]
	v_max_f32_e32 v2, v5, v5
	v_max_f32_e32 v2, 0, v2
	s_waitcnt lgkmcnt(0)
	v_mul_f32_e32 v3, v138, v2
	s_nop 1
	v_mov_b32_dpp v3, v3 quad_perm:[1,0,3,2] row_mask:0xf bank_mask:0xf
	s_waitcnt lgkmcnt(0)
	v_fmac_f32_e32 v3, v138, v2
	s_nop 1
	v_mov_b32_dpp v2, v3 quad_perm:[2,3,0,1] row_mask:0xf bank_mask:0xf
	s_waitcnt lgkmcnt(0)
	v_add_f32_e32 v2, v3, v2
	s_nop 1
	v_mov_b32_dpp v3, v2 row_shl:4 row_mask:0xf bank_mask:0x5
	v_mov_b32_dpp v3, v2 row_shr:4 row_mask:0xf bank_mask:0xa
	s_and_saveexec_b64 s[0:1], vcc
	s_cbranch_execz .LBB0_953
	v_mov_b32_e32 v121, v115
	s_waitcnt lgkmcnt(0)
	v_add_f32_e32 v4, v2, v3
	v_lshl_add_u64 v[2:3], v[122:123], 0, v[120:121]
	global_store_dword v[2:3], v4, off offset:908
.LBB0_953:
	s_or_b64 exec, exec, s[0:1]
	v_max_f32_e32 v2, v6, v6
	v_max_f32_e32 v2, 0, v2
	s_waitcnt lgkmcnt(0)
	v_mul_f32_e32 v3, v138, v2
	s_nop 1
	v_mov_b32_dpp v3, v3 quad_perm:[1,0,3,2] row_mask:0xf bank_mask:0xf
	s_waitcnt lgkmcnt(0)
	v_fmac_f32_e32 v3, v138, v2
	s_nop 1
	v_mov_b32_dpp v2, v3 quad_perm:[2,3,0,1] row_mask:0xf bank_mask:0xf
	s_waitcnt lgkmcnt(0)
	v_add_f32_e32 v2, v3, v2
	s_nop 1
	v_mov_b32_dpp v3, v2 row_shl:4 row_mask:0xf bank_mask:0x5
	v_mov_b32_dpp v3, v2 row_shr:4 row_mask:0xf bank_mask:0xa
	s_and_saveexec_b64 s[0:1], vcc
	s_cbranch_execz .LBB0_955
	v_mov_b32_e32 v121, v115
	s_waitcnt lgkmcnt(0)
	v_add_f32_e32 v4, v2, v3
	v_lshl_add_u64 v[2:3], v[122:123], 0, v[120:121]
	global_store_dword v[2:3], v4, off offset:928
.LBB0_955:
	s_or_b64 exec, exec, s[0:1]
	v_max_f32_e32 v2, v7, v7
	v_max_f32_e32 v2, 0, v2
	s_waitcnt lgkmcnt(0)
	v_mul_f32_e32 v3, v138, v2
	s_nop 1
	v_mov_b32_dpp v3, v3 quad_perm:[1,0,3,2] row_mask:0xf bank_mask:0xf
	s_waitcnt lgkmcnt(0)
	v_fmac_f32_e32 v3, v138, v2
	s_nop 1
	v_mov_b32_dpp v2, v3 quad_perm:[2,3,0,1] row_mask:0xf bank_mask:0xf
	s_waitcnt lgkmcnt(0)
	v_add_f32_e32 v2, v3, v2
	s_nop 1
	v_mov_b32_dpp v3, v2 row_shl:4 row_mask:0xf bank_mask:0x5
	v_mov_b32_dpp v3, v2 row_shr:4 row_mask:0xf bank_mask:0xa
	s_and_saveexec_b64 s[0:1], vcc
	s_cbranch_execz .LBB0_957
	v_mov_b32_e32 v121, v115
	s_waitcnt lgkmcnt(0)
	v_add_f32_e32 v4, v2, v3
	v_lshl_add_u64 v[2:3], v[122:123], 0, v[120:121]
	global_store_dword v[2:3], v4, off offset:932
.LBB0_957:
	s_or_b64 exec, exec, s[0:1]
	v_max_f32_e32 v2, v8, v8
	v_max_f32_e32 v2, 0, v2
	s_waitcnt lgkmcnt(0)
	v_mul_f32_e32 v3, v138, v2
	s_nop 1
	v_mov_b32_dpp v3, v3 quad_perm:[1,0,3,2] row_mask:0xf bank_mask:0xf
	s_waitcnt lgkmcnt(0)
	v_fmac_f32_e32 v3, v138, v2
	s_nop 1
	v_mov_b32_dpp v2, v3 quad_perm:[2,3,0,1] row_mask:0xf bank_mask:0xf
	s_waitcnt lgkmcnt(0)
	v_add_f32_e32 v2, v3, v2
	s_nop 1
	v_mov_b32_dpp v3, v2 row_shl:4 row_mask:0xf bank_mask:0x5
	v_mov_b32_dpp v3, v2 row_shr:4 row_mask:0xf bank_mask:0xa
	s_and_saveexec_b64 s[0:1], vcc
	s_cbranch_execz .LBB0_959
	v_mov_b32_e32 v121, v115
	s_waitcnt lgkmcnt(0)
	v_add_f32_e32 v4, v2, v3
	v_lshl_add_u64 v[2:3], v[122:123], 0, v[120:121]
	global_store_dword v[2:3], v4, off offset:936
.LBB0_959:
	s_or_b64 exec, exec, s[0:1]
	v_max_f32_e32 v2, v9, v9
	v_max_f32_e32 v2, 0, v2
	s_waitcnt lgkmcnt(0)
	v_mul_f32_e32 v3, v138, v2
	s_nop 1
	v_mov_b32_dpp v3, v3 quad_perm:[1,0,3,2] row_mask:0xf bank_mask:0xf
	s_waitcnt lgkmcnt(0)
	v_fmac_f32_e32 v3, v138, v2
	s_nop 1
	v_mov_b32_dpp v2, v3 quad_perm:[2,3,0,1] row_mask:0xf bank_mask:0xf
	s_waitcnt lgkmcnt(0)
	v_add_f32_e32 v2, v3, v2
	s_nop 1
	v_mov_b32_dpp v3, v2 row_shl:4 row_mask:0xf bank_mask:0x5
	v_mov_b32_dpp v3, v2 row_shr:4 row_mask:0xf bank_mask:0xa
	s_and_saveexec_b64 s[0:1], vcc
	s_cbranch_execz .LBB0_961
	v_mov_b32_e32 v121, v115
	s_waitcnt lgkmcnt(0)
	v_add_f32_e32 v4, v2, v3
	v_lshl_add_u64 v[2:3], v[122:123], 0, v[120:121]
	global_store_dword v[2:3], v4, off offset:940
.LBB0_961:
	s_or_b64 exec, exec, s[0:1]
	v_max_f32_e32 v2, v10, v10
	v_max_f32_e32 v2, 0, v2
	s_waitcnt lgkmcnt(0)
	v_mul_f32_e32 v3, v138, v2
	s_nop 1
	v_mov_b32_dpp v3, v3 quad_perm:[1,0,3,2] row_mask:0xf bank_mask:0xf
	s_waitcnt lgkmcnt(0)
	v_fmac_f32_e32 v3, v138, v2
	s_nop 1
	v_mov_b32_dpp v2, v3 quad_perm:[2,3,0,1] row_mask:0xf bank_mask:0xf
	s_waitcnt lgkmcnt(0)
	v_add_f32_e32 v2, v3, v2
	s_nop 1
	v_mov_b32_dpp v3, v2 row_shl:4 row_mask:0xf bank_mask:0x5
	v_mov_b32_dpp v3, v2 row_shr:4 row_mask:0xf bank_mask:0xa
	s_and_saveexec_b64 s[0:1], vcc
	s_cbranch_execz .LBB0_963
	v_mov_b32_e32 v121, v115
	s_waitcnt lgkmcnt(0)
	v_add_f32_e32 v4, v2, v3
	v_lshl_add_u64 v[2:3], v[122:123], 0, v[120:121]
	global_store_dword v[2:3], v4, off offset:960
.LBB0_963:
	s_or_b64 exec, exec, s[0:1]
	v_max_f32_e32 v2, v11, v11
	v_max_f32_e32 v2, 0, v2
	s_waitcnt lgkmcnt(0)
	v_mul_f32_e32 v3, v138, v2
	s_nop 1
	v_mov_b32_dpp v3, v3 quad_perm:[1,0,3,2] row_mask:0xf bank_mask:0xf
	s_waitcnt lgkmcnt(0)
	v_fmac_f32_e32 v3, v138, v2
	s_nop 1
	v_mov_b32_dpp v2, v3 quad_perm:[2,3,0,1] row_mask:0xf bank_mask:0xf
	s_waitcnt lgkmcnt(0)
	v_add_f32_e32 v2, v3, v2
	s_nop 1
	v_mov_b32_dpp v3, v2 row_shl:4 row_mask:0xf bank_mask:0x5
	v_mov_b32_dpp v3, v2 row_shr:4 row_mask:0xf bank_mask:0xa
	s_and_saveexec_b64 s[0:1], vcc
	s_cbranch_execz .LBB0_965
	v_mov_b32_e32 v121, v115
	s_waitcnt lgkmcnt(0)
	v_add_f32_e32 v4, v2, v3
	v_lshl_add_u64 v[2:3], v[122:123], 0, v[120:121]
	global_store_dword v[2:3], v4, off offset:964
.LBB0_965:
	s_or_b64 exec, exec, s[0:1]
	v_max_f32_e32 v2, v12, v12
	v_max_f32_e32 v2, 0, v2
	s_waitcnt lgkmcnt(0)
	v_mul_f32_e32 v3, v138, v2
	s_nop 1
	v_mov_b32_dpp v3, v3 quad_perm:[1,0,3,2] row_mask:0xf bank_mask:0xf
	s_waitcnt lgkmcnt(0)
	v_fmac_f32_e32 v3, v138, v2
	s_nop 1
	v_mov_b32_dpp v2, v3 quad_perm:[2,3,0,1] row_mask:0xf bank_mask:0xf
	s_waitcnt lgkmcnt(0)
	v_add_f32_e32 v2, v3, v2
	s_nop 1
	v_mov_b32_dpp v3, v2 row_shl:4 row_mask:0xf bank_mask:0x5
	v_mov_b32_dpp v3, v2 row_shr:4 row_mask:0xf bank_mask:0xa
	s_and_saveexec_b64 s[0:1], vcc
	s_cbranch_execz .LBB0_967
	v_mov_b32_e32 v121, v115
	s_waitcnt lgkmcnt(0)
	v_add_f32_e32 v4, v2, v3
	v_lshl_add_u64 v[2:3], v[122:123], 0, v[120:121]
	global_store_dword v[2:3], v4, off offset:968
.LBB0_967:
	s_or_b64 exec, exec, s[0:1]
	v_max_f32_e32 v2, v13, v13
	v_max_f32_e32 v2, 0, v2
	s_waitcnt lgkmcnt(0)
	v_mul_f32_e32 v3, v138, v2
	s_nop 1
	v_mov_b32_dpp v3, v3 quad_perm:[1,0,3,2] row_mask:0xf bank_mask:0xf
	s_waitcnt lgkmcnt(0)
	v_fmac_f32_e32 v3, v138, v2
	s_nop 1
	v_mov_b32_dpp v2, v3 quad_perm:[2,3,0,1] row_mask:0xf bank_mask:0xf
	s_waitcnt lgkmcnt(0)
	v_add_f32_e32 v2, v3, v2
	s_nop 1
	v_mov_b32_dpp v3, v2 row_shl:4 row_mask:0xf bank_mask:0x5
	v_mov_b32_dpp v3, v2 row_shr:4 row_mask:0xf bank_mask:0xa
	s_and_saveexec_b64 s[0:1], vcc
	s_cbranch_execz .LBB0_969
	v_mov_b32_e32 v121, v115
	s_waitcnt lgkmcnt(0)
	v_add_f32_e32 v4, v2, v3
	v_lshl_add_u64 v[2:3], v[122:123], 0, v[120:121]
	global_store_dword v[2:3], v4, off offset:972
.LBB0_969:
	s_or_b64 exec, exec, s[0:1]
	v_max_f32_e32 v2, v14, v14
	v_max_f32_e32 v2, 0, v2
	s_waitcnt lgkmcnt(0)
	v_mul_f32_e32 v3, v138, v2
	s_nop 1
	v_mov_b32_dpp v3, v3 quad_perm:[1,0,3,2] row_mask:0xf bank_mask:0xf
	s_waitcnt lgkmcnt(0)
	v_fmac_f32_e32 v3, v138, v2
	s_nop 1
	v_mov_b32_dpp v2, v3 quad_perm:[2,3,0,1] row_mask:0xf bank_mask:0xf
	s_waitcnt lgkmcnt(0)
	v_add_f32_e32 v2, v3, v2
	s_nop 1
	v_mov_b32_dpp v3, v2 row_shl:4 row_mask:0xf bank_mask:0x5
	v_mov_b32_dpp v3, v2 row_shr:4 row_mask:0xf bank_mask:0xa
	s_and_saveexec_b64 s[0:1], vcc
	s_cbranch_execz .LBB0_971
	v_mov_b32_e32 v121, v115
	s_waitcnt lgkmcnt(0)
	v_add_f32_e32 v4, v2, v3
	v_lshl_add_u64 v[2:3], v[122:123], 0, v[120:121]
	global_store_dword v[2:3], v4, off offset:992
.LBB0_971:
	s_or_b64 exec, exec, s[0:1]
	v_max_f32_e32 v2, v15, v15
	v_max_f32_e32 v2, 0, v2
	s_waitcnt lgkmcnt(0)
	v_mul_f32_e32 v3, v138, v2
	s_nop 1
	v_mov_b32_dpp v3, v3 quad_perm:[1,0,3,2] row_mask:0xf bank_mask:0xf
	s_waitcnt lgkmcnt(0)
	v_fmac_f32_e32 v3, v138, v2
	s_nop 1
	v_mov_b32_dpp v2, v3 quad_perm:[2,3,0,1] row_mask:0xf bank_mask:0xf
	s_waitcnt lgkmcnt(0)
	v_add_f32_e32 v2, v3, v2
	s_nop 1
	v_mov_b32_dpp v3, v2 row_shl:4 row_mask:0xf bank_mask:0x5
	v_mov_b32_dpp v3, v2 row_shr:4 row_mask:0xf bank_mask:0xa
	s_and_saveexec_b64 s[0:1], vcc
	s_cbranch_execz .LBB0_973
	v_mov_b32_e32 v121, v115
	s_waitcnt lgkmcnt(0)
	v_add_f32_e32 v4, v2, v3
	v_lshl_add_u64 v[2:3], v[122:123], 0, v[120:121]
	global_store_dword v[2:3], v4, off offset:996
.LBB0_973:
	s_or_b64 exec, exec, s[0:1]
	v_max_f32_e32 v2, v16, v16
	v_max_f32_e32 v2, 0, v2
	s_waitcnt lgkmcnt(0)
	v_mul_f32_e32 v3, v138, v2
	s_nop 1
	v_mov_b32_dpp v3, v3 quad_perm:[1,0,3,2] row_mask:0xf bank_mask:0xf
	s_waitcnt lgkmcnt(0)
	v_fmac_f32_e32 v3, v138, v2
	s_nop 1
	v_mov_b32_dpp v2, v3 quad_perm:[2,3,0,1] row_mask:0xf bank_mask:0xf
	s_waitcnt lgkmcnt(0)
	v_add_f32_e32 v2, v3, v2
	s_nop 1
	v_mov_b32_dpp v3, v2 row_shl:4 row_mask:0xf bank_mask:0x5
	v_mov_b32_dpp v3, v2 row_shr:4 row_mask:0xf bank_mask:0xa
	s_and_saveexec_b64 s[0:1], vcc
	s_cbranch_execz .LBB0_975
	v_mov_b32_e32 v121, v115
	s_waitcnt lgkmcnt(0)
	v_add_f32_e32 v4, v2, v3
	v_lshl_add_u64 v[2:3], v[122:123], 0, v[120:121]
	global_store_dword v[2:3], v4, off offset:1000
.LBB0_975:
	s_or_b64 exec, exec, s[0:1]
	v_max_f32_e32 v2, v17, v17
	v_max_f32_e32 v2, 0, v2
	s_waitcnt lgkmcnt(0)
	v_mul_f32_e32 v3, v138, v2
	s_nop 1
	v_mov_b32_dpp v3, v3 quad_perm:[1,0,3,2] row_mask:0xf bank_mask:0xf
	s_waitcnt lgkmcnt(0)
	v_fmac_f32_e32 v3, v138, v2
	s_nop 1
	v_mov_b32_dpp v2, v3 quad_perm:[2,3,0,1] row_mask:0xf bank_mask:0xf
	s_waitcnt lgkmcnt(0)
	v_add_f32_e32 v2, v3, v2
	s_nop 1
	v_mov_b32_dpp v3, v2 row_shl:4 row_mask:0xf bank_mask:0x5
	v_mov_b32_dpp v3, v2 row_shr:4 row_mask:0xf bank_mask:0xa
	s_and_saveexec_b64 s[0:1], vcc
	s_cbranch_execz .LBB0_977
	v_mov_b32_e32 v121, v115
	s_waitcnt lgkmcnt(0)
	v_add_f32_e32 v4, v2, v3
	v_lshl_add_u64 v[2:3], v[122:123], 0, v[120:121]
	global_store_dword v[2:3], v4, off offset:1004
.LBB0_977:
	s_or_b64 exec, exec, s[0:1]
	s_cmp_lg_u32 s7, 7
	s_cselect_b64 s[0:1], -1, 0
	s_cmp_lg_u32 s6, 7
	s_cselect_b64 s[2:3], -1, 0
	s_or_b64 s[0:1], s[0:1], s[2:3]
	s_and_b64 vcc, exec, s[0:1]
	s_cbranch_vccnz .LBB0_720
	v_and_or_b32 v2, v139, 3, s5
	s_waitcnt lgkmcnt(0)
	v_ashrrev_i32_e32 v3, 31, v2
	v_readlane_b32 s36, v251, 35
	v_lshlrev_b64 v[2:3], 7, v[2:3]
	v_readlane_b32 s40, v251, 39
	v_readlane_b32 s41, v251, 40
	v_lshlrev_b32_e32 v114, 1, v143
	s_mov_b64 s[0:1], 0x10000
	v_lshl_add_u64 v[2:3], s[40:41], 0, v[2:3]
	v_lshl_add_u64 v[34:35], v[2:3], 0, v[114:115]
	global_load_dwordx4 v[2:5], v[34:35], off
	v_readlane_b32 s37, v251, 36
	v_readlane_b32 s38, v251, 37
	v_readlane_b32 s39, v251, 38
	v_readlane_b32 s42, v251, 41
	v_readlane_b32 s43, v251, 42
	v_readlane_b32 s44, v251, 43
	v_readlane_b32 s45, v251, 44
	v_readlane_b32 s46, v251, 45
	v_readlane_b32 s47, v251, 46
	v_readlane_b32 s48, v251, 47
	v_readlane_b32 s49, v251, 48
	v_readlane_b32 s50, v251, 49
	v_readlane_b32 s51, v251, 50
	s_waitcnt vmcnt(0)
	v_mfma_f32_32x32x16_f16 v[2:17], v[2:5], v[30:33], 0
	global_load_dwordx4 v[30:33], v[34:35], off offset:32
	s_waitcnt vmcnt(0)
	v_mfma_f32_32x32x16_f16 v[2:17], v[30:33], v[26:29], v[2:17]
	global_load_dwordx4 v[26:29], v[34:35], off offset:64
	s_waitcnt vmcnt(0)
	v_mfma_f32_32x32x16_f16 v[2:17], v[26:29], v[22:25], v[2:17]
	global_load_dwordx4 v[22:25], v[34:35], off offset:96
	s_waitcnt vmcnt(0)
	v_mfma_f32_32x32x16_f16 v[2:17], v[22:25], v[18:21], v[2:17]
	s_nop 11
	v_or_b32_e32 v9, v136, v137
	v_cmp_eq_u32_e32 vcc, 0, v9
	v_max_f32_e32 v2, v2, v2
	v_max_f32_e32 v2, 0, v2
	v_mul_f32_e32 v6, v138, v2
	s_nop 1
	v_mov_b32_dpp v6, v6 quad_perm:[1,0,3,2] row_mask:0xf bank_mask:0xf
	s_waitcnt lgkmcnt(0)
	v_fmac_f32_e32 v6, v138, v2
	s_nop 1
	v_mov_b32_dpp v2, v6 quad_perm:[2,3,0,1] row_mask:0xf bank_mask:0xf
	s_waitcnt lgkmcnt(0)
	v_add_f32_e32 v2, v6, v2
	s_nop 1
	v_mov_b32_dpp v8, v2 row_shl:4 row_mask:0xf bank_mask:0x5
	v_mov_b32_dpp v8, v2 row_shr:4 row_mask:0xf bank_mask:0xa
	v_lshl_add_u64 v[6:7], v[118:119], 0, s[0:1]
	s_and_saveexec_b64 s[0:1], vcc
	s_cbranch_execz .LBB0_980
	v_mov_b32_e32 v121, v115
	s_waitcnt lgkmcnt(0)
	v_add_f32_e32 v2, v2, v8
	v_lshl_add_u64 v[8:9], v[6:7], 0, v[120:121]
	global_store_dword v[8:9], v2, off
.LBB0_980:
	s_or_b64 exec, exec, s[0:1]
	v_max_f32_e32 v2, v3, v3
	v_max_f32_e32 v2, 0, v2
	v_mul_f32_e32 v3, v138, v2
	s_nop 1
	v_mov_b32_dpp v3, v3 quad_perm:[1,0,3,2] row_mask:0xf bank_mask:0xf
	s_waitcnt lgkmcnt(0)
	v_fmac_f32_e32 v3, v138, v2
	s_nop 1
	v_mov_b32_dpp v2, v3 quad_perm:[2,3,0,1] row_mask:0xf bank_mask:0xf
	s_waitcnt lgkmcnt(0)
	v_add_f32_e32 v2, v3, v2
	s_nop 1
	v_mov_b32_dpp v3, v2 row_shl:4 row_mask:0xf bank_mask:0x5
	v_mov_b32_dpp v3, v2 row_shr:4 row_mask:0xf bank_mask:0xa
	s_and_saveexec_b64 s[0:1], vcc
	s_cbranch_execz .LBB0_982
	v_mov_b32_e32 v121, v115
	s_waitcnt lgkmcnt(0)
	v_add_f32_e32 v8, v2, v3
	v_lshl_add_u64 v[2:3], v[6:7], 0, v[120:121]
	global_store_dword v[2:3], v8, off offset:4
.LBB0_982:
	s_or_b64 exec, exec, s[0:1]
	v_max_f32_e32 v2, v4, v4
	v_max_f32_e32 v2, 0, v2
	s_waitcnt lgkmcnt(0)
	v_mul_f32_e32 v3, v138, v2
	s_nop 1
	v_mov_b32_dpp v3, v3 quad_perm:[1,0,3,2] row_mask:0xf bank_mask:0xf
	s_waitcnt lgkmcnt(0)
	v_fmac_f32_e32 v3, v138, v2
	s_nop 1
	v_mov_b32_dpp v2, v3 quad_perm:[2,3,0,1] row_mask:0xf bank_mask:0xf
	s_waitcnt lgkmcnt(0)
	v_add_f32_e32 v2, v3, v2
	s_nop 1
	v_mov_b32_dpp v3, v2 row_shl:4 row_mask:0xf bank_mask:0x5
	v_mov_b32_dpp v3, v2 row_shr:4 row_mask:0xf bank_mask:0xa
	s_and_saveexec_b64 s[0:1], vcc
	s_cbranch_execz .LBB0_984
	v_mov_b32_e32 v121, v115
	s_waitcnt lgkmcnt(0)
	v_add_f32_e32 v4, v2, v3
	v_lshl_add_u64 v[2:3], v[6:7], 0, v[120:121]
	global_store_dword v[2:3], v4, off offset:8
.LBB0_984:
	s_or_b64 exec, exec, s[0:1]
	v_max_f32_e32 v2, v5, v5
	v_max_f32_e32 v2, 0, v2
	s_waitcnt lgkmcnt(0)
	v_mul_f32_e32 v3, v138, v2
	s_nop 1
	v_mov_b32_dpp v3, v3 quad_perm:[1,0,3,2] row_mask:0xf bank_mask:0xf
	s_waitcnt lgkmcnt(0)
	v_fmac_f32_e32 v3, v138, v2
	s_nop 1
	v_mov_b32_dpp v2, v3 quad_perm:[2,3,0,1] row_mask:0xf bank_mask:0xf
	s_waitcnt lgkmcnt(0)
	v_add_f32_e32 v2, v3, v2
	s_nop 1
	v_mov_b32_dpp v3, v2 row_shl:4 row_mask:0xf bank_mask:0x5
	v_mov_b32_dpp v3, v2 row_shr:4 row_mask:0xf bank_mask:0xa
	s_and_saveexec_b64 s[0:1], vcc
	s_cbranch_execz .LBB0_719
	s_waitcnt lgkmcnt(0)
	v_add_f32_e32 v4, v2, v3
	v_add_co_u32_e32 v2, vcc, 0x10000, v118
	s_nop 1
	v_addc_co_u32_e32 v3, vcc, 0, v119, vcc
	global_store_dword v[2:3], v4, off offset:12
	s_branch .LBB0_719
